# c8 = c7 + DMA group issued before ds_reads in each K-loop load segment
# baseline (speedup 1.0000x reference)
.LBB0_344:
	s_cmp_eq_u32 s81, 28
	s_cselect_b32 s21, s9, s78
	s_cselect_b32 s20, s76, s77
	s_cselect_b32 s23, s11, s80
	s_cselect_b32 s22, s75, s79
	s_add_u32 s82, s18, 0xfff80000
	s_addc_u32 s83, s19, -1
	s_mov_b32 s86, m0
	s_mov_b32 m0, s64
	s_nop 0
	global_load_lds_dwordx4 v138, s[82:83]
	s_mov_b32 m0, s86
	s_nop 0
	s_mov_b32 s86, m0
	s_mov_b32 m0, s67
	s_nop 0
	global_load_lds_dwordx4 v140, s[82:83]
	s_mov_b32 m0, s86
	s_mov_b32 s82, m0
	s_mov_b32 m0, s65
	s_nop 0
	global_load_lds_dwordx4 v138, s[18:19]
	s_mov_b32 m0, s82
	s_nop 0
	s_mov_b32 s82, m0
	s_mov_b32 m0, s73
	s_nop 0
	global_load_lds_dwordx4 v140, s[18:19]
	s_mov_b32 m0, s82
	ds_read_b128 v[148:151], v143
	ds_read_b128 v[152:155], v143 offset:1024
	ds_read_b128 v[156:159], v143 offset:2048
	ds_read_b128 v[160:163], v143 offset:3072
	ds_read_b128 v[164:167], v144
	ds_read_b128 v[168:171], v144 offset:1024
	ds_read_b128 v[172:175], v144 offset:2048
	ds_read_b128 v[176:179], v144 offset:3072
	ds_read_b128 v[180:183], v145
	ds_read_b128 v[184:187], v145 offset:1024
	ds_read_b128 v[188:191], v145 offset:2048
	ds_read_b128 v[192:195], v145 offset:3072
	ds_read_b128 v[196:199], v145 offset:4096
	ds_read_b128 v[200:203], v145 offset:5120
	ds_read_b128 v[204:207], v145 offset:6144
	ds_read_b128 v[208:211], v145 offset:7168
	s_waitcnt vmcnt(8)
	s_waitcnt lgkmcnt(0)
	s_barrier
	s_setprio 1
	s_waitcnt lgkmcnt(7)
	v_mfma_f32_16x16x32_bf16 v[126:129], v[148:151], v[180:183], v[126:129]
	v_mfma_f32_16x16x32_bf16 v[122:125], v[156:159], v[180:183], v[122:125]
	s_waitcnt lgkmcnt(5)
	v_mfma_f32_16x16x32_bf16 v[110:113], v[148:151], v[188:191], v[110:113]
	v_mfma_f32_16x16x32_bf16 v[106:109], v[156:159], v[188:191], v[106:109]
	s_waitcnt lgkmcnt(3)
	v_mfma_f32_16x16x32_bf16 v[94:97], v[148:151], v[196:199], v[94:97]
	v_mfma_f32_16x16x32_bf16 v[90:93], v[156:159], v[196:199], v[90:93]
	s_waitcnt lgkmcnt(1)
	v_mfma_f32_16x16x32_bf16 v[78:81], v[148:151], v[204:207], v[78:81]
	v_mfma_f32_16x16x32_bf16 v[74:77], v[156:159], v[204:207], v[74:77]
	v_mfma_f32_16x16x32_bf16 v[126:129], v[152:155], v[184:187], v[126:129]
	v_mfma_f32_16x16x32_bf16 v[122:125], v[160:163], v[184:187], v[122:125]
	v_mfma_f32_16x16x32_bf16 v[110:113], v[152:155], v[192:195], v[110:113]
	v_mfma_f32_16x16x32_bf16 v[106:109], v[160:163], v[192:195], v[106:109]
	v_mfma_f32_16x16x32_bf16 v[94:97], v[152:155], v[200:203], v[94:97]
	v_mfma_f32_16x16x32_bf16 v[90:93], v[160:163], v[200:203], v[90:93]
	s_waitcnt lgkmcnt(0)
	v_mfma_f32_16x16x32_bf16 v[78:81], v[152:155], v[208:211], v[78:81]
	v_mfma_f32_16x16x32_bf16 v[74:77], v[160:163], v[208:211], v[74:77]
	s_setprio 0
	s_setprio 1
	v_mfma_f32_16x16x32_bf16 v[118:121], v[164:167], v[180:183], v[118:121]
	v_mfma_f32_16x16x32_bf16 v[114:117], v[172:175], v[180:183], v[114:117]
	v_mfma_f32_16x16x32_bf16 v[102:105], v[164:167], v[188:191], v[102:105]
	v_mfma_f32_16x16x32_bf16 v[98:101], v[172:175], v[188:191], v[98:101]
	v_mfma_f32_16x16x32_bf16 v[86:89], v[164:167], v[196:199], v[86:89]
	v_mfma_f32_16x16x32_bf16 v[82:85], v[172:175], v[196:199], v[82:85]
	v_mfma_f32_16x16x32_bf16 v[70:73], v[164:167], v[204:207], v[70:73]
	v_mfma_f32_16x16x32_bf16 v[66:69], v[172:175], v[204:207], v[66:69]
	v_mfma_f32_16x16x32_bf16 v[118:121], v[168:171], v[184:187], v[118:121]
	v_mfma_f32_16x16x32_bf16 v[114:117], v[176:179], v[184:187], v[114:117]
	v_mfma_f32_16x16x32_bf16 v[102:105], v[168:171], v[192:195], v[102:105]
	v_mfma_f32_16x16x32_bf16 v[98:101], v[176:179], v[192:195], v[98:101]
	v_mfma_f32_16x16x32_bf16 v[86:89], v[168:171], v[200:203], v[86:89]
	v_mfma_f32_16x16x32_bf16 v[82:85], v[176:179], v[200:203], v[82:85]
	s_setprio 2
	s_barrier
	v_mfma_f32_16x16x32_bf16 v[70:73], v[168:171], v[208:211], v[70:73]
	v_mfma_f32_16x16x32_bf16 v[66:69], v[176:179], v[208:211], v[66:69]
	s_setprio 0
	s_mov_b32 s82, m0
	s_mov_b32 m0, s35
	s_nop 0
	global_load_lds_dwordx4 v139, s[20:21]
	s_mov_b32 m0, s82
	s_nop 0
	s_mov_b32 s82, m0
	s_mov_b32 m0, s36
	s_nop 0
	global_load_lds_dwordx4 v141, s[20:21]
	s_mov_b32 m0, s82
	s_add_u32 s82, s20, 0x80000
	s_addc_u32 s83, s21, 0
	s_mov_b32 s86, m0
	s_mov_b32 m0, s37
	s_nop 0
	global_load_lds_dwordx4 v139, s[82:83]
	s_mov_b32 m0, s86
	s_nop 0
	s_mov_b32 s86, m0
	s_mov_b32 m0, s42
	s_nop 0
	global_load_lds_dwordx4 v141, s[82:83]
	s_mov_b32 m0, s86
	ds_read_b128 v[180:183], v145 offset:16384
	ds_read_b128 v[184:187], v145 offset:17408
	ds_read_b128 v[188:191], v145 offset:18432
	ds_read_b128 v[192:195], v145 offset:19456
	ds_read_b128 v[196:199], v145 offset:20480
	ds_read_b128 v[200:203], v145 offset:21504
	ds_read_b128 v[204:207], v145 offset:22528
	ds_read_b128 v[208:211], v145 offset:23552
	s_waitcnt vmcnt(4)
	s_waitcnt lgkmcnt(0)
	s_barrier
	s_setprio 1
	s_waitcnt lgkmcnt(7)
	v_mfma_f32_16x16x32_bf16 v[62:65], v[148:151], v[180:183], v[62:65]
	v_mfma_f32_16x16x32_bf16 v[58:61], v[156:159], v[180:183], v[58:61]
	s_waitcnt lgkmcnt(5)
	v_mfma_f32_16x16x32_bf16 v[46:49], v[148:151], v[188:191], v[46:49]
	v_mfma_f32_16x16x32_bf16 v[42:45], v[156:159], v[188:191], v[42:45]
	s_waitcnt lgkmcnt(3)
	v_mfma_f32_16x16x32_bf16 v[30:33], v[148:151], v[196:199], v[30:33]
	v_mfma_f32_16x16x32_bf16 v[26:29], v[156:159], v[196:199], v[26:29]
	s_waitcnt lgkmcnt(1)
	v_mfma_f32_16x16x32_bf16 v[14:17], v[148:151], v[204:207], v[14:17]
	v_mfma_f32_16x16x32_bf16 v[10:13], v[156:159], v[204:207], v[10:13]
	v_mfma_f32_16x16x32_bf16 v[62:65], v[152:155], v[184:187], v[62:65]
	v_mfma_f32_16x16x32_bf16 v[58:61], v[160:163], v[184:187], v[58:61]
	v_mfma_f32_16x16x32_bf16 v[46:49], v[152:155], v[192:195], v[46:49]
	v_mfma_f32_16x16x32_bf16 v[42:45], v[160:163], v[192:195], v[42:45]
	v_mfma_f32_16x16x32_bf16 v[30:33], v[152:155], v[200:203], v[30:33]
	v_mfma_f32_16x16x32_bf16 v[26:29], v[160:163], v[200:203], v[26:29]
	s_waitcnt lgkmcnt(0)
	v_mfma_f32_16x16x32_bf16 v[14:17], v[152:155], v[208:211], v[14:17]
	v_mfma_f32_16x16x32_bf16 v[10:13], v[160:163], v[208:211], v[10:13]
	s_setprio 0
	s_setprio 1
	v_mfma_f32_16x16x32_bf16 v[54:57], v[164:167], v[180:183], v[54:57]
	v_mfma_f32_16x16x32_bf16 v[50:53], v[172:175], v[180:183], v[50:53]
	v_mfma_f32_16x16x32_bf16 v[38:41], v[164:167], v[188:191], v[38:41]
	v_mfma_f32_16x16x32_bf16 v[34:37], v[172:175], v[188:191], v[34:37]
	v_mfma_f32_16x16x32_bf16 v[22:25], v[164:167], v[196:199], v[22:25]
	v_mfma_f32_16x16x32_bf16 v[18:21], v[172:175], v[196:199], v[18:21]
	v_mfma_f32_16x16x32_bf16 v[6:9], v[164:167], v[204:207], v[6:9]
	v_mfma_f32_16x16x32_bf16 v[2:5], v[172:175], v[204:207], v[2:5]
	v_mfma_f32_16x16x32_bf16 v[54:57], v[168:171], v[184:187], v[54:57]
	v_mfma_f32_16x16x32_bf16 v[50:53], v[176:179], v[184:187], v[50:53]
	v_mfma_f32_16x16x32_bf16 v[38:41], v[168:171], v[192:195], v[38:41]
	v_mfma_f32_16x16x32_bf16 v[34:37], v[176:179], v[192:195], v[34:37]
	v_mfma_f32_16x16x32_bf16 v[22:25], v[168:171], v[200:203], v[22:25]
	v_mfma_f32_16x16x32_bf16 v[18:21], v[176:179], v[200:203], v[18:21]
	s_setprio 2
	s_barrier
	v_mfma_f32_16x16x32_bf16 v[6:9], v[168:171], v[208:211], v[6:9]
	v_mfma_f32_16x16x32_bf16 v[2:5], v[176:179], v[208:211], v[2:5]
	s_setprio 0
	s_mov_b32 s82, m0
	s_mov_b32 m0, s31
	s_nop 0
	global_load_lds_dwordx4 v138, s[22:23]
	s_mov_b32 m0, s82
	s_nop 0
	s_mov_b32 s82, m0
	s_mov_b32 m0, s43
	s_nop 0
	global_load_lds_dwordx4 v140, s[22:23]
	s_mov_b32 m0, s82
	s_add_u32 s22, s22, 0x80000
	s_addc_u32 s23, s23, 0
	s_mov_b32 s82, m0
	s_mov_b32 m0, s46
	s_nop 0
	global_load_lds_dwordx4 v138, s[22:23]
	s_mov_b32 m0, s82
	s_nop 0
	s_mov_b32 s82, m0
	s_mov_b32 m0, s47
	s_nop 0
	global_load_lds_dwordx4 v140, s[22:23]
	s_mov_b32 m0, s82
	ds_read_b128 v[148:151], v146
	ds_read_b128 v[152:155], v146 offset:1024
	ds_read_b128 v[156:159], v146 offset:2048
	ds_read_b128 v[160:163], v146 offset:3072
	ds_read_b128 v[164:167], v147
	ds_read_b128 v[168:171], v147 offset:1024
	ds_read_b128 v[172:175], v147 offset:2048
	ds_read_b128 v[176:179], v147 offset:3072
	ds_read_b128 v[180:183], v145 offset:32768
	ds_read_b128 v[184:187], v145 offset:33792
	ds_read_b128 v[188:191], v145 offset:34816
	ds_read_b128 v[192:195], v145 offset:35840
	ds_read_b128 v[196:199], v145 offset:36864
	ds_read_b128 v[200:203], v145 offset:37888
	ds_read_b128 v[204:207], v145 offset:38912
	ds_read_b128 v[208:211], v145 offset:39936
	s_waitcnt vmcnt(8)
	s_waitcnt lgkmcnt(0)
	s_barrier
	s_setprio 1
	s_waitcnt lgkmcnt(7)
	v_mfma_f32_16x16x32_bf16 v[126:129], v[148:151], v[180:183], v[126:129]
	v_mfma_f32_16x16x32_bf16 v[122:125], v[156:159], v[180:183], v[122:125]
	s_waitcnt lgkmcnt(5)
	v_mfma_f32_16x16x32_bf16 v[110:113], v[148:151], v[188:191], v[110:113]
	v_mfma_f32_16x16x32_bf16 v[106:109], v[156:159], v[188:191], v[106:109]
	s_waitcnt lgkmcnt(3)
	v_mfma_f32_16x16x32_bf16 v[94:97], v[148:151], v[196:199], v[94:97]
	v_mfma_f32_16x16x32_bf16 v[90:93], v[156:159], v[196:199], v[90:93]
	s_waitcnt lgkmcnt(1)
	v_mfma_f32_16x16x32_bf16 v[78:81], v[148:151], v[204:207], v[78:81]
	v_mfma_f32_16x16x32_bf16 v[74:77], v[156:159], v[204:207], v[74:77]
	v_mfma_f32_16x16x32_bf16 v[126:129], v[152:155], v[184:187], v[126:129]
	v_mfma_f32_16x16x32_bf16 v[122:125], v[160:163], v[184:187], v[122:125]
	v_mfma_f32_16x16x32_bf16 v[110:113], v[152:155], v[192:195], v[110:113]
	v_mfma_f32_16x16x32_bf16 v[106:109], v[160:163], v[192:195], v[106:109]
	v_mfma_f32_16x16x32_bf16 v[94:97], v[152:155], v[200:203], v[94:97]
	v_mfma_f32_16x16x32_bf16 v[90:93], v[160:163], v[200:203], v[90:93]
	s_waitcnt lgkmcnt(0)
	v_mfma_f32_16x16x32_bf16 v[78:81], v[152:155], v[208:211], v[78:81]
	v_mfma_f32_16x16x32_bf16 v[74:77], v[160:163], v[208:211], v[74:77]
	s_setprio 0
	s_setprio 1
	v_mfma_f32_16x16x32_bf16 v[118:121], v[164:167], v[180:183], v[118:121]
	v_mfma_f32_16x16x32_bf16 v[114:117], v[172:175], v[180:183], v[114:117]
	v_mfma_f32_16x16x32_bf16 v[102:105], v[164:167], v[188:191], v[102:105]
	v_mfma_f32_16x16x32_bf16 v[98:101], v[172:175], v[188:191], v[98:101]
	v_mfma_f32_16x16x32_bf16 v[86:89], v[164:167], v[196:199], v[86:89]
	v_mfma_f32_16x16x32_bf16 v[82:85], v[172:175], v[196:199], v[82:85]
	v_mfma_f32_16x16x32_bf16 v[70:73], v[164:167], v[204:207], v[70:73]
	v_mfma_f32_16x16x32_bf16 v[66:69], v[172:175], v[204:207], v[66:69]
	v_mfma_f32_16x16x32_bf16 v[118:121], v[168:171], v[184:187], v[118:121]
	v_mfma_f32_16x16x32_bf16 v[114:117], v[176:179], v[184:187], v[114:117]
	v_mfma_f32_16x16x32_bf16 v[102:105], v[168:171], v[192:195], v[102:105]
	v_mfma_f32_16x16x32_bf16 v[98:101], v[176:179], v[192:195], v[98:101]
	v_mfma_f32_16x16x32_bf16 v[86:89], v[168:171], v[200:203], v[86:89]
	v_mfma_f32_16x16x32_bf16 v[82:85], v[176:179], v[200:203], v[82:85]
	s_setprio 2
	s_barrier
	v_mfma_f32_16x16x32_bf16 v[70:73], v[168:171], v[208:211], v[70:73]
	v_mfma_f32_16x16x32_bf16 v[66:69], v[176:179], v[208:211], v[66:69]
	s_setprio 0
	s_add_u32 s22, s20, 0x80
	s_addc_u32 s23, s21, 0
	s_mov_b32 s82, m0
	s_mov_b32 m0, s48
	s_nop 0
	global_load_lds_dwordx4 v139, s[22:23]
	s_mov_b32 m0, s82
	s_add_u32 s20, s20, 0x80080
	s_mov_b32 s82, m0
	s_mov_b32 m0, s49
	s_nop 0
	global_load_lds_dwordx4 v141, s[22:23]
	s_mov_b32 m0, s82
	s_addc_u32 s21, s21, 0
	s_mov_b32 s22, m0
	s_mov_b32 m0, s56
	s_nop 0
	global_load_lds_dwordx4 v139, s[20:21]
	s_mov_b32 m0, s22
	s_nop 0
	s_mov_b32 s22, m0
	s_mov_b32 m0, s57
	s_nop 0
	global_load_lds_dwordx4 v141, s[20:21]
	s_mov_b32 m0, s22
	ds_read_b128 v[180:183], v145 offset:49152
	ds_read_b128 v[184:187], v145 offset:50176
	ds_read_b128 v[188:191], v145 offset:51200
	ds_read_b128 v[192:195], v145 offset:52224
	ds_read_b128 v[196:199], v145 offset:53248
	ds_read_b128 v[200:203], v145 offset:54272
	ds_read_b128 v[204:207], v145 offset:55296
	ds_read_b128 v[208:211], v145 offset:56320
	s_waitcnt vmcnt(4)
	s_waitcnt lgkmcnt(0)
	s_barrier
	s_setprio 1
	s_waitcnt lgkmcnt(7)
	v_mfma_f32_16x16x32_bf16 v[62:65], v[148:151], v[180:183], v[62:65]
	v_mfma_f32_16x16x32_bf16 v[58:61], v[156:159], v[180:183], v[58:61]
	s_waitcnt lgkmcnt(5)
	v_mfma_f32_16x16x32_bf16 v[46:49], v[148:151], v[188:191], v[46:49]
	v_mfma_f32_16x16x32_bf16 v[42:45], v[156:159], v[188:191], v[42:45]
	s_waitcnt lgkmcnt(3)
	v_mfma_f32_16x16x32_bf16 v[30:33], v[148:151], v[196:199], v[30:33]
	v_mfma_f32_16x16x32_bf16 v[26:29], v[156:159], v[196:199], v[26:29]
	s_waitcnt lgkmcnt(1)
	v_mfma_f32_16x16x32_bf16 v[14:17], v[148:151], v[204:207], v[14:17]
	v_mfma_f32_16x16x32_bf16 v[10:13], v[156:159], v[204:207], v[10:13]
	v_mfma_f32_16x16x32_bf16 v[62:65], v[152:155], v[184:187], v[62:65]
	v_mfma_f32_16x16x32_bf16 v[58:61], v[160:163], v[184:187], v[58:61]
	v_mfma_f32_16x16x32_bf16 v[46:49], v[152:155], v[192:195], v[46:49]
	v_mfma_f32_16x16x32_bf16 v[42:45], v[160:163], v[192:195], v[42:45]
	v_mfma_f32_16x16x32_bf16 v[30:33], v[152:155], v[200:203], v[30:33]
	v_mfma_f32_16x16x32_bf16 v[26:29], v[160:163], v[200:203], v[26:29]
	s_waitcnt lgkmcnt(0)
	v_mfma_f32_16x16x32_bf16 v[14:17], v[152:155], v[208:211], v[14:17]
	v_mfma_f32_16x16x32_bf16 v[10:13], v[160:163], v[208:211], v[10:13]
	s_setprio 0
	s_setprio 1
	v_mfma_f32_16x16x32_bf16 v[54:57], v[164:167], v[180:183], v[54:57]
	v_mfma_f32_16x16x32_bf16 v[50:53], v[172:175], v[180:183], v[50:53]
	v_mfma_f32_16x16x32_bf16 v[38:41], v[164:167], v[188:191], v[38:41]
	v_mfma_f32_16x16x32_bf16 v[34:37], v[172:175], v[188:191], v[34:37]
	v_mfma_f32_16x16x32_bf16 v[22:25], v[164:167], v[196:199], v[22:25]
	v_mfma_f32_16x16x32_bf16 v[18:21], v[172:175], v[196:199], v[18:21]
	v_mfma_f32_16x16x32_bf16 v[6:9], v[164:167], v[204:207], v[6:9]
	v_mfma_f32_16x16x32_bf16 v[2:5], v[172:175], v[204:207], v[2:5]
	v_mfma_f32_16x16x32_bf16 v[54:57], v[168:171], v[184:187], v[54:57]
	v_mfma_f32_16x16x32_bf16 v[50:53], v[176:179], v[184:187], v[50:53]
	v_mfma_f32_16x16x32_bf16 v[38:41], v[168:171], v[192:195], v[38:41]
	v_mfma_f32_16x16x32_bf16 v[34:37], v[176:179], v[192:195], v[34:37]
	v_mfma_f32_16x16x32_bf16 v[22:25], v[168:171], v[200:203], v[22:25]
	v_mfma_f32_16x16x32_bf16 v[18:21], v[176:179], v[200:203], v[18:21]
	s_setprio 2
	s_barrier
	v_mfma_f32_16x16x32_bf16 v[6:9], v[168:171], v[208:211], v[6:9]
	v_mfma_f32_16x16x32_bf16 v[2:5], v[176:179], v[208:211], v[2:5]
	s_setprio 0
	s_add_i32 s81, s81, 2
	s_add_u32 s77, s77, 0x100
	s_addc_u32 s78, s78, 0
	s_add_u32 s18, s18, 0x100
	s_addc_u32 s19, s19, 0
	s_add_u32 s79, s79, 0x100
	s_addc_u32 s80, s80, 0
	s_cmp_gt_u32 s81, 29
	s_cbranch_scc0 .LBB0_344
	s_and_b64 vcc, exec, s[6:7]
	s_cbranch_vccz .LBB0_347
	s_barrier

.LBB0_473:
	s_cmpk_eq_i32 s82, 0x52
	s_cselect_b32 s23, s11, s79
	s_cselect_b32 s22, s77, s78
	s_cselect_b32 s25, s13, s81
	s_cselect_b32 s24, s76, s80
	s_add_u32 s86, s20, 0xffffc000
	s_addc_u32 s87, s21, -1
	s_mov_b32 s83, m0
	s_mov_b32 m0, s65
	s_nop 0
	global_load_lds_dwordx4 v1, s[86:87]
	s_mov_b32 m0, s83
	s_nop 0
	s_mov_b32 s83, m0
	s_mov_b32 m0, s67
	s_nop 0
	global_load_lds_dwordx4 v157, s[86:87]
	s_mov_b32 m0, s83
	s_nop 0
	s_mov_b32 s83, m0
	s_mov_b32 m0, s66
	s_nop 0
	global_load_lds_dwordx4 v1, s[20:21]
	s_mov_b32 m0, s83
	s_nop 0
	s_mov_b32 s83, m0
	s_mov_b32 m0, s73
	s_nop 0
	global_load_lds_dwordx4 v157, s[20:21]
	s_mov_b32 m0, s83
	ds_read_b128 v[134:137], v161
	ds_read_b128 v[138:141], v161 offset:1024
	ds_read_b128 v[142:145], v161 offset:2048
	ds_read_b128 v[146:149], v161 offset:3072
	ds_read_b128 v[150:153], v162
	ds_read_b128 v[166:169], v162 offset:1024
	ds_read_b128 v[170:173], v162 offset:2048
	ds_read_b128 v[174:177], v162 offset:3072
	ds_read_b128 v[178:181], v163
	ds_read_b128 v[182:185], v163 offset:1024
	ds_read_b128 v[186:189], v163 offset:2048
	ds_read_b128 v[190:193], v163 offset:3072
	ds_read_b128 v[194:197], v163 offset:4096
	ds_read_b128 v[198:201], v163 offset:5120
	ds_read_b128 v[202:205], v163 offset:6144
	ds_read_b128 v[206:209], v163 offset:7168
	s_waitcnt vmcnt(8)
	s_waitcnt lgkmcnt(0)
	s_barrier
	s_setprio 1
	s_waitcnt lgkmcnt(7)
	v_mfma_f32_16x16x32_bf16 v[126:129], v[134:137], v[178:181], v[126:129]
	v_mfma_f32_16x16x32_bf16 v[122:125], v[142:145], v[178:181], v[122:125]
	s_waitcnt lgkmcnt(5)
	v_mfma_f32_16x16x32_bf16 v[118:121], v[134:137], v[186:189], v[118:121]
	v_mfma_f32_16x16x32_bf16 v[114:117], v[142:145], v[186:189], v[114:117]
	s_waitcnt lgkmcnt(3)
	v_mfma_f32_16x16x32_bf16 v[102:105], v[134:137], v[194:197], v[102:105]
	v_mfma_f32_16x16x32_bf16 v[94:97], v[142:145], v[194:197], v[94:97]
	s_waitcnt lgkmcnt(1)
	v_mfma_f32_16x16x32_bf16 v[86:89], v[134:137], v[202:205], v[86:89]
	v_mfma_f32_16x16x32_bf16 v[78:81], v[142:145], v[202:205], v[78:81]
	v_mfma_f32_16x16x32_bf16 v[126:129], v[138:141], v[182:185], v[126:129]
	v_mfma_f32_16x16x32_bf16 v[122:125], v[146:149], v[182:185], v[122:125]
	v_mfma_f32_16x16x32_bf16 v[118:121], v[138:141], v[190:193], v[118:121]
	v_mfma_f32_16x16x32_bf16 v[114:117], v[146:149], v[190:193], v[114:117]
	v_mfma_f32_16x16x32_bf16 v[102:105], v[138:141], v[198:201], v[102:105]
	v_mfma_f32_16x16x32_bf16 v[94:97], v[146:149], v[198:201], v[94:97]
	s_waitcnt lgkmcnt(0)
	v_mfma_f32_16x16x32_bf16 v[86:89], v[138:141], v[206:209], v[86:89]
	v_mfma_f32_16x16x32_bf16 v[78:81], v[146:149], v[206:209], v[78:81]
	s_setprio 0
	s_setprio 1
	v_mfma_f32_16x16x32_bf16 v[110:113], v[150:153], v[178:181], v[110:113]
	v_mfma_f32_16x16x32_bf16 v[106:109], v[170:173], v[178:181], v[106:109]
	v_mfma_f32_16x16x32_bf16 v[98:101], v[150:153], v[186:189], v[98:101]
	v_mfma_f32_16x16x32_bf16 v[90:93], v[170:173], v[186:189], v[90:93]
	v_mfma_f32_16x16x32_bf16 v[82:85], v[150:153], v[194:197], v[82:85]
	v_mfma_f32_16x16x32_bf16 v[74:77], v[170:173], v[194:197], v[74:77]
	v_mfma_f32_16x16x32_bf16 v[70:73], v[150:153], v[202:205], v[70:73]
	v_mfma_f32_16x16x32_bf16 v[66:69], v[170:173], v[202:205], v[66:69]
	v_mfma_f32_16x16x32_bf16 v[110:113], v[166:169], v[182:185], v[110:113]
	v_mfma_f32_16x16x32_bf16 v[106:109], v[174:177], v[182:185], v[106:109]
	v_mfma_f32_16x16x32_bf16 v[98:101], v[166:169], v[190:193], v[98:101]
	v_mfma_f32_16x16x32_bf16 v[90:93], v[174:177], v[190:193], v[90:93]
	v_mfma_f32_16x16x32_bf16 v[82:85], v[166:169], v[198:201], v[82:85]
	v_mfma_f32_16x16x32_bf16 v[74:77], v[174:177], v[198:201], v[74:77]
	s_setprio 2
	s_barrier
	v_mfma_f32_16x16x32_bf16 v[70:73], v[166:169], v[206:209], v[70:73]
	v_mfma_f32_16x16x32_bf16 v[66:69], v[174:177], v[206:209], v[66:69]
	s_setprio 0
	s_mov_b32 s83, m0
	s_mov_b32 m0, s19
	s_nop 0
	global_load_lds_dwordx4 v156, s[22:23]
	s_mov_b32 m0, s83
	s_add_u32 s86, s22, 0x4000
	s_mov_b32 s83, m0
	s_mov_b32 m0, s35
	s_nop 0
	global_load_lds_dwordx4 v158, s[22:23]
	s_mov_b32 m0, s83
	s_addc_u32 s87, s23, 0
	s_mov_b32 s83, m0
	s_mov_b32 m0, s36
	s_nop 0
	global_load_lds_dwordx4 v156, s[86:87]
	s_mov_b32 m0, s83
	s_nop 0
	s_mov_b32 s83, m0
	s_mov_b32 m0, s37
	s_nop 0
	global_load_lds_dwordx4 v158, s[86:87]
	s_mov_b32 m0, s83
	ds_read_b128 v[178:181], v163 offset:16384
	ds_read_b128 v[182:185], v163 offset:17408
	ds_read_b128 v[186:189], v163 offset:18432
	ds_read_b128 v[190:193], v163 offset:19456
	ds_read_b128 v[194:197], v163 offset:20480
	ds_read_b128 v[198:201], v163 offset:21504
	ds_read_b128 v[202:205], v163 offset:22528
	ds_read_b128 v[206:209], v163 offset:23552
	s_waitcnt vmcnt(4)
	s_waitcnt lgkmcnt(0)
	s_barrier
	s_setprio 1
	s_waitcnt lgkmcnt(7)
	v_mfma_f32_16x16x32_bf16 v[62:65], v[134:137], v[178:181], v[62:65]
	v_mfma_f32_16x16x32_bf16 v[58:61], v[142:145], v[178:181], v[58:61]
	s_waitcnt lgkmcnt(5)
	v_mfma_f32_16x16x32_bf16 v[54:57], v[134:137], v[186:189], v[54:57]
	v_mfma_f32_16x16x32_bf16 v[46:49], v[142:145], v[186:189], v[46:49]
	s_waitcnt lgkmcnt(3)
	v_mfma_f32_16x16x32_bf16 v[38:41], v[134:137], v[194:197], v[38:41]
	v_mfma_f32_16x16x32_bf16 v[30:33], v[142:145], v[194:197], v[30:33]
	s_waitcnt lgkmcnt(1)
	v_mfma_f32_16x16x32_bf16 v[22:25], v[134:137], v[202:205], v[22:25]
	v_mfma_f32_16x16x32_bf16 v[14:17], v[142:145], v[202:205], v[14:17]
	v_mfma_f32_16x16x32_bf16 v[62:65], v[138:141], v[182:185], v[62:65]
	v_mfma_f32_16x16x32_bf16 v[58:61], v[146:149], v[182:185], v[58:61]
	v_mfma_f32_16x16x32_bf16 v[54:57], v[138:141], v[190:193], v[54:57]
	v_mfma_f32_16x16x32_bf16 v[46:49], v[146:149], v[190:193], v[46:49]
	v_mfma_f32_16x16x32_bf16 v[38:41], v[138:141], v[198:201], v[38:41]
	v_mfma_f32_16x16x32_bf16 v[30:33], v[146:149], v[198:201], v[30:33]
	s_waitcnt lgkmcnt(0)
	v_mfma_f32_16x16x32_bf16 v[22:25], v[138:141], v[206:209], v[22:25]
	v_mfma_f32_16x16x32_bf16 v[14:17], v[146:149], v[206:209], v[14:17]
	s_setprio 0
	s_setprio 1
	v_mfma_f32_16x16x32_bf16 v[50:53], v[150:153], v[178:181], v[50:53]
	v_mfma_f32_16x16x32_bf16 v[42:45], v[170:173], v[178:181], v[42:45]
	v_mfma_f32_16x16x32_bf16 v[34:37], v[150:153], v[186:189], v[34:37]
	v_mfma_f32_16x16x32_bf16 v[26:29], v[170:173], v[186:189], v[26:29]
	v_mfma_f32_16x16x32_bf16 v[18:21], v[150:153], v[194:197], v[18:21]
	v_mfma_f32_16x16x32_bf16 v[10:13], v[170:173], v[194:197], v[10:13]
	v_mfma_f32_16x16x32_bf16 v[6:9], v[150:153], v[202:205], v[6:9]
	v_mfma_f32_16x16x32_bf16 v[2:5], v[170:173], v[202:205], v[2:5]
	v_mfma_f32_16x16x32_bf16 v[50:53], v[166:169], v[182:185], v[50:53]
	v_mfma_f32_16x16x32_bf16 v[42:45], v[174:177], v[182:185], v[42:45]
	v_mfma_f32_16x16x32_bf16 v[34:37], v[166:169], v[190:193], v[34:37]
	v_mfma_f32_16x16x32_bf16 v[26:29], v[174:177], v[190:193], v[26:29]
	v_mfma_f32_16x16x32_bf16 v[18:21], v[166:169], v[198:201], v[18:21]
	v_mfma_f32_16x16x32_bf16 v[10:13], v[174:177], v[198:201], v[10:13]
	s_setprio 2
	s_barrier
	v_mfma_f32_16x16x32_bf16 v[6:9], v[166:169], v[206:209], v[6:9]
	v_mfma_f32_16x16x32_bf16 v[2:5], v[174:177], v[206:209], v[2:5]
	s_setprio 0
	s_mov_b32 s83, m0
	s_mov_b32 m0, s34
	s_nop 0
	global_load_lds_dwordx4 v1, s[24:25]
	s_mov_b32 m0, s83
	s_nop 0
	s_mov_b32 s83, m0
	s_mov_b32 m0, s42
	s_nop 0
	global_load_lds_dwordx4 v157, s[24:25]
	s_mov_b32 m0, s83
	s_add_u32 s24, s24, 0x4000
	s_addc_u32 s25, s25, 0
	s_mov_b32 s83, m0
	s_mov_b32 m0, s43
	s_nop 0
	global_load_lds_dwordx4 v1, s[24:25]
	s_mov_b32 m0, s83
	s_nop 0
	s_mov_b32 s83, m0
	s_mov_b32 m0, s46
	s_nop 0
	global_load_lds_dwordx4 v157, s[24:25]
	s_mov_b32 m0, s83
	ds_read_b128 v[134:137], v164
	ds_read_b128 v[138:141], v164 offset:1024
	ds_read_b128 v[142:145], v164 offset:2048
	ds_read_b128 v[146:149], v164 offset:3072
	ds_read_b128 v[150:153], v165
	ds_read_b128 v[166:169], v165 offset:1024
	ds_read_b128 v[170:173], v165 offset:2048
	ds_read_b128 v[174:177], v165 offset:3072
	ds_read_b128 v[178:181], v163 offset:32768
	ds_read_b128 v[182:185], v163 offset:33792
	ds_read_b128 v[186:189], v163 offset:34816
	ds_read_b128 v[190:193], v163 offset:35840
	ds_read_b128 v[194:197], v163 offset:36864
	ds_read_b128 v[198:201], v163 offset:37888
	ds_read_b128 v[202:205], v163 offset:38912
	ds_read_b128 v[206:209], v163 offset:39936
	s_waitcnt vmcnt(8)
	s_waitcnt lgkmcnt(0)
	s_barrier
	s_setprio 1
	s_waitcnt lgkmcnt(7)
	v_mfma_f32_16x16x32_bf16 v[126:129], v[134:137], v[178:181], v[126:129]
	v_mfma_f32_16x16x32_bf16 v[122:125], v[142:145], v[178:181], v[122:125]
	s_waitcnt lgkmcnt(5)
	v_mfma_f32_16x16x32_bf16 v[118:121], v[134:137], v[186:189], v[118:121]
	v_mfma_f32_16x16x32_bf16 v[114:117], v[142:145], v[186:189], v[114:117]
	s_waitcnt lgkmcnt(3)
	v_mfma_f32_16x16x32_bf16 v[102:105], v[134:137], v[194:197], v[102:105]
	v_mfma_f32_16x16x32_bf16 v[94:97], v[142:145], v[194:197], v[94:97]
	s_waitcnt lgkmcnt(1)
	v_mfma_f32_16x16x32_bf16 v[86:89], v[134:137], v[202:205], v[86:89]
	v_mfma_f32_16x16x32_bf16 v[78:81], v[142:145], v[202:205], v[78:81]
	v_mfma_f32_16x16x32_bf16 v[126:129], v[138:141], v[182:185], v[126:129]
	v_mfma_f32_16x16x32_bf16 v[122:125], v[146:149], v[182:185], v[122:125]
	v_mfma_f32_16x16x32_bf16 v[118:121], v[138:141], v[190:193], v[118:121]
	v_mfma_f32_16x16x32_bf16 v[114:117], v[146:149], v[190:193], v[114:117]
	v_mfma_f32_16x16x32_bf16 v[102:105], v[138:141], v[198:201], v[102:105]
	v_mfma_f32_16x16x32_bf16 v[94:97], v[146:149], v[198:201], v[94:97]
	s_waitcnt lgkmcnt(0)
	v_mfma_f32_16x16x32_bf16 v[86:89], v[138:141], v[206:209], v[86:89]
	v_mfma_f32_16x16x32_bf16 v[78:81], v[146:149], v[206:209], v[78:81]
	s_setprio 0
	s_setprio 1
	v_mfma_f32_16x16x32_bf16 v[110:113], v[150:153], v[178:181], v[110:113]
	v_mfma_f32_16x16x32_bf16 v[106:109], v[170:173], v[178:181], v[106:109]
	v_mfma_f32_16x16x32_bf16 v[98:101], v[150:153], v[186:189], v[98:101]
	v_mfma_f32_16x16x32_bf16 v[90:93], v[170:173], v[186:189], v[90:93]
	v_mfma_f32_16x16x32_bf16 v[82:85], v[150:153], v[194:197], v[82:85]
	v_mfma_f32_16x16x32_bf16 v[74:77], v[170:173], v[194:197], v[74:77]
	v_mfma_f32_16x16x32_bf16 v[70:73], v[150:153], v[202:205], v[70:73]
	v_mfma_f32_16x16x32_bf16 v[66:69], v[170:173], v[202:205], v[66:69]
	v_mfma_f32_16x16x32_bf16 v[110:113], v[166:169], v[182:185], v[110:113]
	v_mfma_f32_16x16x32_bf16 v[106:109], v[174:177], v[182:185], v[106:109]
	v_mfma_f32_16x16x32_bf16 v[98:101], v[166:169], v[190:193], v[98:101]
	v_mfma_f32_16x16x32_bf16 v[90:93], v[174:177], v[190:193], v[90:93]
	v_mfma_f32_16x16x32_bf16 v[82:85], v[166:169], v[198:201], v[82:85]
	v_mfma_f32_16x16x32_bf16 v[74:77], v[174:177], v[198:201], v[74:77]
	s_setprio 2
	s_barrier
	v_mfma_f32_16x16x32_bf16 v[70:73], v[166:169], v[206:209], v[70:73]
	v_mfma_f32_16x16x32_bf16 v[66:69], v[174:177], v[206:209], v[66:69]
	s_setprio 0
	s_add_u32 s24, s22, 0x40000
	s_addc_u32 s25, s23, 0
	s_mov_b32 s83, m0
	s_mov_b32 m0, s47
	s_nop 0
	global_load_lds_dwordx4 v156, s[24:25]
	s_mov_b32 m0, s83
	s_add_u32 s22, s22, 0x44000
	s_mov_b32 s83, m0
	s_mov_b32 m0, s48
	s_nop 0
	global_load_lds_dwordx4 v158, s[24:25]
	s_mov_b32 m0, s83
	s_addc_u32 s23, s23, 0
	s_mov_b32 s24, m0
	s_mov_b32 m0, s49
	s_nop 0
	global_load_lds_dwordx4 v156, s[22:23]
	s_mov_b32 m0, s24
	s_nop 0
	s_mov_b32 s24, m0
	s_mov_b32 m0, s56
	s_nop 0
	global_load_lds_dwordx4 v158, s[22:23]
	s_mov_b32 m0, s24
	ds_read_b128 v[178:181], v163 offset:49152
	ds_read_b128 v[182:185], v163 offset:50176
	ds_read_b128 v[186:189], v163 offset:51200
	ds_read_b128 v[190:193], v163 offset:52224
	ds_read_b128 v[194:197], v163 offset:53248
	ds_read_b128 v[198:201], v163 offset:54272
	ds_read_b128 v[202:205], v163 offset:55296
	ds_read_b128 v[206:209], v163 offset:56320
	s_waitcnt vmcnt(4)
	s_waitcnt lgkmcnt(0)
	s_barrier
	s_setprio 1
	s_waitcnt lgkmcnt(7)
	v_mfma_f32_16x16x32_bf16 v[62:65], v[134:137], v[178:181], v[62:65]
	v_mfma_f32_16x16x32_bf16 v[58:61], v[142:145], v[178:181], v[58:61]
	s_waitcnt lgkmcnt(5)
	v_mfma_f32_16x16x32_bf16 v[54:57], v[134:137], v[186:189], v[54:57]
	v_mfma_f32_16x16x32_bf16 v[46:49], v[142:145], v[186:189], v[46:49]
	s_waitcnt lgkmcnt(3)
	v_mfma_f32_16x16x32_bf16 v[38:41], v[134:137], v[194:197], v[38:41]
	v_mfma_f32_16x16x32_bf16 v[30:33], v[142:145], v[194:197], v[30:33]
	s_waitcnt lgkmcnt(1)
	v_mfma_f32_16x16x32_bf16 v[22:25], v[134:137], v[202:205], v[22:25]
	v_mfma_f32_16x16x32_bf16 v[14:17], v[142:145], v[202:205], v[14:17]
	v_mfma_f32_16x16x32_bf16 v[62:65], v[138:141], v[182:185], v[62:65]
	v_mfma_f32_16x16x32_bf16 v[58:61], v[146:149], v[182:185], v[58:61]
	v_mfma_f32_16x16x32_bf16 v[54:57], v[138:141], v[190:193], v[54:57]
	v_mfma_f32_16x16x32_bf16 v[46:49], v[146:149], v[190:193], v[46:49]
	v_mfma_f32_16x16x32_bf16 v[38:41], v[138:141], v[198:201], v[38:41]
	v_mfma_f32_16x16x32_bf16 v[30:33], v[146:149], v[198:201], v[30:33]
	s_waitcnt lgkmcnt(0)
	v_mfma_f32_16x16x32_bf16 v[22:25], v[138:141], v[206:209], v[22:25]
	v_mfma_f32_16x16x32_bf16 v[14:17], v[146:149], v[206:209], v[14:17]
	s_setprio 0
	s_setprio 1
	v_mfma_f32_16x16x32_bf16 v[50:53], v[150:153], v[178:181], v[50:53]
	v_mfma_f32_16x16x32_bf16 v[42:45], v[170:173], v[178:181], v[42:45]
	v_mfma_f32_16x16x32_bf16 v[34:37], v[150:153], v[186:189], v[34:37]
	v_mfma_f32_16x16x32_bf16 v[26:29], v[170:173], v[186:189], v[26:29]
	v_mfma_f32_16x16x32_bf16 v[18:21], v[150:153], v[194:197], v[18:21]
	v_mfma_f32_16x16x32_bf16 v[10:13], v[170:173], v[194:197], v[10:13]
	v_mfma_f32_16x16x32_bf16 v[6:9], v[150:153], v[202:205], v[6:9]
	v_mfma_f32_16x16x32_bf16 v[2:5], v[170:173], v[202:205], v[2:5]
	v_mfma_f32_16x16x32_bf16 v[50:53], v[166:169], v[182:185], v[50:53]
	v_mfma_f32_16x16x32_bf16 v[42:45], v[174:177], v[182:185], v[42:45]
	v_mfma_f32_16x16x32_bf16 v[34:37], v[166:169], v[190:193], v[34:37]
	v_mfma_f32_16x16x32_bf16 v[26:29], v[174:177], v[190:193], v[26:29]
	v_mfma_f32_16x16x32_bf16 v[18:21], v[166:169], v[198:201], v[18:21]
	v_mfma_f32_16x16x32_bf16 v[10:13], v[174:177], v[198:201], v[10:13]
	s_setprio 2
	s_barrier
	v_mfma_f32_16x16x32_bf16 v[6:9], v[166:169], v[206:209], v[6:9]
	v_mfma_f32_16x16x32_bf16 v[2:5], v[174:177], v[206:209], v[2:5]
	s_setprio 0
	s_add_i32 s82, s82, 2
	s_add_u32 s78, s78, 0x80000
	s_addc_u32 s79, s79, 0
	s_add_u32 s20, s20, 0x400000
	s_addc_u32 s21, s21, 0
	s_add_u32 s80, s80, 0x400000
	s_addc_u32 s81, s81, 0
	s_cmpk_gt_u32 s82, 0x53
	s_cbranch_scc0 .LBB0_473
	s_and_b64 vcc, exec, s[8:9]
	s_cbranch_vccz .LBB0_476
	s_barrier

.LBB0_654:
	s_cmp_eq_u32 s74, 28
	s_cselect_b32 s11, s21, s31
	s_cselect_b32 s10, s23, s30
	s_cselect_b32 s29, s7, s73
	s_cselect_b32 s28, s9, s33
	s_add_u32 s76, s4, 0xfff80000
	s_addc_u32 s77, s5, -1
	s_mov_b32 s75, m0
	s_mov_b32 m0, s80
	s_nop 0
	global_load_lds_dwordx4 v1, s[76:77]
	s_mov_b32 m0, s75
	s_nop 0
	s_mov_b32 s75, m0
	s_mov_b32 m0, s82
	s_nop 0
	global_load_lds_dwordx4 v157, s[76:77]
	s_mov_b32 m0, s75
	s_nop 0
	s_mov_b32 s75, m0
	s_mov_b32 m0, s81
	s_nop 0
	global_load_lds_dwordx4 v1, s[4:5]
	s_mov_b32 m0, s75
	s_nop 0
	s_mov_b32 s75, m0
	s_mov_b32 m0, s83
	s_nop 0
	global_load_lds_dwordx4 v157, s[4:5]
	s_mov_b32 m0, s75
	ds_read_b128 v[130:133], v161
	ds_read_b128 v[138:141], v161 offset:1024
	ds_read_b128 v[142:145], v161 offset:2048
	ds_read_b128 v[146:149], v161 offset:3072
	ds_read_b128 v[150:153], v162
	ds_read_b128 v[168:171], v162 offset:1024
	ds_read_b128 v[172:175], v162 offset:2048
	ds_read_b128 v[176:179], v162 offset:3072
	ds_read_b128 v[180:183], v163
	ds_read_b128 v[184:187], v163 offset:1024
	ds_read_b128 v[188:191], v163 offset:2048
	ds_read_b128 v[192:195], v163 offset:3072
	ds_read_b128 v[196:199], v163 offset:4096
	ds_read_b128 v[200:203], v163 offset:5120
	ds_read_b128 v[204:207], v163 offset:6144
	ds_read_b128 v[208:211], v163 offset:7168
	s_waitcnt vmcnt(8)
	s_waitcnt lgkmcnt(0)
	s_barrier
	s_setprio 1
	s_waitcnt lgkmcnt(7)
	v_mfma_f32_16x16x32_bf16 v[126:129], v[130:133], v[180:183], v[126:129]
	v_mfma_f32_16x16x32_bf16 v[122:125], v[142:145], v[180:183], v[122:125]
	s_waitcnt lgkmcnt(5)
	v_mfma_f32_16x16x32_bf16 v[110:113], v[130:133], v[188:191], v[110:113]
	v_mfma_f32_16x16x32_bf16 v[106:109], v[142:145], v[188:191], v[106:109]
	s_waitcnt lgkmcnt(3)
	v_mfma_f32_16x16x32_bf16 v[94:97], v[130:133], v[196:199], v[94:97]
	v_mfma_f32_16x16x32_bf16 v[90:93], v[142:145], v[196:199], v[90:93]
	s_waitcnt lgkmcnt(1)
	v_mfma_f32_16x16x32_bf16 v[78:81], v[130:133], v[204:207], v[78:81]
	v_mfma_f32_16x16x32_bf16 v[74:77], v[142:145], v[204:207], v[74:77]
	v_mfma_f32_16x16x32_bf16 v[126:129], v[138:141], v[184:187], v[126:129]
	v_mfma_f32_16x16x32_bf16 v[122:125], v[146:149], v[184:187], v[122:125]
	v_mfma_f32_16x16x32_bf16 v[110:113], v[138:141], v[192:195], v[110:113]
	v_mfma_f32_16x16x32_bf16 v[106:109], v[146:149], v[192:195], v[106:109]
	v_mfma_f32_16x16x32_bf16 v[94:97], v[138:141], v[200:203], v[94:97]
	v_mfma_f32_16x16x32_bf16 v[90:93], v[146:149], v[200:203], v[90:93]
	s_waitcnt lgkmcnt(0)
	v_mfma_f32_16x16x32_bf16 v[78:81], v[138:141], v[208:211], v[78:81]
	v_mfma_f32_16x16x32_bf16 v[74:77], v[146:149], v[208:211], v[74:77]
	s_setprio 0
	s_setprio 1
	v_mfma_f32_16x16x32_bf16 v[118:121], v[150:153], v[180:183], v[118:121]
	v_mfma_f32_16x16x32_bf16 v[114:117], v[172:175], v[180:183], v[114:117]
	v_mfma_f32_16x16x32_bf16 v[102:105], v[150:153], v[188:191], v[102:105]
	v_mfma_f32_16x16x32_bf16 v[98:101], v[172:175], v[188:191], v[98:101]
	v_mfma_f32_16x16x32_bf16 v[86:89], v[150:153], v[196:199], v[86:89]
	v_mfma_f32_16x16x32_bf16 v[82:85], v[172:175], v[196:199], v[82:85]
	v_mfma_f32_16x16x32_bf16 v[70:73], v[150:153], v[204:207], v[70:73]
	v_mfma_f32_16x16x32_bf16 v[66:69], v[172:175], v[204:207], v[66:69]
	v_mfma_f32_16x16x32_bf16 v[118:121], v[168:171], v[184:187], v[118:121]
	v_mfma_f32_16x16x32_bf16 v[114:117], v[176:179], v[184:187], v[114:117]
	v_mfma_f32_16x16x32_bf16 v[102:105], v[168:171], v[192:195], v[102:105]
	v_mfma_f32_16x16x32_bf16 v[98:101], v[176:179], v[192:195], v[98:101]
	v_mfma_f32_16x16x32_bf16 v[86:89], v[168:171], v[200:203], v[86:89]
	v_mfma_f32_16x16x32_bf16 v[82:85], v[176:179], v[200:203], v[82:85]
	s_setprio 2
	s_barrier
	v_mfma_f32_16x16x32_bf16 v[70:73], v[168:171], v[208:211], v[70:73]
	v_mfma_f32_16x16x32_bf16 v[66:69], v[176:179], v[208:211], v[66:69]
	s_setprio 0
	s_mov_b32 s75, m0
	s_mov_b32 m0, s43
	s_nop 0
	global_load_lds_dwordx4 v156, s[10:11]
	s_mov_b32 m0, s75
	s_add_u32 s76, s10, 0x80000
	s_mov_b32 s75, m0
	s_mov_b32 m0, s46
	s_nop 0
	global_load_lds_dwordx4 v158, s[10:11]
	s_mov_b32 m0, s75
	s_addc_u32 s77, s11, 0
	s_mov_b32 s75, m0
	s_mov_b32 m0, s47
	s_nop 0
	global_load_lds_dwordx4 v156, s[76:77]
	s_mov_b32 m0, s75
	s_nop 0
	s_mov_b32 s75, m0
	s_mov_b32 m0, s48
	s_nop 0
	global_load_lds_dwordx4 v158, s[76:77]
	s_mov_b32 m0, s75
	ds_read_b128 v[180:183], v163 offset:16384
	ds_read_b128 v[184:187], v163 offset:17408
	ds_read_b128 v[188:191], v163 offset:18432
	ds_read_b128 v[192:195], v163 offset:19456
	ds_read_b128 v[196:199], v163 offset:20480
	ds_read_b128 v[200:203], v163 offset:21504
	ds_read_b128 v[204:207], v163 offset:22528
	ds_read_b128 v[208:211], v163 offset:23552
	s_waitcnt vmcnt(4)
	s_waitcnt lgkmcnt(0)
	s_barrier
	s_setprio 1
	s_waitcnt lgkmcnt(7)
	v_mfma_f32_16x16x32_bf16 v[62:65], v[130:133], v[180:183], v[62:65]
	v_mfma_f32_16x16x32_bf16 v[58:61], v[142:145], v[180:183], v[58:61]
	s_waitcnt lgkmcnt(5)
	v_mfma_f32_16x16x32_bf16 v[46:49], v[130:133], v[188:191], v[46:49]
	v_mfma_f32_16x16x32_bf16 v[42:45], v[142:145], v[188:191], v[42:45]
	s_waitcnt lgkmcnt(3)
	v_mfma_f32_16x16x32_bf16 v[30:33], v[130:133], v[196:199], v[30:33]
	v_mfma_f32_16x16x32_bf16 v[26:29], v[142:145], v[196:199], v[26:29]
	s_waitcnt lgkmcnt(1)
	v_mfma_f32_16x16x32_bf16 v[14:17], v[130:133], v[204:207], v[14:17]
	v_mfma_f32_16x16x32_bf16 v[10:13], v[142:145], v[204:207], v[10:13]
	v_mfma_f32_16x16x32_bf16 v[62:65], v[138:141], v[184:187], v[62:65]
	v_mfma_f32_16x16x32_bf16 v[58:61], v[146:149], v[184:187], v[58:61]
	v_mfma_f32_16x16x32_bf16 v[46:49], v[138:141], v[192:195], v[46:49]
	v_mfma_f32_16x16x32_bf16 v[42:45], v[146:149], v[192:195], v[42:45]
	v_mfma_f32_16x16x32_bf16 v[30:33], v[138:141], v[200:203], v[30:33]
	v_mfma_f32_16x16x32_bf16 v[26:29], v[146:149], v[200:203], v[26:29]
	s_waitcnt lgkmcnt(0)
	v_mfma_f32_16x16x32_bf16 v[14:17], v[138:141], v[208:211], v[14:17]
	v_mfma_f32_16x16x32_bf16 v[10:13], v[146:149], v[208:211], v[10:13]
	s_setprio 0
	s_setprio 1
	v_mfma_f32_16x16x32_bf16 v[54:57], v[150:153], v[180:183], v[54:57]
	v_mfma_f32_16x16x32_bf16 v[50:53], v[172:175], v[180:183], v[50:53]
	v_mfma_f32_16x16x32_bf16 v[38:41], v[150:153], v[188:191], v[38:41]
	v_mfma_f32_16x16x32_bf16 v[34:37], v[172:175], v[188:191], v[34:37]
	v_mfma_f32_16x16x32_bf16 v[22:25], v[150:153], v[196:199], v[22:25]
	v_mfma_f32_16x16x32_bf16 v[18:21], v[172:175], v[196:199], v[18:21]
	v_mfma_f32_16x16x32_bf16 v[6:9], v[150:153], v[204:207], v[6:9]
	v_mfma_f32_16x16x32_bf16 v[2:5], v[172:175], v[204:207], v[2:5]
	v_mfma_f32_16x16x32_bf16 v[54:57], v[168:171], v[184:187], v[54:57]
	v_mfma_f32_16x16x32_bf16 v[50:53], v[176:179], v[184:187], v[50:53]
	v_mfma_f32_16x16x32_bf16 v[38:41], v[168:171], v[192:195], v[38:41]
	v_mfma_f32_16x16x32_bf16 v[34:37], v[176:179], v[192:195], v[34:37]
	v_mfma_f32_16x16x32_bf16 v[22:25], v[168:171], v[200:203], v[22:25]
	v_mfma_f32_16x16x32_bf16 v[18:21], v[176:179], v[200:203], v[18:21]
	s_setprio 2
	s_barrier
	v_mfma_f32_16x16x32_bf16 v[6:9], v[168:171], v[208:211], v[6:9]
	v_mfma_f32_16x16x32_bf16 v[2:5], v[176:179], v[208:211], v[2:5]
	s_setprio 0
	s_mov_b32 s75, m0
	s_mov_b32 m0, s42
	s_nop 0
	global_load_lds_dwordx4 v1, s[28:29]
	s_mov_b32 m0, s75
	s_nop 0
	s_mov_b32 s75, m0
	s_mov_b32 m0, s49
	s_nop 0
	global_load_lds_dwordx4 v157, s[28:29]
	s_mov_b32 m0, s75
	s_add_u32 s28, s28, 0x80000
	s_addc_u32 s29, s29, 0
	s_mov_b32 s75, m0
	s_mov_b32 m0, s56
	s_nop 0
	global_load_lds_dwordx4 v1, s[28:29]
	s_mov_b32 m0, s75
	s_nop 0
	s_mov_b32 s75, m0
	s_mov_b32 m0, s57
	s_nop 0
	global_load_lds_dwordx4 v157, s[28:29]
	s_mov_b32 m0, s75
	ds_read_b128 v[130:133], v164
	ds_read_b128 v[138:141], v164 offset:1024
	ds_read_b128 v[142:145], v164 offset:2048
	ds_read_b128 v[146:149], v164 offset:3072
	ds_read_b128 v[150:153], v165
	ds_read_b128 v[168:171], v165 offset:1024
	ds_read_b128 v[172:175], v165 offset:2048
	ds_read_b128 v[176:179], v165 offset:3072
	ds_read_b128 v[180:183], v163 offset:32768
	ds_read_b128 v[184:187], v163 offset:33792
	ds_read_b128 v[188:191], v163 offset:34816
	ds_read_b128 v[192:195], v163 offset:35840
	ds_read_b128 v[196:199], v163 offset:36864
	ds_read_b128 v[200:203], v163 offset:37888
	ds_read_b128 v[204:207], v163 offset:38912
	ds_read_b128 v[208:211], v163 offset:39936
	s_waitcnt vmcnt(8)
	s_waitcnt lgkmcnt(0)
	s_barrier
	s_setprio 1
	s_waitcnt lgkmcnt(7)
	v_mfma_f32_16x16x32_bf16 v[126:129], v[130:133], v[180:183], v[126:129]
	v_mfma_f32_16x16x32_bf16 v[122:125], v[142:145], v[180:183], v[122:125]
	s_waitcnt lgkmcnt(5)
	v_mfma_f32_16x16x32_bf16 v[110:113], v[130:133], v[188:191], v[110:113]
	v_mfma_f32_16x16x32_bf16 v[106:109], v[142:145], v[188:191], v[106:109]
	s_waitcnt lgkmcnt(3)
	v_mfma_f32_16x16x32_bf16 v[94:97], v[130:133], v[196:199], v[94:97]
	v_mfma_f32_16x16x32_bf16 v[90:93], v[142:145], v[196:199], v[90:93]
	s_waitcnt lgkmcnt(1)
	v_mfma_f32_16x16x32_bf16 v[78:81], v[130:133], v[204:207], v[78:81]
	v_mfma_f32_16x16x32_bf16 v[74:77], v[142:145], v[204:207], v[74:77]
	v_mfma_f32_16x16x32_bf16 v[126:129], v[138:141], v[184:187], v[126:129]
	v_mfma_f32_16x16x32_bf16 v[122:125], v[146:149], v[184:187], v[122:125]
	v_mfma_f32_16x16x32_bf16 v[110:113], v[138:141], v[192:195], v[110:113]
	v_mfma_f32_16x16x32_bf16 v[106:109], v[146:149], v[192:195], v[106:109]
	v_mfma_f32_16x16x32_bf16 v[94:97], v[138:141], v[200:203], v[94:97]
	v_mfma_f32_16x16x32_bf16 v[90:93], v[146:149], v[200:203], v[90:93]
	s_waitcnt lgkmcnt(0)
	v_mfma_f32_16x16x32_bf16 v[78:81], v[138:141], v[208:211], v[78:81]
	v_mfma_f32_16x16x32_bf16 v[74:77], v[146:149], v[208:211], v[74:77]
	s_setprio 0
	s_setprio 1
	v_mfma_f32_16x16x32_bf16 v[118:121], v[150:153], v[180:183], v[118:121]
	v_mfma_f32_16x16x32_bf16 v[114:117], v[172:175], v[180:183], v[114:117]
	v_mfma_f32_16x16x32_bf16 v[102:105], v[150:153], v[188:191], v[102:105]
	v_mfma_f32_16x16x32_bf16 v[98:101], v[172:175], v[188:191], v[98:101]
	v_mfma_f32_16x16x32_bf16 v[86:89], v[150:153], v[196:199], v[86:89]
	v_mfma_f32_16x16x32_bf16 v[82:85], v[172:175], v[196:199], v[82:85]
	v_mfma_f32_16x16x32_bf16 v[70:73], v[150:153], v[204:207], v[70:73]
	v_mfma_f32_16x16x32_bf16 v[66:69], v[172:175], v[204:207], v[66:69]
	v_mfma_f32_16x16x32_bf16 v[118:121], v[168:171], v[184:187], v[118:121]
	v_mfma_f32_16x16x32_bf16 v[114:117], v[176:179], v[184:187], v[114:117]
	v_mfma_f32_16x16x32_bf16 v[102:105], v[168:171], v[192:195], v[102:105]
	v_mfma_f32_16x16x32_bf16 v[98:101], v[176:179], v[192:195], v[98:101]
	v_mfma_f32_16x16x32_bf16 v[86:89], v[168:171], v[200:203], v[86:89]
	v_mfma_f32_16x16x32_bf16 v[82:85], v[176:179], v[200:203], v[82:85]
	s_setprio 2
	s_barrier
	v_mfma_f32_16x16x32_bf16 v[70:73], v[168:171], v[208:211], v[70:73]
	v_mfma_f32_16x16x32_bf16 v[66:69], v[176:179], v[208:211], v[66:69]
	s_setprio 0
	s_add_u32 s28, s10, 0x80
	s_addc_u32 s29, s11, 0
	s_mov_b32 s75, m0
	s_mov_b32 m0, s64
	s_nop 0
	global_load_lds_dwordx4 v156, s[28:29]
	s_mov_b32 m0, s75
	s_add_u32 s10, s10, 0x80080
	s_mov_b32 s75, m0
	s_mov_b32 m0, s65
	s_nop 0
	global_load_lds_dwordx4 v158, s[28:29]
	s_mov_b32 m0, s75
	s_addc_u32 s11, s11, 0
	s_mov_b32 s28, m0
	s_mov_b32 m0, s66
	s_nop 0
	global_load_lds_dwordx4 v156, s[10:11]
	s_mov_b32 m0, s28
	s_nop 0
	s_mov_b32 s28, m0
	s_mov_b32 m0, s67
	s_nop 0
	global_load_lds_dwordx4 v158, s[10:11]
	s_mov_b32 m0, s28
	ds_read_b128 v[180:183], v163 offset:49152
	ds_read_b128 v[184:187], v163 offset:50176
	ds_read_b128 v[188:191], v163 offset:51200
	ds_read_b128 v[192:195], v163 offset:52224
	ds_read_b128 v[196:199], v163 offset:53248
	ds_read_b128 v[200:203], v163 offset:54272
	ds_read_b128 v[204:207], v163 offset:55296
	ds_read_b128 v[208:211], v163 offset:56320
	s_waitcnt vmcnt(4)
	s_waitcnt lgkmcnt(0)
	s_barrier
	s_setprio 1
	s_waitcnt lgkmcnt(7)
	v_mfma_f32_16x16x32_bf16 v[62:65], v[130:133], v[180:183], v[62:65]
	v_mfma_f32_16x16x32_bf16 v[58:61], v[142:145], v[180:183], v[58:61]
	s_waitcnt lgkmcnt(5)
	v_mfma_f32_16x16x32_bf16 v[46:49], v[130:133], v[188:191], v[46:49]
	v_mfma_f32_16x16x32_bf16 v[42:45], v[142:145], v[188:191], v[42:45]
	s_waitcnt lgkmcnt(3)
	v_mfma_f32_16x16x32_bf16 v[30:33], v[130:133], v[196:199], v[30:33]
	v_mfma_f32_16x16x32_bf16 v[26:29], v[142:145], v[196:199], v[26:29]
	s_waitcnt lgkmcnt(1)
	v_mfma_f32_16x16x32_bf16 v[14:17], v[130:133], v[204:207], v[14:17]
	v_mfma_f32_16x16x32_bf16 v[10:13], v[142:145], v[204:207], v[10:13]
	v_mfma_f32_16x16x32_bf16 v[62:65], v[138:141], v[184:187], v[62:65]
	v_mfma_f32_16x16x32_bf16 v[58:61], v[146:149], v[184:187], v[58:61]
	v_mfma_f32_16x16x32_bf16 v[46:49], v[138:141], v[192:195], v[46:49]
	v_mfma_f32_16x16x32_bf16 v[42:45], v[146:149], v[192:195], v[42:45]
	v_mfma_f32_16x16x32_bf16 v[30:33], v[138:141], v[200:203], v[30:33]
	v_mfma_f32_16x16x32_bf16 v[26:29], v[146:149], v[200:203], v[26:29]
	s_waitcnt lgkmcnt(0)
	v_mfma_f32_16x16x32_bf16 v[14:17], v[138:141], v[208:211], v[14:17]
	v_mfma_f32_16x16x32_bf16 v[10:13], v[146:149], v[208:211], v[10:13]
	s_setprio 0
	s_setprio 1
	v_mfma_f32_16x16x32_bf16 v[54:57], v[150:153], v[180:183], v[54:57]
	v_mfma_f32_16x16x32_bf16 v[50:53], v[172:175], v[180:183], v[50:53]
	v_mfma_f32_16x16x32_bf16 v[38:41], v[150:153], v[188:191], v[38:41]
	v_mfma_f32_16x16x32_bf16 v[34:37], v[172:175], v[188:191], v[34:37]
	v_mfma_f32_16x16x32_bf16 v[22:25], v[150:153], v[196:199], v[22:25]
	v_mfma_f32_16x16x32_bf16 v[18:21], v[172:175], v[196:199], v[18:21]
	v_mfma_f32_16x16x32_bf16 v[6:9], v[150:153], v[204:207], v[6:9]
	v_mfma_f32_16x16x32_bf16 v[2:5], v[172:175], v[204:207], v[2:5]
	v_mfma_f32_16x16x32_bf16 v[54:57], v[168:171], v[184:187], v[54:57]
	v_mfma_f32_16x16x32_bf16 v[50:53], v[176:179], v[184:187], v[50:53]
	v_mfma_f32_16x16x32_bf16 v[38:41], v[168:171], v[192:195], v[38:41]
	v_mfma_f32_16x16x32_bf16 v[34:37], v[176:179], v[192:195], v[34:37]
	v_mfma_f32_16x16x32_bf16 v[22:25], v[168:171], v[200:203], v[22:25]
	v_mfma_f32_16x16x32_bf16 v[18:21], v[176:179], v[200:203], v[18:21]
	s_setprio 2
	s_barrier
	v_mfma_f32_16x16x32_bf16 v[6:9], v[168:171], v[208:211], v[6:9]
	v_mfma_f32_16x16x32_bf16 v[2:5], v[176:179], v[208:211], v[2:5]
	s_setprio 0
	s_add_i32 s74, s74, 2
	s_add_u32 s30, s30, 0x100
	s_addc_u32 s31, s31, 0
	s_add_u32 s4, s4, 0x100
	s_addc_u32 s5, s5, 0
	s_add_u32 s33, s33, 0x100
	s_addc_u32 s73, s73, 0
	s_cmp_gt_u32 s74, 29
	s_cbranch_scc0 .LBB0_654
	s_and_b64 vcc, exec, s[18:19]
	s_cbranch_vccz .LBB0_657
	s_barrier

.LBB0_1053:
	s_cmp_eq_u32 s78, 28
	s_cselect_b32 s23, s11, s75
	s_cselect_b32 s22, s73, s74
	s_cselect_b32 s25, s13, s77
	s_cselect_b32 s24, s67, s76
	s_add_u32 s80, s20, 0xfff80000
	s_addc_u32 s81, s21, -1
	s_mov_b32 s79, m0
	s_mov_b32 m0, s58
	s_nop 0
	global_load_lds_dwordx4 v1, s[80:81]
	s_mov_b32 m0, s79
	s_nop 0
	s_mov_b32 s79, m0
	s_mov_b32 m0, s64
	s_nop 0
	global_load_lds_dwordx4 v177, s[80:81]
	s_mov_b32 m0, s79
	s_nop 0
	s_mov_b32 s79, m0
	s_mov_b32 m0, s59
	s_nop 0
	global_load_lds_dwordx4 v1, s[20:21]
	s_mov_b32 m0, s79
	s_nop 0
	s_mov_b32 s79, m0
	s_mov_b32 m0, s65
	s_nop 0
	global_load_lds_dwordx4 v177, s[20:21]
	s_mov_b32 m0, s79
	ds_read_b128 v[130:133], v181
	ds_read_b128 v[134:137], v181 offset:1024
	ds_read_b128 v[138:141], v181 offset:2048
	ds_read_b128 v[142:145], v181 offset:3072
	ds_read_b128 v[146:149], v182
	ds_read_b128 v[150:153], v182 offset:1024
	ds_read_b128 v[154:157], v182 offset:2048
	ds_read_b128 v[158:161], v182 offset:3072
	ds_read_b128 v[166:169], v183
	ds_read_b128 v[170:173], v183 offset:1024
	ds_read_b128 v[186:189], v183 offset:2048
	ds_read_b128 v[190:193], v183 offset:3072
	ds_read_b128 v[194:197], v183 offset:4096
	ds_read_b128 v[198:201], v183 offset:5120
	ds_read_b128 v[202:205], v183 offset:6144
	ds_read_b128 v[206:209], v183 offset:7168
	s_waitcnt vmcnt(8)
	s_waitcnt lgkmcnt(0)
	s_barrier
	s_setprio 1
	s_waitcnt lgkmcnt(7)
	v_mfma_f32_16x16x32_bf16 v[126:129], v[130:133], v[166:169], v[126:129]
	v_mfma_f32_16x16x32_bf16 v[122:125], v[138:141], v[166:169], v[122:125]
	s_waitcnt lgkmcnt(5)
	v_mfma_f32_16x16x32_bf16 v[118:121], v[130:133], v[186:189], v[118:121]
	v_mfma_f32_16x16x32_bf16 v[114:117], v[138:141], v[186:189], v[114:117]
	s_waitcnt lgkmcnt(3)
	v_mfma_f32_16x16x32_bf16 v[94:97], v[130:133], v[194:197], v[94:97]
	v_mfma_f32_16x16x32_bf16 v[90:93], v[138:141], v[194:197], v[90:93]
	s_waitcnt lgkmcnt(1)
	v_mfma_f32_16x16x32_bf16 v[86:89], v[130:133], v[202:205], v[86:89]
	v_mfma_f32_16x16x32_bf16 v[78:81], v[138:141], v[202:205], v[78:81]
	v_mfma_f32_16x16x32_bf16 v[126:129], v[134:137], v[170:173], v[126:129]
	v_mfma_f32_16x16x32_bf16 v[122:125], v[142:145], v[170:173], v[122:125]
	v_mfma_f32_16x16x32_bf16 v[118:121], v[134:137], v[190:193], v[118:121]
	v_mfma_f32_16x16x32_bf16 v[114:117], v[142:145], v[190:193], v[114:117]
	v_mfma_f32_16x16x32_bf16 v[94:97], v[134:137], v[198:201], v[94:97]
	v_mfma_f32_16x16x32_bf16 v[90:93], v[142:145], v[198:201], v[90:93]
	s_waitcnt lgkmcnt(0)
	v_mfma_f32_16x16x32_bf16 v[86:89], v[134:137], v[206:209], v[86:89]
	v_mfma_f32_16x16x32_bf16 v[78:81], v[142:145], v[206:209], v[78:81]
	s_setprio 0
	s_setprio 1
	v_mfma_f32_16x16x32_bf16 v[110:113], v[146:149], v[166:169], v[110:113]
	v_mfma_f32_16x16x32_bf16 v[106:109], v[154:157], v[166:169], v[106:109]
	v_mfma_f32_16x16x32_bf16 v[102:105], v[146:149], v[186:189], v[102:105]
	v_mfma_f32_16x16x32_bf16 v[98:101], v[154:157], v[186:189], v[98:101]
	v_mfma_f32_16x16x32_bf16 v[82:85], v[146:149], v[194:197], v[82:85]
	v_mfma_f32_16x16x32_bf16 v[74:77], v[154:157], v[194:197], v[74:77]
	v_mfma_f32_16x16x32_bf16 v[70:73], v[146:149], v[202:205], v[70:73]
	v_mfma_f32_16x16x32_bf16 v[66:69], v[154:157], v[202:205], v[66:69]
	v_mfma_f32_16x16x32_bf16 v[110:113], v[150:153], v[170:173], v[110:113]
	v_mfma_f32_16x16x32_bf16 v[106:109], v[158:161], v[170:173], v[106:109]
	v_mfma_f32_16x16x32_bf16 v[102:105], v[150:153], v[190:193], v[102:105]
	v_mfma_f32_16x16x32_bf16 v[98:101], v[158:161], v[190:193], v[98:101]
	v_mfma_f32_16x16x32_bf16 v[82:85], v[150:153], v[198:201], v[82:85]
	v_mfma_f32_16x16x32_bf16 v[74:77], v[158:161], v[198:201], v[74:77]
	s_setprio 2
	s_barrier
	v_mfma_f32_16x16x32_bf16 v[70:73], v[150:153], v[206:209], v[70:73]
	v_mfma_f32_16x16x32_bf16 v[66:69], v[158:161], v[206:209], v[66:69]
	s_setprio 0
	s_mov_b32 s79, m0
	s_mov_b32 m0, s35
	s_nop 0
	global_load_lds_dwordx4 v176, s[22:23]
	s_mov_b32 m0, s79
	s_add_u32 s80, s22, 0x80000
	s_mov_b32 s79, m0
	s_mov_b32 m0, s36
	s_nop 0
	global_load_lds_dwordx4 v178, s[22:23]
	s_mov_b32 m0, s79
	s_addc_u32 s81, s23, 0
	s_mov_b32 s79, m0
	s_mov_b32 m0, s37
	s_nop 0
	global_load_lds_dwordx4 v176, s[80:81]
	s_mov_b32 m0, s79
	s_nop 0
	s_mov_b32 s79, m0
	s_mov_b32 m0, s40
	s_nop 0
	global_load_lds_dwordx4 v178, s[80:81]
	s_mov_b32 m0, s79
	ds_read_b128 v[166:169], v183 offset:16384
	ds_read_b128 v[170:173], v183 offset:17408
	ds_read_b128 v[186:189], v183 offset:18432
	ds_read_b128 v[190:193], v183 offset:19456
	ds_read_b128 v[194:197], v183 offset:20480
	ds_read_b128 v[198:201], v183 offset:21504
	ds_read_b128 v[202:205], v183 offset:22528
	ds_read_b128 v[206:209], v183 offset:23552
	s_waitcnt vmcnt(4)
	s_waitcnt lgkmcnt(0)
	s_barrier
	s_setprio 1
	s_waitcnt lgkmcnt(7)
	v_mfma_f32_16x16x32_bf16 v[62:65], v[130:133], v[166:169], v[62:65]
	v_mfma_f32_16x16x32_bf16 v[58:61], v[138:141], v[166:169], v[58:61]
	s_waitcnt lgkmcnt(5)
	v_mfma_f32_16x16x32_bf16 v[46:49], v[130:133], v[186:189], v[46:49]
	v_mfma_f32_16x16x32_bf16 v[42:45], v[138:141], v[186:189], v[42:45]
	s_waitcnt lgkmcnt(3)
	v_mfma_f32_16x16x32_bf16 v[30:33], v[130:133], v[194:197], v[30:33]
	v_mfma_f32_16x16x32_bf16 v[26:29], v[138:141], v[194:197], v[26:29]
	s_waitcnt lgkmcnt(1)
	v_mfma_f32_16x16x32_bf16 v[14:17], v[130:133], v[202:205], v[14:17]
	v_mfma_f32_16x16x32_bf16 v[10:13], v[138:141], v[202:205], v[10:13]
	v_mfma_f32_16x16x32_bf16 v[62:65], v[134:137], v[170:173], v[62:65]
	v_mfma_f32_16x16x32_bf16 v[58:61], v[142:145], v[170:173], v[58:61]
	v_mfma_f32_16x16x32_bf16 v[46:49], v[134:137], v[190:193], v[46:49]
	v_mfma_f32_16x16x32_bf16 v[42:45], v[142:145], v[190:193], v[42:45]
	v_mfma_f32_16x16x32_bf16 v[30:33], v[134:137], v[198:201], v[30:33]
	v_mfma_f32_16x16x32_bf16 v[26:29], v[142:145], v[198:201], v[26:29]
	s_waitcnt lgkmcnt(0)
	v_mfma_f32_16x16x32_bf16 v[14:17], v[134:137], v[206:209], v[14:17]
	v_mfma_f32_16x16x32_bf16 v[10:13], v[142:145], v[206:209], v[10:13]
	s_setprio 0
	s_setprio 1
	v_mfma_f32_16x16x32_bf16 v[54:57], v[146:149], v[166:169], v[54:57]
	v_mfma_f32_16x16x32_bf16 v[50:53], v[154:157], v[166:169], v[50:53]
	v_mfma_f32_16x16x32_bf16 v[38:41], v[146:149], v[186:189], v[38:41]
	v_mfma_f32_16x16x32_bf16 v[34:37], v[154:157], v[186:189], v[34:37]
	v_mfma_f32_16x16x32_bf16 v[22:25], v[146:149], v[194:197], v[22:25]
	v_mfma_f32_16x16x32_bf16 v[18:21], v[154:157], v[194:197], v[18:21]
	v_mfma_f32_16x16x32_bf16 v[6:9], v[146:149], v[202:205], v[6:9]
	v_mfma_f32_16x16x32_bf16 v[2:5], v[154:157], v[202:205], v[2:5]
	v_mfma_f32_16x16x32_bf16 v[54:57], v[150:153], v[170:173], v[54:57]
	v_mfma_f32_16x16x32_bf16 v[50:53], v[158:161], v[170:173], v[50:53]
	v_mfma_f32_16x16x32_bf16 v[38:41], v[150:153], v[190:193], v[38:41]
	v_mfma_f32_16x16x32_bf16 v[34:37], v[158:161], v[190:193], v[34:37]
	v_mfma_f32_16x16x32_bf16 v[22:25], v[150:153], v[198:201], v[22:25]
	v_mfma_f32_16x16x32_bf16 v[18:21], v[158:161], v[198:201], v[18:21]
	s_setprio 2
	s_barrier
	v_mfma_f32_16x16x32_bf16 v[6:9], v[150:153], v[206:209], v[6:9]
	v_mfma_f32_16x16x32_bf16 v[2:5], v[158:161], v[206:209], v[2:5]
	s_setprio 0
	s_mov_b32 s79, m0
	s_mov_b32 m0, s34
	s_nop 0
	global_load_lds_dwordx4 v1, s[24:25]
	s_mov_b32 m0, s79
	s_nop 0
	s_mov_b32 s79, m0
	s_mov_b32 m0, s41
	s_nop 0
	global_load_lds_dwordx4 v177, s[24:25]
	s_mov_b32 m0, s79
	s_add_u32 s24, s24, 0x80000
	s_addc_u32 s25, s25, 0
	s_mov_b32 s79, m0
	s_mov_b32 m0, s42
	s_nop 0
	global_load_lds_dwordx4 v1, s[24:25]
	s_mov_b32 m0, s79
	s_nop 0
	s_mov_b32 s79, m0
	s_mov_b32 m0, s43
	s_nop 0
	global_load_lds_dwordx4 v177, s[24:25]
	s_mov_b32 m0, s79
	ds_read_b128 v[130:133], v184
	ds_read_b128 v[134:137], v184 offset:1024
	ds_read_b128 v[138:141], v184 offset:2048
	ds_read_b128 v[142:145], v184 offset:3072
	ds_read_b128 v[146:149], v185
	ds_read_b128 v[150:153], v185 offset:1024
	ds_read_b128 v[154:157], v185 offset:2048
	ds_read_b128 v[158:161], v185 offset:3072
	ds_read_b128 v[166:169], v183 offset:32768
	ds_read_b128 v[170:173], v183 offset:33792
	ds_read_b128 v[186:189], v183 offset:34816
	ds_read_b128 v[190:193], v183 offset:35840
	ds_read_b128 v[194:197], v183 offset:36864
	ds_read_b128 v[198:201], v183 offset:37888
	ds_read_b128 v[202:205], v183 offset:38912
	ds_read_b128 v[206:209], v183 offset:39936
	s_waitcnt vmcnt(8)
	s_waitcnt lgkmcnt(0)
	s_barrier
	s_setprio 1
	s_waitcnt lgkmcnt(7)
	v_mfma_f32_16x16x32_bf16 v[126:129], v[130:133], v[166:169], v[126:129]
	v_mfma_f32_16x16x32_bf16 v[122:125], v[138:141], v[166:169], v[122:125]
	s_waitcnt lgkmcnt(5)
	v_mfma_f32_16x16x32_bf16 v[118:121], v[130:133], v[186:189], v[118:121]
	v_mfma_f32_16x16x32_bf16 v[114:117], v[138:141], v[186:189], v[114:117]
	s_waitcnt lgkmcnt(3)
	v_mfma_f32_16x16x32_bf16 v[94:97], v[130:133], v[194:197], v[94:97]
	v_mfma_f32_16x16x32_bf16 v[90:93], v[138:141], v[194:197], v[90:93]
	s_waitcnt lgkmcnt(1)
	v_mfma_f32_16x16x32_bf16 v[86:89], v[130:133], v[202:205], v[86:89]
	v_mfma_f32_16x16x32_bf16 v[78:81], v[138:141], v[202:205], v[78:81]
	v_mfma_f32_16x16x32_bf16 v[126:129], v[134:137], v[170:173], v[126:129]
	v_mfma_f32_16x16x32_bf16 v[122:125], v[142:145], v[170:173], v[122:125]
	v_mfma_f32_16x16x32_bf16 v[118:121], v[134:137], v[190:193], v[118:121]
	v_mfma_f32_16x16x32_bf16 v[114:117], v[142:145], v[190:193], v[114:117]
	v_mfma_f32_16x16x32_bf16 v[94:97], v[134:137], v[198:201], v[94:97]
	v_mfma_f32_16x16x32_bf16 v[90:93], v[142:145], v[198:201], v[90:93]
	s_waitcnt lgkmcnt(0)
	v_mfma_f32_16x16x32_bf16 v[86:89], v[134:137], v[206:209], v[86:89]
	v_mfma_f32_16x16x32_bf16 v[78:81], v[142:145], v[206:209], v[78:81]
	s_setprio 0
	s_setprio 1
	v_mfma_f32_16x16x32_bf16 v[110:113], v[146:149], v[166:169], v[110:113]
	v_mfma_f32_16x16x32_bf16 v[106:109], v[154:157], v[166:169], v[106:109]
	v_mfma_f32_16x16x32_bf16 v[102:105], v[146:149], v[186:189], v[102:105]
	v_mfma_f32_16x16x32_bf16 v[98:101], v[154:157], v[186:189], v[98:101]
	v_mfma_f32_16x16x32_bf16 v[82:85], v[146:149], v[194:197], v[82:85]
	v_mfma_f32_16x16x32_bf16 v[74:77], v[154:157], v[194:197], v[74:77]
	v_mfma_f32_16x16x32_bf16 v[70:73], v[146:149], v[202:205], v[70:73]
	v_mfma_f32_16x16x32_bf16 v[66:69], v[154:157], v[202:205], v[66:69]
	v_mfma_f32_16x16x32_bf16 v[110:113], v[150:153], v[170:173], v[110:113]
	v_mfma_f32_16x16x32_bf16 v[106:109], v[158:161], v[170:173], v[106:109]
	v_mfma_f32_16x16x32_bf16 v[102:105], v[150:153], v[190:193], v[102:105]
	v_mfma_f32_16x16x32_bf16 v[98:101], v[158:161], v[190:193], v[98:101]
	v_mfma_f32_16x16x32_bf16 v[82:85], v[150:153], v[198:201], v[82:85]
	v_mfma_f32_16x16x32_bf16 v[74:77], v[158:161], v[198:201], v[74:77]
	s_setprio 2
	s_barrier
	v_mfma_f32_16x16x32_bf16 v[70:73], v[150:153], v[206:209], v[70:73]
	v_mfma_f32_16x16x32_bf16 v[66:69], v[158:161], v[206:209], v[66:69]
	s_setprio 0
	s_add_u32 s24, s22, 0x80
	s_addc_u32 s25, s23, 0
	s_mov_b32 s79, m0
	s_mov_b32 m0, s46
	s_nop 0
	global_load_lds_dwordx4 v176, s[24:25]
	s_mov_b32 m0, s79
	s_add_u32 s22, s22, 0x80080
	s_mov_b32 s79, m0
	s_mov_b32 m0, s47
	s_nop 0
	global_load_lds_dwordx4 v178, s[24:25]
	s_mov_b32 m0, s79
	s_addc_u32 s23, s23, 0
	s_mov_b32 s24, m0
	s_mov_b32 m0, s48
	s_nop 0
	global_load_lds_dwordx4 v176, s[22:23]
	s_mov_b32 m0, s24
	s_nop 0
	s_mov_b32 s24, m0
	s_mov_b32 m0, s49
	s_nop 0
	global_load_lds_dwordx4 v178, s[22:23]
	s_mov_b32 m0, s24
	ds_read_b128 v[166:169], v183 offset:49152
	ds_read_b128 v[170:173], v183 offset:50176
	ds_read_b128 v[186:189], v183 offset:51200
	ds_read_b128 v[190:193], v183 offset:52224
	ds_read_b128 v[194:197], v183 offset:53248
	ds_read_b128 v[198:201], v183 offset:54272
	ds_read_b128 v[202:205], v183 offset:55296
	ds_read_b128 v[206:209], v183 offset:56320
	s_waitcnt vmcnt(4)
	s_waitcnt lgkmcnt(0)
	s_barrier
	s_setprio 1
	s_waitcnt lgkmcnt(7)
	v_mfma_f32_16x16x32_bf16 v[62:65], v[130:133], v[166:169], v[62:65]
	v_mfma_f32_16x16x32_bf16 v[58:61], v[138:141], v[166:169], v[58:61]
	s_waitcnt lgkmcnt(5)
	v_mfma_f32_16x16x32_bf16 v[46:49], v[130:133], v[186:189], v[46:49]
	v_mfma_f32_16x16x32_bf16 v[42:45], v[138:141], v[186:189], v[42:45]
	s_waitcnt lgkmcnt(3)
	v_mfma_f32_16x16x32_bf16 v[30:33], v[130:133], v[194:197], v[30:33]
	v_mfma_f32_16x16x32_bf16 v[26:29], v[138:141], v[194:197], v[26:29]
	s_waitcnt lgkmcnt(1)
	v_mfma_f32_16x16x32_bf16 v[14:17], v[130:133], v[202:205], v[14:17]
	v_mfma_f32_16x16x32_bf16 v[10:13], v[138:141], v[202:205], v[10:13]
	v_mfma_f32_16x16x32_bf16 v[62:65], v[134:137], v[170:173], v[62:65]
	v_mfma_f32_16x16x32_bf16 v[58:61], v[142:145], v[170:173], v[58:61]
	v_mfma_f32_16x16x32_bf16 v[46:49], v[134:137], v[190:193], v[46:49]
	v_mfma_f32_16x16x32_bf16 v[42:45], v[142:145], v[190:193], v[42:45]
	v_mfma_f32_16x16x32_bf16 v[30:33], v[134:137], v[198:201], v[30:33]
	v_mfma_f32_16x16x32_bf16 v[26:29], v[142:145], v[198:201], v[26:29]
	s_waitcnt lgkmcnt(0)
	v_mfma_f32_16x16x32_bf16 v[14:17], v[134:137], v[206:209], v[14:17]
	v_mfma_f32_16x16x32_bf16 v[10:13], v[142:145], v[206:209], v[10:13]
	s_setprio 0
	s_setprio 1
	v_mfma_f32_16x16x32_bf16 v[54:57], v[146:149], v[166:169], v[54:57]
	v_mfma_f32_16x16x32_bf16 v[50:53], v[154:157], v[166:169], v[50:53]
	v_mfma_f32_16x16x32_bf16 v[38:41], v[146:149], v[186:189], v[38:41]
	v_mfma_f32_16x16x32_bf16 v[34:37], v[154:157], v[186:189], v[34:37]
	v_mfma_f32_16x16x32_bf16 v[22:25], v[146:149], v[194:197], v[22:25]
	v_mfma_f32_16x16x32_bf16 v[18:21], v[154:157], v[194:197], v[18:21]
	v_mfma_f32_16x16x32_bf16 v[6:9], v[146:149], v[202:205], v[6:9]
	v_mfma_f32_16x16x32_bf16 v[2:5], v[154:157], v[202:205], v[2:5]
	v_mfma_f32_16x16x32_bf16 v[54:57], v[150:153], v[170:173], v[54:57]
	v_mfma_f32_16x16x32_bf16 v[50:53], v[158:161], v[170:173], v[50:53]
	v_mfma_f32_16x16x32_bf16 v[38:41], v[150:153], v[190:193], v[38:41]
	v_mfma_f32_16x16x32_bf16 v[34:37], v[158:161], v[190:193], v[34:37]
	v_mfma_f32_16x16x32_bf16 v[22:25], v[150:153], v[198:201], v[22:25]
	v_mfma_f32_16x16x32_bf16 v[18:21], v[158:161], v[198:201], v[18:21]
	s_setprio 2
	s_barrier
	v_mfma_f32_16x16x32_bf16 v[6:9], v[150:153], v[206:209], v[6:9]
	v_mfma_f32_16x16x32_bf16 v[2:5], v[158:161], v[206:209], v[2:5]
	s_setprio 0
	s_add_i32 s78, s78, 2
	s_add_u32 s74, s74, 0x100
	s_addc_u32 s75, s75, 0
	s_add_u32 s20, s20, 0x100
	s_addc_u32 s21, s21, 0
	s_add_u32 s76, s76, 0x100
	s_addc_u32 s77, s77, 0
	s_cmp_gt_u32 s78, 29
	s_cbranch_scc0 .LBB0_1053
	s_and_b64 vcc, exec, s[8:9]
	s_cbranch_vccz .LBB0_1056
	s_barrier

.LBB0_1224:
	s_cmp_eq_u32 s77, 28
	s_cselect_b32 s21, s9, s74
	s_cselect_b32 s20, s67, s73
	s_cselect_b32 s23, s11, s76
	s_cselect_b32 s22, s66, s75
	s_add_u32 s78, s18, 0xfff80000
	s_addc_u32 s79, s19, -1
	s_mov_b32 s80, m0
	s_mov_b32 m0, s56
	s_nop 0
	global_load_lds_dwordx4 v138, s[78:79]
	s_mov_b32 m0, s80
	s_nop 0
	s_mov_b32 s80, m0
	s_mov_b32 m0, s59
	s_nop 0
	global_load_lds_dwordx4 v140, s[78:79]
	s_mov_b32 m0, s80
	s_mov_b32 s78, m0
	s_mov_b32 m0, s57
	s_nop 0
	global_load_lds_dwordx4 v138, s[18:19]
	s_mov_b32 m0, s78
	s_nop 0
	s_mov_b32 s78, m0
	s_mov_b32 m0, s64
	s_nop 0
	global_load_lds_dwordx4 v140, s[18:19]
	s_mov_b32 m0, s78
	ds_read_b128 v[148:151], v143
	ds_read_b128 v[152:155], v143 offset:1024
	ds_read_b128 v[156:159], v143 offset:2048
	ds_read_b128 v[160:163], v143 offset:3072
	ds_read_b128 v[164:167], v144
	ds_read_b128 v[168:171], v144 offset:1024
	ds_read_b128 v[172:175], v144 offset:2048
	ds_read_b128 v[176:179], v144 offset:3072
	ds_read_b128 v[180:183], v145
	ds_read_b128 v[184:187], v145 offset:1024
	ds_read_b128 v[188:191], v145 offset:2048
	ds_read_b128 v[192:195], v145 offset:3072
	ds_read_b128 v[196:199], v145 offset:4096
	ds_read_b128 v[200:203], v145 offset:5120
	ds_read_b128 v[204:207], v145 offset:6144
	ds_read_b128 v[208:211], v145 offset:7168
	s_waitcnt vmcnt(8)
	s_waitcnt lgkmcnt(0)
	s_barrier
	s_setprio 1
	s_waitcnt lgkmcnt(7)
	v_mfma_f32_16x16x32_bf16 v[126:129], v[148:151], v[180:183], v[126:129]
	v_mfma_f32_16x16x32_bf16 v[122:125], v[156:159], v[180:183], v[122:125]
	s_waitcnt lgkmcnt(5)
	v_mfma_f32_16x16x32_bf16 v[110:113], v[148:151], v[188:191], v[110:113]
	v_mfma_f32_16x16x32_bf16 v[106:109], v[156:159], v[188:191], v[106:109]
	s_waitcnt lgkmcnt(3)
	v_mfma_f32_16x16x32_bf16 v[94:97], v[148:151], v[196:199], v[94:97]
	v_mfma_f32_16x16x32_bf16 v[90:93], v[156:159], v[196:199], v[90:93]
	s_waitcnt lgkmcnt(1)
	v_mfma_f32_16x16x32_bf16 v[78:81], v[148:151], v[204:207], v[78:81]
	v_mfma_f32_16x16x32_bf16 v[74:77], v[156:159], v[204:207], v[74:77]
	v_mfma_f32_16x16x32_bf16 v[126:129], v[152:155], v[184:187], v[126:129]
	v_mfma_f32_16x16x32_bf16 v[122:125], v[160:163], v[184:187], v[122:125]
	v_mfma_f32_16x16x32_bf16 v[110:113], v[152:155], v[192:195], v[110:113]
	v_mfma_f32_16x16x32_bf16 v[106:109], v[160:163], v[192:195], v[106:109]
	v_mfma_f32_16x16x32_bf16 v[94:97], v[152:155], v[200:203], v[94:97]
	v_mfma_f32_16x16x32_bf16 v[90:93], v[160:163], v[200:203], v[90:93]
	s_waitcnt lgkmcnt(0)
	v_mfma_f32_16x16x32_bf16 v[78:81], v[152:155], v[208:211], v[78:81]
	v_mfma_f32_16x16x32_bf16 v[74:77], v[160:163], v[208:211], v[74:77]
	s_setprio 0
	s_setprio 1
	v_mfma_f32_16x16x32_bf16 v[118:121], v[164:167], v[180:183], v[118:121]
	v_mfma_f32_16x16x32_bf16 v[114:117], v[172:175], v[180:183], v[114:117]
	v_mfma_f32_16x16x32_bf16 v[102:105], v[164:167], v[188:191], v[102:105]
	v_mfma_f32_16x16x32_bf16 v[98:101], v[172:175], v[188:191], v[98:101]
	v_mfma_f32_16x16x32_bf16 v[86:89], v[164:167], v[196:199], v[86:89]
	v_mfma_f32_16x16x32_bf16 v[82:85], v[172:175], v[196:199], v[82:85]
	v_mfma_f32_16x16x32_bf16 v[70:73], v[164:167], v[204:207], v[70:73]
	v_mfma_f32_16x16x32_bf16 v[66:69], v[172:175], v[204:207], v[66:69]
	v_mfma_f32_16x16x32_bf16 v[118:121], v[168:171], v[184:187], v[118:121]
	v_mfma_f32_16x16x32_bf16 v[114:117], v[176:179], v[184:187], v[114:117]
	v_mfma_f32_16x16x32_bf16 v[102:105], v[168:171], v[192:195], v[102:105]
	v_mfma_f32_16x16x32_bf16 v[98:101], v[176:179], v[192:195], v[98:101]
	v_mfma_f32_16x16x32_bf16 v[86:89], v[168:171], v[200:203], v[86:89]
	v_mfma_f32_16x16x32_bf16 v[82:85], v[176:179], v[200:203], v[82:85]
	s_setprio 2
	s_barrier
	v_mfma_f32_16x16x32_bf16 v[70:73], v[168:171], v[208:211], v[70:73]
	v_mfma_f32_16x16x32_bf16 v[66:69], v[176:179], v[208:211], v[66:69]
	s_setprio 0
	s_mov_b32 s78, m0
	s_mov_b32 m0, s35
	s_nop 0
	global_load_lds_dwordx4 v139, s[20:21]
	s_mov_b32 m0, s78
	s_nop 0
	s_mov_b32 s78, m0
	s_mov_b32 m0, s36
	s_nop 0
	global_load_lds_dwordx4 v141, s[20:21]
	s_mov_b32 m0, s78
	s_add_u32 s78, s20, 0x80000
	s_addc_u32 s79, s21, 0
	s_mov_b32 s80, m0
	s_mov_b32 m0, s37
	s_nop 0
	global_load_lds_dwordx4 v139, s[78:79]
	s_mov_b32 m0, s80
	s_nop 0
	s_mov_b32 s80, m0
	s_mov_b32 m0, s40
	s_nop 0
	global_load_lds_dwordx4 v141, s[78:79]
	s_mov_b32 m0, s80
	ds_read_b128 v[180:183], v145 offset:16384
	ds_read_b128 v[184:187], v145 offset:17408
	ds_read_b128 v[188:191], v145 offset:18432
	ds_read_b128 v[192:195], v145 offset:19456
	ds_read_b128 v[196:199], v145 offset:20480
	ds_read_b128 v[200:203], v145 offset:21504
	ds_read_b128 v[204:207], v145 offset:22528
	ds_read_b128 v[208:211], v145 offset:23552
	s_waitcnt vmcnt(4)
	s_waitcnt lgkmcnt(0)
	s_barrier
	s_setprio 1
	s_waitcnt lgkmcnt(7)
	v_mfma_f32_16x16x32_bf16 v[62:65], v[148:151], v[180:183], v[62:65]
	v_mfma_f32_16x16x32_bf16 v[58:61], v[156:159], v[180:183], v[58:61]
	s_waitcnt lgkmcnt(5)
	v_mfma_f32_16x16x32_bf16 v[46:49], v[148:151], v[188:191], v[46:49]
	v_mfma_f32_16x16x32_bf16 v[42:45], v[156:159], v[188:191], v[42:45]
	s_waitcnt lgkmcnt(3)
	v_mfma_f32_16x16x32_bf16 v[30:33], v[148:151], v[196:199], v[30:33]
	v_mfma_f32_16x16x32_bf16 v[26:29], v[156:159], v[196:199], v[26:29]
	s_waitcnt lgkmcnt(1)
	v_mfma_f32_16x16x32_bf16 v[14:17], v[148:151], v[204:207], v[14:17]
	v_mfma_f32_16x16x32_bf16 v[10:13], v[156:159], v[204:207], v[10:13]
	v_mfma_f32_16x16x32_bf16 v[62:65], v[152:155], v[184:187], v[62:65]
	v_mfma_f32_16x16x32_bf16 v[58:61], v[160:163], v[184:187], v[58:61]
	v_mfma_f32_16x16x32_bf16 v[46:49], v[152:155], v[192:195], v[46:49]
	v_mfma_f32_16x16x32_bf16 v[42:45], v[160:163], v[192:195], v[42:45]
	v_mfma_f32_16x16x32_bf16 v[30:33], v[152:155], v[200:203], v[30:33]
	v_mfma_f32_16x16x32_bf16 v[26:29], v[160:163], v[200:203], v[26:29]
	s_waitcnt lgkmcnt(0)
	v_mfma_f32_16x16x32_bf16 v[14:17], v[152:155], v[208:211], v[14:17]
	v_mfma_f32_16x16x32_bf16 v[10:13], v[160:163], v[208:211], v[10:13]
	s_setprio 0
	s_setprio 1
	v_mfma_f32_16x16x32_bf16 v[54:57], v[164:167], v[180:183], v[54:57]
	v_mfma_f32_16x16x32_bf16 v[50:53], v[172:175], v[180:183], v[50:53]
	v_mfma_f32_16x16x32_bf16 v[38:41], v[164:167], v[188:191], v[38:41]
	v_mfma_f32_16x16x32_bf16 v[34:37], v[172:175], v[188:191], v[34:37]
	v_mfma_f32_16x16x32_bf16 v[22:25], v[164:167], v[196:199], v[22:25]
	v_mfma_f32_16x16x32_bf16 v[18:21], v[172:175], v[196:199], v[18:21]
	v_mfma_f32_16x16x32_bf16 v[6:9], v[164:167], v[204:207], v[6:9]
	v_mfma_f32_16x16x32_bf16 v[2:5], v[172:175], v[204:207], v[2:5]
	v_mfma_f32_16x16x32_bf16 v[54:57], v[168:171], v[184:187], v[54:57]
	v_mfma_f32_16x16x32_bf16 v[50:53], v[176:179], v[184:187], v[50:53]
	v_mfma_f32_16x16x32_bf16 v[38:41], v[168:171], v[192:195], v[38:41]
	v_mfma_f32_16x16x32_bf16 v[34:37], v[176:179], v[192:195], v[34:37]
	v_mfma_f32_16x16x32_bf16 v[22:25], v[168:171], v[200:203], v[22:25]
	v_mfma_f32_16x16x32_bf16 v[18:21], v[176:179], v[200:203], v[18:21]
	s_setprio 2
	s_barrier
	v_mfma_f32_16x16x32_bf16 v[6:9], v[168:171], v[208:211], v[6:9]
	v_mfma_f32_16x16x32_bf16 v[2:5], v[176:179], v[208:211], v[2:5]
	s_setprio 0
	s_mov_b32 s78, m0
	s_mov_b32 m0, s31
	s_nop 0
	global_load_lds_dwordx4 v138, s[22:23]
	s_mov_b32 m0, s78
	s_nop 0
	s_mov_b32 s78, m0
	s_mov_b32 m0, s41
	s_nop 0
	global_load_lds_dwordx4 v140, s[22:23]
	s_mov_b32 m0, s78
	s_add_u32 s22, s22, 0x80000
	s_addc_u32 s23, s23, 0
	s_mov_b32 s78, m0
	s_mov_b32 m0, s42
	s_nop 0
	global_load_lds_dwordx4 v138, s[22:23]
	s_mov_b32 m0, s78
	s_nop 0
	s_mov_b32 s78, m0
	s_mov_b32 m0, s43
	s_nop 0
	global_load_lds_dwordx4 v140, s[22:23]
	s_mov_b32 m0, s78
	ds_read_b128 v[148:151], v146
	ds_read_b128 v[152:155], v146 offset:1024
	ds_read_b128 v[156:159], v146 offset:2048
	ds_read_b128 v[160:163], v146 offset:3072
	ds_read_b128 v[164:167], v147
	ds_read_b128 v[168:171], v147 offset:1024
	ds_read_b128 v[172:175], v147 offset:2048
	ds_read_b128 v[176:179], v147 offset:3072
	ds_read_b128 v[180:183], v145 offset:32768
	ds_read_b128 v[184:187], v145 offset:33792
	ds_read_b128 v[188:191], v145 offset:34816
	ds_read_b128 v[192:195], v145 offset:35840
	ds_read_b128 v[196:199], v145 offset:36864
	ds_read_b128 v[200:203], v145 offset:37888
	ds_read_b128 v[204:207], v145 offset:38912
	ds_read_b128 v[208:211], v145 offset:39936
	s_waitcnt vmcnt(8)
	s_waitcnt lgkmcnt(0)
	s_barrier
	s_setprio 1
	s_waitcnt lgkmcnt(7)
	v_mfma_f32_16x16x32_bf16 v[126:129], v[148:151], v[180:183], v[126:129]
	v_mfma_f32_16x16x32_bf16 v[122:125], v[156:159], v[180:183], v[122:125]
	s_waitcnt lgkmcnt(5)
	v_mfma_f32_16x16x32_bf16 v[110:113], v[148:151], v[188:191], v[110:113]
	v_mfma_f32_16x16x32_bf16 v[106:109], v[156:159], v[188:191], v[106:109]
	s_waitcnt lgkmcnt(3)
	v_mfma_f32_16x16x32_bf16 v[94:97], v[148:151], v[196:199], v[94:97]
	v_mfma_f32_16x16x32_bf16 v[90:93], v[156:159], v[196:199], v[90:93]
	s_waitcnt lgkmcnt(1)
	v_mfma_f32_16x16x32_bf16 v[78:81], v[148:151], v[204:207], v[78:81]
	v_mfma_f32_16x16x32_bf16 v[74:77], v[156:159], v[204:207], v[74:77]
	v_mfma_f32_16x16x32_bf16 v[126:129], v[152:155], v[184:187], v[126:129]
	v_mfma_f32_16x16x32_bf16 v[122:125], v[160:163], v[184:187], v[122:125]
	v_mfma_f32_16x16x32_bf16 v[110:113], v[152:155], v[192:195], v[110:113]
	v_mfma_f32_16x16x32_bf16 v[106:109], v[160:163], v[192:195], v[106:109]
	v_mfma_f32_16x16x32_bf16 v[94:97], v[152:155], v[200:203], v[94:97]
	v_mfma_f32_16x16x32_bf16 v[90:93], v[160:163], v[200:203], v[90:93]
	s_waitcnt lgkmcnt(0)
	v_mfma_f32_16x16x32_bf16 v[78:81], v[152:155], v[208:211], v[78:81]
	v_mfma_f32_16x16x32_bf16 v[74:77], v[160:163], v[208:211], v[74:77]
	s_setprio 0
	s_setprio 1
	v_mfma_f32_16x16x32_bf16 v[118:121], v[164:167], v[180:183], v[118:121]
	v_mfma_f32_16x16x32_bf16 v[114:117], v[172:175], v[180:183], v[114:117]
	v_mfma_f32_16x16x32_bf16 v[102:105], v[164:167], v[188:191], v[102:105]
	v_mfma_f32_16x16x32_bf16 v[98:101], v[172:175], v[188:191], v[98:101]
	v_mfma_f32_16x16x32_bf16 v[86:89], v[164:167], v[196:199], v[86:89]
	v_mfma_f32_16x16x32_bf16 v[82:85], v[172:175], v[196:199], v[82:85]
	v_mfma_f32_16x16x32_bf16 v[70:73], v[164:167], v[204:207], v[70:73]
	v_mfma_f32_16x16x32_bf16 v[66:69], v[172:175], v[204:207], v[66:69]
	v_mfma_f32_16x16x32_bf16 v[118:121], v[168:171], v[184:187], v[118:121]
	v_mfma_f32_16x16x32_bf16 v[114:117], v[176:179], v[184:187], v[114:117]
	v_mfma_f32_16x16x32_bf16 v[102:105], v[168:171], v[192:195], v[102:105]
	v_mfma_f32_16x16x32_bf16 v[98:101], v[176:179], v[192:195], v[98:101]
	v_mfma_f32_16x16x32_bf16 v[86:89], v[168:171], v[200:203], v[86:89]
	v_mfma_f32_16x16x32_bf16 v[82:85], v[176:179], v[200:203], v[82:85]
	s_setprio 2
	s_barrier
	v_mfma_f32_16x16x32_bf16 v[70:73], v[168:171], v[208:211], v[70:73]
	v_mfma_f32_16x16x32_bf16 v[66:69], v[176:179], v[208:211], v[66:69]
	s_setprio 0
	s_add_u32 s22, s20, 0x80
	s_addc_u32 s23, s21, 0
	s_mov_b32 s78, m0
	s_mov_b32 m0, s46
	s_nop 0
	global_load_lds_dwordx4 v139, s[22:23]
	s_mov_b32 m0, s78
	s_add_u32 s20, s20, 0x80080
	s_mov_b32 s78, m0
	s_mov_b32 m0, s47
	s_nop 0
	global_load_lds_dwordx4 v141, s[22:23]
	s_mov_b32 m0, s78
	s_addc_u32 s21, s21, 0
	s_mov_b32 s22, m0
	s_mov_b32 m0, s48
	s_nop 0
	global_load_lds_dwordx4 v139, s[20:21]
	s_mov_b32 m0, s22
	s_nop 0
	s_mov_b32 s22, m0
	s_mov_b32 m0, s49
	s_nop 0
	global_load_lds_dwordx4 v141, s[20:21]
	s_mov_b32 m0, s22
	ds_read_b128 v[180:183], v145 offset:49152
	ds_read_b128 v[184:187], v145 offset:50176
	ds_read_b128 v[188:191], v145 offset:51200
	ds_read_b128 v[192:195], v145 offset:52224
	ds_read_b128 v[196:199], v145 offset:53248
	ds_read_b128 v[200:203], v145 offset:54272
	ds_read_b128 v[204:207], v145 offset:55296
	ds_read_b128 v[208:211], v145 offset:56320
	s_waitcnt vmcnt(4)
	s_waitcnt lgkmcnt(0)
	s_barrier
	s_setprio 1
	s_waitcnt lgkmcnt(7)
	v_mfma_f32_16x16x32_bf16 v[62:65], v[148:151], v[180:183], v[62:65]
	v_mfma_f32_16x16x32_bf16 v[58:61], v[156:159], v[180:183], v[58:61]
	s_waitcnt lgkmcnt(5)
	v_mfma_f32_16x16x32_bf16 v[46:49], v[148:151], v[188:191], v[46:49]
	v_mfma_f32_16x16x32_bf16 v[42:45], v[156:159], v[188:191], v[42:45]
	s_waitcnt lgkmcnt(3)
	v_mfma_f32_16x16x32_bf16 v[30:33], v[148:151], v[196:199], v[30:33]
	v_mfma_f32_16x16x32_bf16 v[26:29], v[156:159], v[196:199], v[26:29]
	s_waitcnt lgkmcnt(1)
	v_mfma_f32_16x16x32_bf16 v[14:17], v[148:151], v[204:207], v[14:17]
	v_mfma_f32_16x16x32_bf16 v[10:13], v[156:159], v[204:207], v[10:13]
	v_mfma_f32_16x16x32_bf16 v[62:65], v[152:155], v[184:187], v[62:65]
	v_mfma_f32_16x16x32_bf16 v[58:61], v[160:163], v[184:187], v[58:61]
	v_mfma_f32_16x16x32_bf16 v[46:49], v[152:155], v[192:195], v[46:49]
	v_mfma_f32_16x16x32_bf16 v[42:45], v[160:163], v[192:195], v[42:45]
	v_mfma_f32_16x16x32_bf16 v[30:33], v[152:155], v[200:203], v[30:33]
	v_mfma_f32_16x16x32_bf16 v[26:29], v[160:163], v[200:203], v[26:29]
	s_waitcnt lgkmcnt(0)
	v_mfma_f32_16x16x32_bf16 v[14:17], v[152:155], v[208:211], v[14:17]
	v_mfma_f32_16x16x32_bf16 v[10:13], v[160:163], v[208:211], v[10:13]
	s_setprio 0
	s_setprio 1
	v_mfma_f32_16x16x32_bf16 v[54:57], v[164:167], v[180:183], v[54:57]
	v_mfma_f32_16x16x32_bf16 v[50:53], v[172:175], v[180:183], v[50:53]
	v_mfma_f32_16x16x32_bf16 v[38:41], v[164:167], v[188:191], v[38:41]
	v_mfma_f32_16x16x32_bf16 v[34:37], v[172:175], v[188:191], v[34:37]
	v_mfma_f32_16x16x32_bf16 v[22:25], v[164:167], v[196:199], v[22:25]
	v_mfma_f32_16x16x32_bf16 v[18:21], v[172:175], v[196:199], v[18:21]
	v_mfma_f32_16x16x32_bf16 v[6:9], v[164:167], v[204:207], v[6:9]
	v_mfma_f32_16x16x32_bf16 v[2:5], v[172:175], v[204:207], v[2:5]
	v_mfma_f32_16x16x32_bf16 v[54:57], v[168:171], v[184:187], v[54:57]
	v_mfma_f32_16x16x32_bf16 v[50:53], v[176:179], v[184:187], v[50:53]
	v_mfma_f32_16x16x32_bf16 v[38:41], v[168:171], v[192:195], v[38:41]
	v_mfma_f32_16x16x32_bf16 v[34:37], v[176:179], v[192:195], v[34:37]
	v_mfma_f32_16x16x32_bf16 v[22:25], v[168:171], v[200:203], v[22:25]
	v_mfma_f32_16x16x32_bf16 v[18:21], v[176:179], v[200:203], v[18:21]
	s_setprio 2
	s_barrier
	v_mfma_f32_16x16x32_bf16 v[6:9], v[168:171], v[208:211], v[6:9]
	v_mfma_f32_16x16x32_bf16 v[2:5], v[176:179], v[208:211], v[2:5]
	s_setprio 0
	s_add_i32 s77, s77, 2
	s_add_u32 s73, s73, 0x100
	s_addc_u32 s74, s74, 0
	s_add_u32 s18, s18, 0x100
	s_addc_u32 s19, s19, 0
	s_add_u32 s75, s75, 0x100
	s_addc_u32 s76, s76, 0
	s_cmp_gt_u32 s77, 29
	s_cbranch_scc0 .LBB0_1224
	s_and_b64 vcc, exec, s[6:7]
	s_cbranch_vccz .LBB0_1227
	s_barrier

.LBB0_1357:
	s_cmpk_eq_i32 s78, 0x52
	s_cselect_b32 s23, s11, s75
	s_cselect_b32 s22, s73, s74
	s_cselect_b32 s25, s13, s77
	s_cselect_b32 s24, s67, s76
	s_add_u32 s80, s20, 0xffffc000
	s_addc_u32 s81, s21, -1
	s_mov_b32 s79, m0
	s_mov_b32 m0, s58
	s_nop 0
	global_load_lds_dwordx4 v1, s[80:81]
	s_mov_b32 m0, s79
	s_nop 0
	s_mov_b32 s79, m0
	s_mov_b32 m0, s64
	s_nop 0
	global_load_lds_dwordx4 v177, s[80:81]
	s_mov_b32 m0, s79
	s_nop 0
	s_mov_b32 s79, m0
	s_mov_b32 m0, s59
	s_nop 0
	global_load_lds_dwordx4 v1, s[20:21]
	s_mov_b32 m0, s79
	s_nop 0
	s_mov_b32 s79, m0
	s_mov_b32 m0, s65
	s_nop 0
	global_load_lds_dwordx4 v177, s[20:21]
	s_mov_b32 m0, s79
	ds_read_b128 v[130:133], v181
	ds_read_b128 v[134:137], v181 offset:1024
	ds_read_b128 v[138:141], v181 offset:2048
	ds_read_b128 v[142:145], v181 offset:3072
	ds_read_b128 v[150:153], v182
	ds_read_b128 v[154:157], v182 offset:1024
	ds_read_b128 v[158:161], v182 offset:2048
	ds_read_b128 v[162:165], v182 offset:3072
	ds_read_b128 v[166:169], v183
	ds_read_b128 v[170:173], v183 offset:1024
	ds_read_b128 v[186:189], v183 offset:2048
	ds_read_b128 v[190:193], v183 offset:3072
	ds_read_b128 v[194:197], v183 offset:4096
	ds_read_b128 v[198:201], v183 offset:5120
	ds_read_b128 v[202:205], v183 offset:6144
	ds_read_b128 v[206:209], v183 offset:7168
	s_waitcnt vmcnt(8)
	s_waitcnt lgkmcnt(0)
	s_barrier
	s_setprio 1
	s_waitcnt lgkmcnt(7)
	v_mfma_f32_16x16x32_bf16 v[126:129], v[130:133], v[166:169], v[126:129]
	v_mfma_f32_16x16x32_bf16 v[122:125], v[138:141], v[166:169], v[122:125]
	s_waitcnt lgkmcnt(5)
	v_mfma_f32_16x16x32_bf16 v[118:121], v[130:133], v[186:189], v[118:121]
	v_mfma_f32_16x16x32_bf16 v[110:113], v[138:141], v[186:189], v[110:113]
	s_waitcnt lgkmcnt(3)
	v_mfma_f32_16x16x32_bf16 v[94:97], v[130:133], v[194:197], v[94:97]
	v_mfma_f32_16x16x32_bf16 v[90:93], v[138:141], v[194:197], v[90:93]
	s_waitcnt lgkmcnt(1)
	v_mfma_f32_16x16x32_bf16 v[86:89], v[130:133], v[202:205], v[86:89]
	v_mfma_f32_16x16x32_bf16 v[78:81], v[138:141], v[202:205], v[78:81]
	v_mfma_f32_16x16x32_bf16 v[126:129], v[134:137], v[170:173], v[126:129]
	v_mfma_f32_16x16x32_bf16 v[122:125], v[142:145], v[170:173], v[122:125]
	v_mfma_f32_16x16x32_bf16 v[118:121], v[134:137], v[190:193], v[118:121]
	v_mfma_f32_16x16x32_bf16 v[110:113], v[142:145], v[190:193], v[110:113]
	v_mfma_f32_16x16x32_bf16 v[94:97], v[134:137], v[198:201], v[94:97]
	v_mfma_f32_16x16x32_bf16 v[90:93], v[142:145], v[198:201], v[90:93]
	s_waitcnt lgkmcnt(0)
	v_mfma_f32_16x16x32_bf16 v[86:89], v[134:137], v[206:209], v[86:89]
	v_mfma_f32_16x16x32_bf16 v[78:81], v[142:145], v[206:209], v[78:81]
	s_setprio 0
	s_setprio 1
	v_mfma_f32_16x16x32_bf16 v[114:117], v[150:153], v[166:169], v[114:117]
	v_mfma_f32_16x16x32_bf16 v[106:109], v[158:161], v[166:169], v[106:109]
	v_mfma_f32_16x16x32_bf16 v[102:105], v[150:153], v[186:189], v[102:105]
	v_mfma_f32_16x16x32_bf16 v[98:101], v[158:161], v[186:189], v[98:101]
	v_mfma_f32_16x16x32_bf16 v[82:85], v[150:153], v[194:197], v[82:85]
	v_mfma_f32_16x16x32_bf16 v[74:77], v[158:161], v[194:197], v[74:77]
	v_mfma_f32_16x16x32_bf16 v[70:73], v[150:153], v[202:205], v[70:73]
	v_mfma_f32_16x16x32_bf16 v[66:69], v[158:161], v[202:205], v[66:69]
	v_mfma_f32_16x16x32_bf16 v[114:117], v[154:157], v[170:173], v[114:117]
	v_mfma_f32_16x16x32_bf16 v[106:109], v[162:165], v[170:173], v[106:109]
	v_mfma_f32_16x16x32_bf16 v[102:105], v[154:157], v[190:193], v[102:105]
	v_mfma_f32_16x16x32_bf16 v[98:101], v[162:165], v[190:193], v[98:101]
	v_mfma_f32_16x16x32_bf16 v[82:85], v[154:157], v[198:201], v[82:85]
	v_mfma_f32_16x16x32_bf16 v[74:77], v[162:165], v[198:201], v[74:77]
	s_setprio 2
	s_barrier
	v_mfma_f32_16x16x32_bf16 v[70:73], v[154:157], v[206:209], v[70:73]
	v_mfma_f32_16x16x32_bf16 v[66:69], v[162:165], v[206:209], v[66:69]
	s_setprio 0
	s_mov_b32 s79, m0
	s_mov_b32 m0, s35
	s_nop 0
	global_load_lds_dwordx4 v176, s[22:23]
	s_mov_b32 m0, s79
	s_add_u32 s80, s22, 0x4000
	s_mov_b32 s79, m0
	s_mov_b32 m0, s36
	s_nop 0
	global_load_lds_dwordx4 v178, s[22:23]
	s_mov_b32 m0, s79
	s_addc_u32 s81, s23, 0
	s_mov_b32 s79, m0
	s_mov_b32 m0, s37
	s_nop 0
	global_load_lds_dwordx4 v176, s[80:81]
	s_mov_b32 m0, s79
	s_nop 0
	s_mov_b32 s79, m0
	s_mov_b32 m0, s40
	s_nop 0
	global_load_lds_dwordx4 v178, s[80:81]
	s_mov_b32 m0, s79
	ds_read_b128 v[166:169], v183 offset:16384
	ds_read_b128 v[170:173], v183 offset:17408
	ds_read_b128 v[186:189], v183 offset:18432
	ds_read_b128 v[190:193], v183 offset:19456
	ds_read_b128 v[194:197], v183 offset:20480
	ds_read_b128 v[198:201], v183 offset:21504
	ds_read_b128 v[202:205], v183 offset:22528
	ds_read_b128 v[206:209], v183 offset:23552
	s_waitcnt vmcnt(4)
	s_waitcnt lgkmcnt(0)
	s_barrier
	s_setprio 1
	s_waitcnt lgkmcnt(7)
	v_mfma_f32_16x16x32_bf16 v[62:65], v[130:133], v[166:169], v[62:65]
	v_mfma_f32_16x16x32_bf16 v[58:61], v[138:141], v[166:169], v[58:61]
	s_waitcnt lgkmcnt(5)
	v_mfma_f32_16x16x32_bf16 v[46:49], v[130:133], v[186:189], v[46:49]
	v_mfma_f32_16x16x32_bf16 v[42:45], v[138:141], v[186:189], v[42:45]
	s_waitcnt lgkmcnt(3)
	v_mfma_f32_16x16x32_bf16 v[30:33], v[130:133], v[194:197], v[30:33]
	v_mfma_f32_16x16x32_bf16 v[26:29], v[138:141], v[194:197], v[26:29]
	s_waitcnt lgkmcnt(1)
	v_mfma_f32_16x16x32_bf16 v[14:17], v[130:133], v[202:205], v[14:17]
	v_mfma_f32_16x16x32_bf16 v[10:13], v[138:141], v[202:205], v[10:13]
	v_mfma_f32_16x16x32_bf16 v[62:65], v[134:137], v[170:173], v[62:65]
	v_mfma_f32_16x16x32_bf16 v[58:61], v[142:145], v[170:173], v[58:61]
	v_mfma_f32_16x16x32_bf16 v[46:49], v[134:137], v[190:193], v[46:49]
	v_mfma_f32_16x16x32_bf16 v[42:45], v[142:145], v[190:193], v[42:45]
	v_mfma_f32_16x16x32_bf16 v[30:33], v[134:137], v[198:201], v[30:33]
	v_mfma_f32_16x16x32_bf16 v[26:29], v[142:145], v[198:201], v[26:29]
	s_waitcnt lgkmcnt(0)
	v_mfma_f32_16x16x32_bf16 v[14:17], v[134:137], v[206:209], v[14:17]
	v_mfma_f32_16x16x32_bf16 v[10:13], v[142:145], v[206:209], v[10:13]
	s_setprio 0
	s_setprio 1
	v_mfma_f32_16x16x32_bf16 v[54:57], v[150:153], v[166:169], v[54:57]
	v_mfma_f32_16x16x32_bf16 v[50:53], v[158:161], v[166:169], v[50:53]
	v_mfma_f32_16x16x32_bf16 v[38:41], v[150:153], v[186:189], v[38:41]
	v_mfma_f32_16x16x32_bf16 v[34:37], v[158:161], v[186:189], v[34:37]
	v_mfma_f32_16x16x32_bf16 v[22:25], v[150:153], v[194:197], v[22:25]
	v_mfma_f32_16x16x32_bf16 v[18:21], v[158:161], v[194:197], v[18:21]
	v_mfma_f32_16x16x32_bf16 v[6:9], v[150:153], v[202:205], v[6:9]
	v_mfma_f32_16x16x32_bf16 v[2:5], v[158:161], v[202:205], v[2:5]
	v_mfma_f32_16x16x32_bf16 v[54:57], v[154:157], v[170:173], v[54:57]
	v_mfma_f32_16x16x32_bf16 v[50:53], v[162:165], v[170:173], v[50:53]
	v_mfma_f32_16x16x32_bf16 v[38:41], v[154:157], v[190:193], v[38:41]
	v_mfma_f32_16x16x32_bf16 v[34:37], v[162:165], v[190:193], v[34:37]
	v_mfma_f32_16x16x32_bf16 v[22:25], v[154:157], v[198:201], v[22:25]
	v_mfma_f32_16x16x32_bf16 v[18:21], v[162:165], v[198:201], v[18:21]
	s_setprio 2
	s_barrier
	v_mfma_f32_16x16x32_bf16 v[6:9], v[154:157], v[206:209], v[6:9]
	v_mfma_f32_16x16x32_bf16 v[2:5], v[162:165], v[206:209], v[2:5]
	s_setprio 0
	s_mov_b32 s79, m0
	s_mov_b32 m0, s34
	s_nop 0
	global_load_lds_dwordx4 v1, s[24:25]
	s_mov_b32 m0, s79
	s_nop 0
	s_mov_b32 s79, m0
	s_mov_b32 m0, s41
	s_nop 0
	global_load_lds_dwordx4 v177, s[24:25]
	s_mov_b32 m0, s79
	s_add_u32 s24, s24, 0x4000
	s_addc_u32 s25, s25, 0
	s_mov_b32 s79, m0
	s_mov_b32 m0, s42
	s_nop 0
	global_load_lds_dwordx4 v1, s[24:25]
	s_mov_b32 m0, s79
	s_nop 0
	s_mov_b32 s79, m0
	s_mov_b32 m0, s43
	s_nop 0
	global_load_lds_dwordx4 v177, s[24:25]
	s_mov_b32 m0, s79
	ds_read_b128 v[130:133], v184
	ds_read_b128 v[134:137], v184 offset:1024
	ds_read_b128 v[138:141], v184 offset:2048
	ds_read_b128 v[142:145], v184 offset:3072
	ds_read_b128 v[150:153], v185
	ds_read_b128 v[154:157], v185 offset:1024
	ds_read_b128 v[158:161], v185 offset:2048
	ds_read_b128 v[162:165], v185 offset:3072
	ds_read_b128 v[166:169], v183 offset:32768
	ds_read_b128 v[170:173], v183 offset:33792
	ds_read_b128 v[186:189], v183 offset:34816
	ds_read_b128 v[190:193], v183 offset:35840
	ds_read_b128 v[194:197], v183 offset:36864
	ds_read_b128 v[198:201], v183 offset:37888
	ds_read_b128 v[202:205], v183 offset:38912
	ds_read_b128 v[206:209], v183 offset:39936
	s_waitcnt vmcnt(8)
	s_waitcnt lgkmcnt(0)
	s_barrier
	s_setprio 1
	s_waitcnt lgkmcnt(7)
	v_mfma_f32_16x16x32_bf16 v[126:129], v[130:133], v[166:169], v[126:129]
	v_mfma_f32_16x16x32_bf16 v[122:125], v[138:141], v[166:169], v[122:125]
	s_waitcnt lgkmcnt(5)
	v_mfma_f32_16x16x32_bf16 v[118:121], v[130:133], v[186:189], v[118:121]
	v_mfma_f32_16x16x32_bf16 v[110:113], v[138:141], v[186:189], v[110:113]
	s_waitcnt lgkmcnt(3)
	v_mfma_f32_16x16x32_bf16 v[94:97], v[130:133], v[194:197], v[94:97]
	v_mfma_f32_16x16x32_bf16 v[90:93], v[138:141], v[194:197], v[90:93]
	s_waitcnt lgkmcnt(1)
	v_mfma_f32_16x16x32_bf16 v[86:89], v[130:133], v[202:205], v[86:89]
	v_mfma_f32_16x16x32_bf16 v[78:81], v[138:141], v[202:205], v[78:81]
	v_mfma_f32_16x16x32_bf16 v[126:129], v[134:137], v[170:173], v[126:129]
	v_mfma_f32_16x16x32_bf16 v[122:125], v[142:145], v[170:173], v[122:125]
	v_mfma_f32_16x16x32_bf16 v[118:121], v[134:137], v[190:193], v[118:121]
	v_mfma_f32_16x16x32_bf16 v[110:113], v[142:145], v[190:193], v[110:113]
	v_mfma_f32_16x16x32_bf16 v[94:97], v[134:137], v[198:201], v[94:97]
	v_mfma_f32_16x16x32_bf16 v[90:93], v[142:145], v[198:201], v[90:93]
	s_waitcnt lgkmcnt(0)
	v_mfma_f32_16x16x32_bf16 v[86:89], v[134:137], v[206:209], v[86:89]
	v_mfma_f32_16x16x32_bf16 v[78:81], v[142:145], v[206:209], v[78:81]
	s_setprio 0
	s_setprio 1
	v_mfma_f32_16x16x32_bf16 v[114:117], v[150:153], v[166:169], v[114:117]
	v_mfma_f32_16x16x32_bf16 v[106:109], v[158:161], v[166:169], v[106:109]
	v_mfma_f32_16x16x32_bf16 v[102:105], v[150:153], v[186:189], v[102:105]
	v_mfma_f32_16x16x32_bf16 v[98:101], v[158:161], v[186:189], v[98:101]
	v_mfma_f32_16x16x32_bf16 v[82:85], v[150:153], v[194:197], v[82:85]
	v_mfma_f32_16x16x32_bf16 v[74:77], v[158:161], v[194:197], v[74:77]
	v_mfma_f32_16x16x32_bf16 v[70:73], v[150:153], v[202:205], v[70:73]
	v_mfma_f32_16x16x32_bf16 v[66:69], v[158:161], v[202:205], v[66:69]
	v_mfma_f32_16x16x32_bf16 v[114:117], v[154:157], v[170:173], v[114:117]
	v_mfma_f32_16x16x32_bf16 v[106:109], v[162:165], v[170:173], v[106:109]
	v_mfma_f32_16x16x32_bf16 v[102:105], v[154:157], v[190:193], v[102:105]
	v_mfma_f32_16x16x32_bf16 v[98:101], v[162:165], v[190:193], v[98:101]
	v_mfma_f32_16x16x32_bf16 v[82:85], v[154:157], v[198:201], v[82:85]
	v_mfma_f32_16x16x32_bf16 v[74:77], v[162:165], v[198:201], v[74:77]
	s_setprio 2
	s_barrier
	v_mfma_f32_16x16x32_bf16 v[70:73], v[154:157], v[206:209], v[70:73]
	v_mfma_f32_16x16x32_bf16 v[66:69], v[162:165], v[206:209], v[66:69]
	s_setprio 0
	s_add_u32 s24, s22, 0x40000
	s_addc_u32 s25, s23, 0
	s_mov_b32 s79, m0
	s_mov_b32 m0, s46
	s_nop 0
	global_load_lds_dwordx4 v176, s[24:25]
	s_mov_b32 m0, s79
	s_add_u32 s22, s22, 0x44000
	s_mov_b32 s79, m0
	s_mov_b32 m0, s47
	s_nop 0
	global_load_lds_dwordx4 v178, s[24:25]
	s_mov_b32 m0, s79
	s_addc_u32 s23, s23, 0
	s_mov_b32 s24, m0
	s_mov_b32 m0, s48
	s_nop 0
	global_load_lds_dwordx4 v176, s[22:23]
	s_mov_b32 m0, s24
	s_nop 0
	s_mov_b32 s24, m0
	s_mov_b32 m0, s49
	s_nop 0
	global_load_lds_dwordx4 v178, s[22:23]
	s_mov_b32 m0, s24
	ds_read_b128 v[166:169], v183 offset:49152
	ds_read_b128 v[170:173], v183 offset:50176
	ds_read_b128 v[186:189], v183 offset:51200
	ds_read_b128 v[190:193], v183 offset:52224
	ds_read_b128 v[194:197], v183 offset:53248
	ds_read_b128 v[198:201], v183 offset:54272
	ds_read_b128 v[202:205], v183 offset:55296
	ds_read_b128 v[206:209], v183 offset:56320
	s_waitcnt vmcnt(4)
	s_waitcnt lgkmcnt(0)
	s_barrier
	s_setprio 1
	s_waitcnt lgkmcnt(7)
	v_mfma_f32_16x16x32_bf16 v[62:65], v[130:133], v[166:169], v[62:65]
	v_mfma_f32_16x16x32_bf16 v[58:61], v[138:141], v[166:169], v[58:61]
	s_waitcnt lgkmcnt(5)
	v_mfma_f32_16x16x32_bf16 v[46:49], v[130:133], v[186:189], v[46:49]
	v_mfma_f32_16x16x32_bf16 v[42:45], v[138:141], v[186:189], v[42:45]
	s_waitcnt lgkmcnt(3)
	v_mfma_f32_16x16x32_bf16 v[30:33], v[130:133], v[194:197], v[30:33]
	v_mfma_f32_16x16x32_bf16 v[26:29], v[138:141], v[194:197], v[26:29]
	s_waitcnt lgkmcnt(1)
	v_mfma_f32_16x16x32_bf16 v[14:17], v[130:133], v[202:205], v[14:17]
	v_mfma_f32_16x16x32_bf16 v[10:13], v[138:141], v[202:205], v[10:13]
	v_mfma_f32_16x16x32_bf16 v[62:65], v[134:137], v[170:173], v[62:65]
	v_mfma_f32_16x16x32_bf16 v[58:61], v[142:145], v[170:173], v[58:61]
	v_mfma_f32_16x16x32_bf16 v[46:49], v[134:137], v[190:193], v[46:49]
	v_mfma_f32_16x16x32_bf16 v[42:45], v[142:145], v[190:193], v[42:45]
	v_mfma_f32_16x16x32_bf16 v[30:33], v[134:137], v[198:201], v[30:33]
	v_mfma_f32_16x16x32_bf16 v[26:29], v[142:145], v[198:201], v[26:29]
	s_waitcnt lgkmcnt(0)
	v_mfma_f32_16x16x32_bf16 v[14:17], v[134:137], v[206:209], v[14:17]
	v_mfma_f32_16x16x32_bf16 v[10:13], v[142:145], v[206:209], v[10:13]
	s_setprio 0
	s_setprio 1
	v_mfma_f32_16x16x32_bf16 v[54:57], v[150:153], v[166:169], v[54:57]
	v_mfma_f32_16x16x32_bf16 v[50:53], v[158:161], v[166:169], v[50:53]
	v_mfma_f32_16x16x32_bf16 v[38:41], v[150:153], v[186:189], v[38:41]
	v_mfma_f32_16x16x32_bf16 v[34:37], v[158:161], v[186:189], v[34:37]
	v_mfma_f32_16x16x32_bf16 v[22:25], v[150:153], v[194:197], v[22:25]
	v_mfma_f32_16x16x32_bf16 v[18:21], v[158:161], v[194:197], v[18:21]
	v_mfma_f32_16x16x32_bf16 v[6:9], v[150:153], v[202:205], v[6:9]
	v_mfma_f32_16x16x32_bf16 v[2:5], v[158:161], v[202:205], v[2:5]
	v_mfma_f32_16x16x32_bf16 v[54:57], v[154:157], v[170:173], v[54:57]
	v_mfma_f32_16x16x32_bf16 v[50:53], v[162:165], v[170:173], v[50:53]
	v_mfma_f32_16x16x32_bf16 v[38:41], v[154:157], v[190:193], v[38:41]
	v_mfma_f32_16x16x32_bf16 v[34:37], v[162:165], v[190:193], v[34:37]
	v_mfma_f32_16x16x32_bf16 v[22:25], v[154:157], v[198:201], v[22:25]
	v_mfma_f32_16x16x32_bf16 v[18:21], v[162:165], v[198:201], v[18:21]
	s_setprio 2
	s_barrier
	v_mfma_f32_16x16x32_bf16 v[6:9], v[154:157], v[206:209], v[6:9]
	v_mfma_f32_16x16x32_bf16 v[2:5], v[162:165], v[206:209], v[2:5]
	s_setprio 0
	s_add_i32 s78, s78, 2
	s_add_u32 s74, s74, 0x80000
	s_addc_u32 s75, s75, 0
	s_add_u32 s20, s20, 0x400000
	s_addc_u32 s21, s21, 0
	s_add_u32 s76, s76, 0x400000
	s_addc_u32 s77, s77, 0
	s_cmpk_gt_u32 s78, 0x53
	s_cbranch_scc0 .LBB0_1357
	s_and_b64 vcc, exec, s[8:9]
	s_cbranch_vccz .LBB0_1360
	s_barrier

.LBB0_1538:
	s_cmp_eq_u32 s83, 28
	s_cselect_b32 s35, s21, s80
	s_cselect_b32 s34, s29, s79
	s_cselect_b32 s37, s7, s82
	s_cselect_b32 s36, s23, s81
	s_add_u32 s86, s30, 0xfff80000
	s_addc_u32 s87, s31, -1
	s_mov_b32 s92, m0
	s_mov_b32 m0, s73
	s_nop 0
	global_load_lds_dwordx4 v176, s[86:87]
	s_mov_b32 m0, s92
	s_nop 0
	s_mov_b32 s92, m0
	s_mov_b32 m0, s75
	s_nop 0
	global_load_lds_dwordx4 v178, s[86:87]
	s_mov_b32 m0, s92
	s_mov_b32 s86, m0
	s_mov_b32 m0, s74
	s_nop 0
	global_load_lds_dwordx4 v176, s[30:31]
	s_mov_b32 m0, s86
	s_nop 0
	s_mov_b32 s86, m0
	s_mov_b32 m0, s76
	s_nop 0
	global_load_lds_dwordx4 v178, s[30:31]
	s_mov_b32 m0, s86
	ds_read_b128 v[46:49], v182
	ds_read_b128 v[54:57], v182 offset:1024
	ds_read_b128 v[58:61], v182 offset:2048
	ds_read_b128 v[62:65], v182 offset:3072
	ds_read_b128 v[146:149], v183
	ds_read_b128 v[150:153], v183 offset:1024
	ds_read_b128 v[154:157], v183 offset:2048
	ds_read_b128 v[158:161], v183 offset:3072
	ds_read_b128 v[170:173], v184
	ds_read_b128 v[188:191], v184 offset:1024
	ds_read_b128 v[192:195], v184 offset:2048
	ds_read_b128 v[196:199], v184 offset:3072
	ds_read_b128 v[200:203], v184 offset:4096
	ds_read_b128 v[204:207], v184 offset:5120
	ds_read_b128 v[208:211], v184 offset:6144
	ds_read_b128 v[212:215], v184 offset:7168
	s_waitcnt vmcnt(8)
	s_waitcnt lgkmcnt(0)
	s_barrier
	s_setprio 1
	s_waitcnt lgkmcnt(7)
	v_mfma_f32_16x16x32_bf16 v[142:145], v[46:49], v[170:173], v[142:145]
	v_mfma_f32_16x16x32_bf16 v[138:141], v[58:61], v[170:173], v[138:141]
	s_waitcnt lgkmcnt(5)
	v_mfma_f32_16x16x32_bf16 v[126:129], v[46:49], v[192:195], v[126:129]
	v_mfma_f32_16x16x32_bf16 v[122:125], v[58:61], v[192:195], v[122:125]
	s_waitcnt lgkmcnt(3)
	v_mfma_f32_16x16x32_bf16 v[110:113], v[46:49], v[200:203], v[110:113]
	v_mfma_f32_16x16x32_bf16 v[106:109], v[58:61], v[200:203], v[106:109]
	s_waitcnt lgkmcnt(1)
	v_mfma_f32_16x16x32_bf16 v[94:97], v[46:49], v[208:211], v[94:97]
	v_mfma_f32_16x16x32_bf16 v[90:93], v[58:61], v[208:211], v[90:93]
	v_mfma_f32_16x16x32_bf16 v[142:145], v[54:57], v[188:191], v[142:145]
	v_mfma_f32_16x16x32_bf16 v[138:141], v[62:65], v[188:191], v[138:141]
	v_mfma_f32_16x16x32_bf16 v[126:129], v[54:57], v[196:199], v[126:129]
	v_mfma_f32_16x16x32_bf16 v[122:125], v[62:65], v[196:199], v[122:125]
	v_mfma_f32_16x16x32_bf16 v[110:113], v[54:57], v[204:207], v[110:113]
	v_mfma_f32_16x16x32_bf16 v[106:109], v[62:65], v[204:207], v[106:109]
	s_waitcnt lgkmcnt(0)
	v_mfma_f32_16x16x32_bf16 v[94:97], v[54:57], v[212:215], v[94:97]
	v_mfma_f32_16x16x32_bf16 v[90:93], v[62:65], v[212:215], v[90:93]
	s_setprio 0
	s_setprio 1
	v_mfma_f32_16x16x32_bf16 v[134:137], v[146:149], v[170:173], v[134:137]
	v_mfma_f32_16x16x32_bf16 v[130:133], v[154:157], v[170:173], v[130:133]
	v_mfma_f32_16x16x32_bf16 v[118:121], v[146:149], v[192:195], v[118:121]
	v_mfma_f32_16x16x32_bf16 v[114:117], v[154:157], v[192:195], v[114:117]
	v_mfma_f32_16x16x32_bf16 v[102:105], v[146:149], v[200:203], v[102:105]
	v_mfma_f32_16x16x32_bf16 v[98:101], v[154:157], v[200:203], v[98:101]
	v_mfma_f32_16x16x32_bf16 v[86:89], v[146:149], v[208:211], v[86:89]
	v_mfma_f32_16x16x32_bf16 v[82:85], v[154:157], v[208:211], v[82:85]
	v_mfma_f32_16x16x32_bf16 v[134:137], v[150:153], v[188:191], v[134:137]
	v_mfma_f32_16x16x32_bf16 v[130:133], v[158:161], v[188:191], v[130:133]
	v_mfma_f32_16x16x32_bf16 v[118:121], v[150:153], v[196:199], v[118:121]
	v_mfma_f32_16x16x32_bf16 v[114:117], v[158:161], v[196:199], v[114:117]
	v_mfma_f32_16x16x32_bf16 v[102:105], v[150:153], v[204:207], v[102:105]
	v_mfma_f32_16x16x32_bf16 v[98:101], v[158:161], v[204:207], v[98:101]
	s_setprio 2
	s_barrier
	v_mfma_f32_16x16x32_bf16 v[86:89], v[150:153], v[212:215], v[86:89]
	v_mfma_f32_16x16x32_bf16 v[82:85], v[158:161], v[212:215], v[82:85]
	s_setprio 0
	s_mov_b32 s86, m0
	s_mov_b32 m0, s49
	s_nop 0
	global_load_lds_dwordx4 v177, s[34:35]
	s_mov_b32 m0, s86
	s_nop 0
	s_mov_b32 s86, m0
	s_mov_b32 m0, s56
	s_nop 0
	global_load_lds_dwordx4 v179, s[34:35]
	s_mov_b32 m0, s86
	s_add_u32 s86, s34, 0x80000
	s_addc_u32 s87, s35, 0
	s_mov_b32 s92, m0
	s_mov_b32 m0, s57
	s_nop 0
	global_load_lds_dwordx4 v177, s[86:87]
	s_mov_b32 m0, s92
	s_nop 0
	s_mov_b32 s92, m0
	s_mov_b32 m0, s58
	s_nop 0
	global_load_lds_dwordx4 v179, s[86:87]
	s_mov_b32 m0, s92
	ds_read_b128 v[170:173], v184 offset:16384
	ds_read_b128 v[188:191], v184 offset:17408
	ds_read_b128 v[192:195], v184 offset:18432
	ds_read_b128 v[196:199], v184 offset:19456
	ds_read_b128 v[200:203], v184 offset:20480
	ds_read_b128 v[204:207], v184 offset:21504
	ds_read_b128 v[208:211], v184 offset:22528
	ds_read_b128 v[212:215], v184 offset:23552
	s_waitcnt vmcnt(4)
	s_waitcnt lgkmcnt(0)
	s_barrier
	s_setprio 1
	s_waitcnt lgkmcnt(7)
	v_mfma_f32_16x16x32_bf16 v[78:81], v[46:49], v[170:173], v[78:81]
	v_mfma_f32_16x16x32_bf16 v[74:77], v[58:61], v[170:173], v[74:77]
	s_waitcnt lgkmcnt(5)
	v_mfma_f32_16x16x32_bf16 v[50:53], v[46:49], v[192:195], v[50:53]
	v_mfma_f32_16x16x32_bf16 v[42:45], v[58:61], v[192:195], v[42:45]
	s_waitcnt lgkmcnt(3)
	v_mfma_f32_16x16x32_bf16 v[30:33], v[46:49], v[200:203], v[30:33]
	v_mfma_f32_16x16x32_bf16 v[26:29], v[58:61], v[200:203], v[26:29]
	s_waitcnt lgkmcnt(1)
	v_mfma_f32_16x16x32_bf16 v[14:17], v[46:49], v[208:211], v[14:17]
	v_mfma_f32_16x16x32_bf16 v[10:13], v[58:61], v[208:211], v[10:13]
	v_mfma_f32_16x16x32_bf16 v[78:81], v[54:57], v[188:191], v[78:81]
	v_mfma_f32_16x16x32_bf16 v[74:77], v[62:65], v[188:191], v[74:77]
	v_mfma_f32_16x16x32_bf16 v[50:53], v[54:57], v[196:199], v[50:53]
	v_mfma_f32_16x16x32_bf16 v[42:45], v[62:65], v[196:199], v[42:45]
	v_mfma_f32_16x16x32_bf16 v[30:33], v[54:57], v[204:207], v[30:33]
	v_mfma_f32_16x16x32_bf16 v[26:29], v[62:65], v[204:207], v[26:29]
	s_waitcnt lgkmcnt(0)
	v_mfma_f32_16x16x32_bf16 v[14:17], v[54:57], v[212:215], v[14:17]
	v_mfma_f32_16x16x32_bf16 v[10:13], v[62:65], v[212:215], v[10:13]
	s_setprio 0
	s_setprio 1
	v_mfma_f32_16x16x32_bf16 v[38:41], v[146:149], v[192:195], v[38:41]
	v_mfma_f32_16x16x32_bf16 v[34:37], v[154:157], v[192:195], v[34:37]
	v_mfma_f32_16x16x32_bf16 v[22:25], v[146:149], v[200:203], v[22:25]
	v_mfma_f32_16x16x32_bf16 v[18:21], v[154:157], v[200:203], v[18:21]
	v_mfma_f32_16x16x32_bf16 v[6:9], v[146:149], v[208:211], v[6:9]
	v_mfma_f32_16x16x32_bf16 v[2:5], v[154:157], v[208:211], v[2:5]
	v_mfma_f32_16x16x32_bf16 v[46:49], v[146:149], v[170:173], v[70:73]
	v_mfma_f32_16x16x32_bf16 v[54:57], v[154:157], v[170:173], v[66:69]
	v_mfma_f32_16x16x32_bf16 v[38:41], v[150:153], v[196:199], v[38:41]
	v_mfma_f32_16x16x32_bf16 v[34:37], v[158:161], v[196:199], v[34:37]
	v_mfma_f32_16x16x32_bf16 v[22:25], v[150:153], v[204:207], v[22:25]
	v_mfma_f32_16x16x32_bf16 v[18:21], v[158:161], v[204:207], v[18:21]
	v_mfma_f32_16x16x32_bf16 v[6:9], v[150:153], v[212:215], v[6:9]
	v_mfma_f32_16x16x32_bf16 v[2:5], v[158:161], v[212:215], v[2:5]
	s_setprio 2
	s_barrier
	v_mfma_f32_16x16x32_bf16 v[46:49], v[150:153], v[188:191], v[46:49]
	v_mfma_f32_16x16x32_bf16 v[54:57], v[158:161], v[188:191], v[54:57]
	s_setprio 0
	s_mov_b32 s86, m0
	s_mov_b32 m0, s48
	s_nop 0
	global_load_lds_dwordx4 v176, s[36:37]
	s_mov_b32 m0, s86
	s_nop 0
	s_mov_b32 s86, m0
	s_mov_b32 m0, s59
	s_nop 0
	global_load_lds_dwordx4 v178, s[36:37]
	s_mov_b32 m0, s86
	s_add_u32 s36, s36, 0x80000
	s_addc_u32 s37, s37, 0
	s_mov_b32 s86, m0
	s_mov_b32 m0, s62
	s_nop 0
	global_load_lds_dwordx4 v176, s[36:37]
	s_mov_b32 m0, s86
	s_nop 0
	s_mov_b32 s86, m0
	s_mov_b32 m0, s63
	s_nop 0
	global_load_lds_dwordx4 v178, s[36:37]
	s_mov_b32 m0, s86
	ds_read_b128 v[58:61], v185
	ds_read_b128 v[62:65], v185 offset:1024
	ds_read_b128 v[66:69], v185 offset:2048
	ds_read_b128 v[70:73], v185 offset:3072
	ds_read_b128 v[146:149], v186
	ds_read_b128 v[150:153], v186 offset:1024
	ds_read_b128 v[154:157], v186 offset:2048
	ds_read_b128 v[158:161], v186 offset:3072
	ds_read_b128 v[170:173], v184 offset:32768
	ds_read_b128 v[188:191], v184 offset:33792
	ds_read_b128 v[192:195], v184 offset:34816
	ds_read_b128 v[196:199], v184 offset:35840
	ds_read_b128 v[200:203], v184 offset:36864
	ds_read_b128 v[204:207], v184 offset:37888
	ds_read_b128 v[208:211], v184 offset:38912
	ds_read_b128 v[212:215], v184 offset:39936
	s_waitcnt vmcnt(8)
	s_waitcnt lgkmcnt(0)
	s_barrier
	s_setprio 1
	s_waitcnt lgkmcnt(7)
	v_mfma_f32_16x16x32_bf16 v[142:145], v[58:61], v[170:173], v[142:145]
	v_mfma_f32_16x16x32_bf16 v[138:141], v[66:69], v[170:173], v[138:141]
	s_waitcnt lgkmcnt(5)
	v_mfma_f32_16x16x32_bf16 v[126:129], v[58:61], v[192:195], v[126:129]
	v_mfma_f32_16x16x32_bf16 v[122:125], v[66:69], v[192:195], v[122:125]
	s_waitcnt lgkmcnt(3)
	v_mfma_f32_16x16x32_bf16 v[110:113], v[58:61], v[200:203], v[110:113]
	v_mfma_f32_16x16x32_bf16 v[106:109], v[66:69], v[200:203], v[106:109]
	s_waitcnt lgkmcnt(1)
	v_mfma_f32_16x16x32_bf16 v[94:97], v[58:61], v[208:211], v[94:97]
	v_mfma_f32_16x16x32_bf16 v[90:93], v[66:69], v[208:211], v[90:93]
	v_mfma_f32_16x16x32_bf16 v[142:145], v[62:65], v[188:191], v[142:145]
	v_mfma_f32_16x16x32_bf16 v[138:141], v[70:73], v[188:191], v[138:141]
	v_mfma_f32_16x16x32_bf16 v[126:129], v[62:65], v[196:199], v[126:129]
	v_mfma_f32_16x16x32_bf16 v[122:125], v[70:73], v[196:199], v[122:125]
	v_mfma_f32_16x16x32_bf16 v[110:113], v[62:65], v[204:207], v[110:113]
	v_mfma_f32_16x16x32_bf16 v[106:109], v[70:73], v[204:207], v[106:109]
	s_waitcnt lgkmcnt(0)
	v_mfma_f32_16x16x32_bf16 v[94:97], v[62:65], v[212:215], v[94:97]
	v_mfma_f32_16x16x32_bf16 v[90:93], v[70:73], v[212:215], v[90:93]
	s_setprio 0
	s_setprio 1
	v_mfma_f32_16x16x32_bf16 v[134:137], v[146:149], v[170:173], v[134:137]
	v_mfma_f32_16x16x32_bf16 v[130:133], v[154:157], v[170:173], v[130:133]
	v_mfma_f32_16x16x32_bf16 v[118:121], v[146:149], v[192:195], v[118:121]
	v_mfma_f32_16x16x32_bf16 v[114:117], v[154:157], v[192:195], v[114:117]
	v_mfma_f32_16x16x32_bf16 v[102:105], v[146:149], v[200:203], v[102:105]
	v_mfma_f32_16x16x32_bf16 v[98:101], v[154:157], v[200:203], v[98:101]
	v_mfma_f32_16x16x32_bf16 v[86:89], v[146:149], v[208:211], v[86:89]
	v_mfma_f32_16x16x32_bf16 v[82:85], v[154:157], v[208:211], v[82:85]
	v_mfma_f32_16x16x32_bf16 v[134:137], v[150:153], v[188:191], v[134:137]
	v_mfma_f32_16x16x32_bf16 v[130:133], v[158:161], v[188:191], v[130:133]
	v_mfma_f32_16x16x32_bf16 v[118:121], v[150:153], v[196:199], v[118:121]
	v_mfma_f32_16x16x32_bf16 v[114:117], v[158:161], v[196:199], v[114:117]
	v_mfma_f32_16x16x32_bf16 v[102:105], v[150:153], v[204:207], v[102:105]
	v_mfma_f32_16x16x32_bf16 v[98:101], v[158:161], v[204:207], v[98:101]
	s_setprio 2
	s_barrier
	v_mfma_f32_16x16x32_bf16 v[86:89], v[150:153], v[212:215], v[86:89]
	v_mfma_f32_16x16x32_bf16 v[82:85], v[158:161], v[212:215], v[82:85]
	s_setprio 0
	s_add_u32 s36, s34, 0x80
	s_addc_u32 s37, s35, 0
	s_mov_b32 s86, m0
	s_mov_b32 m0, s64
	s_nop 0
	global_load_lds_dwordx4 v177, s[36:37]
	s_mov_b32 m0, s86
	s_add_u32 s34, s34, 0x80080
	s_mov_b32 s86, m0
	s_mov_b32 m0, s65
	s_nop 0
	global_load_lds_dwordx4 v179, s[36:37]
	s_mov_b32 m0, s86
	s_addc_u32 s35, s35, 0
	s_mov_b32 s36, m0
	s_mov_b32 m0, s66
	s_nop 0
	global_load_lds_dwordx4 v177, s[34:35]
	s_mov_b32 m0, s36
	s_nop 0
	s_mov_b32 s36, m0
	s_mov_b32 m0, s67
	s_nop 0
	global_load_lds_dwordx4 v179, s[34:35]
	s_mov_b32 m0, s36
	ds_read_b128 v[170:173], v184 offset:49152
	ds_read_b128 v[188:191], v184 offset:50176
	ds_read_b128 v[192:195], v184 offset:51200
	ds_read_b128 v[196:199], v184 offset:52224
	ds_read_b128 v[200:203], v184 offset:53248
	ds_read_b128 v[204:207], v184 offset:54272
	ds_read_b128 v[208:211], v184 offset:55296
	ds_read_b128 v[212:215], v184 offset:56320
	s_waitcnt vmcnt(4)
	s_waitcnt lgkmcnt(0)
	s_barrier
	s_setprio 1
	s_waitcnt lgkmcnt(7)
	v_mfma_f32_16x16x32_bf16 v[78:81], v[58:61], v[170:173], v[78:81]
	v_mfma_f32_16x16x32_bf16 v[74:77], v[66:69], v[170:173], v[74:77]
	s_waitcnt lgkmcnt(5)
	v_mfma_f32_16x16x32_bf16 v[50:53], v[58:61], v[192:195], v[50:53]
	v_mfma_f32_16x16x32_bf16 v[42:45], v[66:69], v[192:195], v[42:45]
	s_waitcnt lgkmcnt(3)
	v_mfma_f32_16x16x32_bf16 v[30:33], v[58:61], v[200:203], v[30:33]
	v_mfma_f32_16x16x32_bf16 v[26:29], v[66:69], v[200:203], v[26:29]
	s_waitcnt lgkmcnt(1)
	v_mfma_f32_16x16x32_bf16 v[14:17], v[58:61], v[208:211], v[14:17]
	v_mfma_f32_16x16x32_bf16 v[10:13], v[66:69], v[208:211], v[10:13]
	v_mfma_f32_16x16x32_bf16 v[78:81], v[62:65], v[188:191], v[78:81]
	v_mfma_f32_16x16x32_bf16 v[74:77], v[70:73], v[188:191], v[74:77]
	v_mfma_f32_16x16x32_bf16 v[50:53], v[62:65], v[196:199], v[50:53]
	v_mfma_f32_16x16x32_bf16 v[42:45], v[70:73], v[196:199], v[42:45]
	v_mfma_f32_16x16x32_bf16 v[30:33], v[62:65], v[204:207], v[30:33]
	v_mfma_f32_16x16x32_bf16 v[26:29], v[70:73], v[204:207], v[26:29]
	s_waitcnt lgkmcnt(0)
	v_mfma_f32_16x16x32_bf16 v[14:17], v[62:65], v[212:215], v[14:17]
	v_mfma_f32_16x16x32_bf16 v[10:13], v[70:73], v[212:215], v[10:13]
	s_setprio 0
	s_setprio 1
	v_mfma_f32_16x16x32_bf16 v[46:49], v[146:149], v[170:173], v[46:49]
	v_mfma_f32_16x16x32_bf16 v[70:73], v[150:153], v[188:191], v[46:49]
	v_mfma_f32_16x16x32_bf16 v[46:49], v[154:157], v[170:173], v[54:57]
	v_mfma_f32_16x16x32_bf16 v[38:41], v[146:149], v[192:195], v[38:41]
	v_mfma_f32_16x16x32_bf16 v[34:37], v[154:157], v[192:195], v[34:37]
	v_mfma_f32_16x16x32_bf16 v[22:25], v[146:149], v[200:203], v[22:25]
	v_mfma_f32_16x16x32_bf16 v[18:21], v[154:157], v[200:203], v[18:21]
	v_mfma_f32_16x16x32_bf16 v[6:9], v[146:149], v[208:211], v[6:9]
	v_mfma_f32_16x16x32_bf16 v[2:5], v[154:157], v[208:211], v[2:5]
	v_mfma_f32_16x16x32_bf16 v[66:69], v[158:161], v[188:191], v[46:49]
	v_mfma_f32_16x16x32_bf16 v[38:41], v[150:153], v[196:199], v[38:41]
	v_mfma_f32_16x16x32_bf16 v[34:37], v[158:161], v[196:199], v[34:37]
	v_mfma_f32_16x16x32_bf16 v[22:25], v[150:153], v[204:207], v[22:25]
	v_mfma_f32_16x16x32_bf16 v[18:21], v[158:161], v[204:207], v[18:21]
	s_setprio 2
	s_barrier
	v_mfma_f32_16x16x32_bf16 v[6:9], v[150:153], v[212:215], v[6:9]
	v_mfma_f32_16x16x32_bf16 v[2:5], v[158:161], v[212:215], v[2:5]
	s_setprio 0
	s_add_i32 s83, s83, 2
	s_add_u32 s79, s79, 0x100
	s_addc_u32 s80, s80, 0
	s_add_u32 s30, s30, 0x100
	s_addc_u32 s31, s31, 0
	s_add_u32 s81, s81, 0x100
	s_addc_u32 s82, s82, 0
	s_cmp_gt_u32 s83, 29
	s_cbranch_scc0 .LBB0_1538
	s_and_b64 vcc, exec, s[16:17]
	s_cbranch_vccz .LBB0_1541
	s_barrier

.LBB0_1785:
	s_cmp_eq_u32 s73, 28
	s_cselect_b32 s21, s9, s67
	s_cselect_b32 s20, s65, s66
	s_cselect_b32 s23, s11, s71
	s_cselect_b32 s22, s64, s70
	s_add_u32 s74, s18, 0xfff80000
	s_addc_u32 s75, s19, -1
	s_mov_b32 s76, m0
	s_mov_b32 m0, s56
	s_nop 0
	global_load_lds_dwordx4 v138, s[74:75]
	s_mov_b32 m0, s76
	s_nop 0
	s_mov_b32 s76, m0
	s_mov_b32 m0, s59
	s_nop 0
	global_load_lds_dwordx4 v140, s[74:75]
	s_mov_b32 m0, s76
	s_mov_b32 s74, m0
	s_mov_b32 m0, s57
	s_nop 0
	global_load_lds_dwordx4 v138, s[18:19]
	s_mov_b32 m0, s74
	s_nop 0
	s_mov_b32 s74, m0
	s_mov_b32 m0, s62
	s_nop 0
	global_load_lds_dwordx4 v140, s[18:19]
	s_mov_b32 m0, s74
	ds_read_b128 v[148:151], v143
	ds_read_b128 v[152:155], v143 offset:1024
	ds_read_b128 v[156:159], v143 offset:2048
	ds_read_b128 v[160:163], v143 offset:3072
	ds_read_b128 v[164:167], v144
	ds_read_b128 v[168:171], v144 offset:1024
	ds_read_b128 v[172:175], v144 offset:2048
	ds_read_b128 v[176:179], v144 offset:3072
	ds_read_b128 v[180:183], v145
	ds_read_b128 v[184:187], v145 offset:1024
	ds_read_b128 v[188:191], v145 offset:2048
	ds_read_b128 v[192:195], v145 offset:3072
	ds_read_b128 v[196:199], v145 offset:4096
	ds_read_b128 v[200:203], v145 offset:5120
	ds_read_b128 v[204:207], v145 offset:6144
	ds_read_b128 v[208:211], v145 offset:7168
	s_waitcnt vmcnt(8)
	s_waitcnt lgkmcnt(0)
	s_barrier
	s_setprio 1
	s_waitcnt lgkmcnt(7)
	v_mfma_f32_16x16x32_bf16 v[126:129], v[148:151], v[180:183], v[126:129]
	v_mfma_f32_16x16x32_bf16 v[122:125], v[156:159], v[180:183], v[122:125]
	s_waitcnt lgkmcnt(5)
	v_mfma_f32_16x16x32_bf16 v[110:113], v[148:151], v[188:191], v[110:113]
	v_mfma_f32_16x16x32_bf16 v[106:109], v[156:159], v[188:191], v[106:109]
	s_waitcnt lgkmcnt(3)
	v_mfma_f32_16x16x32_bf16 v[94:97], v[148:151], v[196:199], v[94:97]
	v_mfma_f32_16x16x32_bf16 v[90:93], v[156:159], v[196:199], v[90:93]
	s_waitcnt lgkmcnt(1)
	v_mfma_f32_16x16x32_bf16 v[78:81], v[148:151], v[204:207], v[78:81]
	v_mfma_f32_16x16x32_bf16 v[74:77], v[156:159], v[204:207], v[74:77]
	v_mfma_f32_16x16x32_bf16 v[126:129], v[152:155], v[184:187], v[126:129]
	v_mfma_f32_16x16x32_bf16 v[122:125], v[160:163], v[184:187], v[122:125]
	v_mfma_f32_16x16x32_bf16 v[110:113], v[152:155], v[192:195], v[110:113]
	v_mfma_f32_16x16x32_bf16 v[106:109], v[160:163], v[192:195], v[106:109]
	v_mfma_f32_16x16x32_bf16 v[94:97], v[152:155], v[200:203], v[94:97]
	v_mfma_f32_16x16x32_bf16 v[90:93], v[160:163], v[200:203], v[90:93]
	s_waitcnt lgkmcnt(0)
	v_mfma_f32_16x16x32_bf16 v[78:81], v[152:155], v[208:211], v[78:81]
	v_mfma_f32_16x16x32_bf16 v[74:77], v[160:163], v[208:211], v[74:77]
	s_setprio 0
	s_setprio 1
	v_mfma_f32_16x16x32_bf16 v[118:121], v[164:167], v[180:183], v[118:121]
	v_mfma_f32_16x16x32_bf16 v[114:117], v[172:175], v[180:183], v[114:117]
	v_mfma_f32_16x16x32_bf16 v[102:105], v[164:167], v[188:191], v[102:105]
	v_mfma_f32_16x16x32_bf16 v[98:101], v[172:175], v[188:191], v[98:101]
	v_mfma_f32_16x16x32_bf16 v[86:89], v[164:167], v[196:199], v[86:89]
	v_mfma_f32_16x16x32_bf16 v[82:85], v[172:175], v[196:199], v[82:85]
	v_mfma_f32_16x16x32_bf16 v[70:73], v[164:167], v[204:207], v[70:73]
	v_mfma_f32_16x16x32_bf16 v[66:69], v[172:175], v[204:207], v[66:69]
	v_mfma_f32_16x16x32_bf16 v[118:121], v[168:171], v[184:187], v[118:121]
	v_mfma_f32_16x16x32_bf16 v[114:117], v[176:179], v[184:187], v[114:117]
	v_mfma_f32_16x16x32_bf16 v[102:105], v[168:171], v[192:195], v[102:105]
	v_mfma_f32_16x16x32_bf16 v[98:101], v[176:179], v[192:195], v[98:101]
	v_mfma_f32_16x16x32_bf16 v[86:89], v[168:171], v[200:203], v[86:89]
	v_mfma_f32_16x16x32_bf16 v[82:85], v[176:179], v[200:203], v[82:85]
	s_setprio 2
	s_barrier
	v_mfma_f32_16x16x32_bf16 v[70:73], v[168:171], v[208:211], v[70:73]
	v_mfma_f32_16x16x32_bf16 v[66:69], v[176:179], v[208:211], v[66:69]
	s_setprio 0
	s_mov_b32 s74, m0
	s_mov_b32 m0, s35
	s_nop 0
	global_load_lds_dwordx4 v139, s[20:21]
	s_mov_b32 m0, s74
	s_nop 0
	s_mov_b32 s74, m0
	s_mov_b32 m0, s36
	s_nop 0
	global_load_lds_dwordx4 v141, s[20:21]
	s_mov_b32 m0, s74
	s_add_u32 s74, s20, 0x80000
	s_addc_u32 s75, s21, 0
	s_mov_b32 s76, m0
	s_mov_b32 m0, s37
	s_nop 0
	global_load_lds_dwordx4 v139, s[74:75]
	s_mov_b32 m0, s76
	s_nop 0
	s_mov_b32 s76, m0
	s_mov_b32 m0, s40
	s_nop 0
	global_load_lds_dwordx4 v141, s[74:75]
	s_mov_b32 m0, s76
	ds_read_b128 v[180:183], v145 offset:16384
	ds_read_b128 v[184:187], v145 offset:17408
	ds_read_b128 v[188:191], v145 offset:18432
	ds_read_b128 v[192:195], v145 offset:19456
	ds_read_b128 v[196:199], v145 offset:20480
	ds_read_b128 v[200:203], v145 offset:21504
	ds_read_b128 v[204:207], v145 offset:22528
	ds_read_b128 v[208:211], v145 offset:23552
	s_waitcnt vmcnt(4)
	s_waitcnt lgkmcnt(0)
	s_barrier
	s_setprio 1
	s_waitcnt lgkmcnt(7)
	v_mfma_f32_16x16x32_bf16 v[62:65], v[148:151], v[180:183], v[62:65]
	v_mfma_f32_16x16x32_bf16 v[58:61], v[156:159], v[180:183], v[58:61]
	s_waitcnt lgkmcnt(5)
	v_mfma_f32_16x16x32_bf16 v[46:49], v[148:151], v[188:191], v[46:49]
	v_mfma_f32_16x16x32_bf16 v[42:45], v[156:159], v[188:191], v[42:45]
	s_waitcnt lgkmcnt(3)
	v_mfma_f32_16x16x32_bf16 v[30:33], v[148:151], v[196:199], v[30:33]
	v_mfma_f32_16x16x32_bf16 v[26:29], v[156:159], v[196:199], v[26:29]
	s_waitcnt lgkmcnt(1)
	v_mfma_f32_16x16x32_bf16 v[14:17], v[148:151], v[204:207], v[14:17]
	v_mfma_f32_16x16x32_bf16 v[10:13], v[156:159], v[204:207], v[10:13]
	v_mfma_f32_16x16x32_bf16 v[62:65], v[152:155], v[184:187], v[62:65]
	v_mfma_f32_16x16x32_bf16 v[58:61], v[160:163], v[184:187], v[58:61]
	v_mfma_f32_16x16x32_bf16 v[46:49], v[152:155], v[192:195], v[46:49]
	v_mfma_f32_16x16x32_bf16 v[42:45], v[160:163], v[192:195], v[42:45]
	v_mfma_f32_16x16x32_bf16 v[30:33], v[152:155], v[200:203], v[30:33]
	v_mfma_f32_16x16x32_bf16 v[26:29], v[160:163], v[200:203], v[26:29]
	s_waitcnt lgkmcnt(0)
	v_mfma_f32_16x16x32_bf16 v[14:17], v[152:155], v[208:211], v[14:17]
	v_mfma_f32_16x16x32_bf16 v[10:13], v[160:163], v[208:211], v[10:13]
	s_setprio 0
	s_setprio 1
	v_mfma_f32_16x16x32_bf16 v[54:57], v[164:167], v[180:183], v[54:57]
	v_mfma_f32_16x16x32_bf16 v[50:53], v[172:175], v[180:183], v[50:53]
	v_mfma_f32_16x16x32_bf16 v[38:41], v[164:167], v[188:191], v[38:41]
	v_mfma_f32_16x16x32_bf16 v[34:37], v[172:175], v[188:191], v[34:37]
	v_mfma_f32_16x16x32_bf16 v[22:25], v[164:167], v[196:199], v[22:25]
	v_mfma_f32_16x16x32_bf16 v[18:21], v[172:175], v[196:199], v[18:21]
	v_mfma_f32_16x16x32_bf16 v[6:9], v[164:167], v[204:207], v[6:9]
	v_mfma_f32_16x16x32_bf16 v[2:5], v[172:175], v[204:207], v[2:5]
	v_mfma_f32_16x16x32_bf16 v[54:57], v[168:171], v[184:187], v[54:57]
	v_mfma_f32_16x16x32_bf16 v[50:53], v[176:179], v[184:187], v[50:53]
	v_mfma_f32_16x16x32_bf16 v[38:41], v[168:171], v[192:195], v[38:41]
	v_mfma_f32_16x16x32_bf16 v[34:37], v[176:179], v[192:195], v[34:37]
	v_mfma_f32_16x16x32_bf16 v[22:25], v[168:171], v[200:203], v[22:25]
	v_mfma_f32_16x16x32_bf16 v[18:21], v[176:179], v[200:203], v[18:21]
	s_setprio 2
	s_barrier
	v_mfma_f32_16x16x32_bf16 v[6:9], v[168:171], v[208:211], v[6:9]
	v_mfma_f32_16x16x32_bf16 v[2:5], v[176:179], v[208:211], v[2:5]
	s_setprio 0
	s_mov_b32 s74, m0
	s_mov_b32 m0, s31
	s_nop 0
	global_load_lds_dwordx4 v138, s[22:23]
	s_mov_b32 m0, s74
	s_nop 0
	s_mov_b32 s74, m0
	s_mov_b32 m0, s41
	s_nop 0
	global_load_lds_dwordx4 v140, s[22:23]
	s_mov_b32 m0, s74
	s_add_u32 s22, s22, 0x80000
	s_addc_u32 s23, s23, 0
	s_mov_b32 s74, m0
	s_mov_b32 m0, s42
	s_nop 0
	global_load_lds_dwordx4 v138, s[22:23]
	s_mov_b32 m0, s74
	s_nop 0
	s_mov_b32 s74, m0
	s_mov_b32 m0, s43
	s_nop 0
	global_load_lds_dwordx4 v140, s[22:23]
	s_mov_b32 m0, s74
	ds_read_b128 v[148:151], v146
	ds_read_b128 v[152:155], v146 offset:1024
	ds_read_b128 v[156:159], v146 offset:2048
	ds_read_b128 v[160:163], v146 offset:3072
	ds_read_b128 v[164:167], v147
	ds_read_b128 v[168:171], v147 offset:1024
	ds_read_b128 v[172:175], v147 offset:2048
	ds_read_b128 v[176:179], v147 offset:3072
	ds_read_b128 v[180:183], v145 offset:32768
	ds_read_b128 v[184:187], v145 offset:33792
	ds_read_b128 v[188:191], v145 offset:34816
	ds_read_b128 v[192:195], v145 offset:35840
	ds_read_b128 v[196:199], v145 offset:36864
	ds_read_b128 v[200:203], v145 offset:37888
	ds_read_b128 v[204:207], v145 offset:38912
	ds_read_b128 v[208:211], v145 offset:39936
	s_waitcnt vmcnt(8)
	s_waitcnt lgkmcnt(0)
	s_barrier
	s_setprio 1
	s_waitcnt lgkmcnt(7)
	v_mfma_f32_16x16x32_bf16 v[126:129], v[148:151], v[180:183], v[126:129]
	v_mfma_f32_16x16x32_bf16 v[122:125], v[156:159], v[180:183], v[122:125]
	s_waitcnt lgkmcnt(5)
	v_mfma_f32_16x16x32_bf16 v[110:113], v[148:151], v[188:191], v[110:113]
	v_mfma_f32_16x16x32_bf16 v[106:109], v[156:159], v[188:191], v[106:109]
	s_waitcnt lgkmcnt(3)
	v_mfma_f32_16x16x32_bf16 v[94:97], v[148:151], v[196:199], v[94:97]
	v_mfma_f32_16x16x32_bf16 v[90:93], v[156:159], v[196:199], v[90:93]
	s_waitcnt lgkmcnt(1)
	v_mfma_f32_16x16x32_bf16 v[78:81], v[148:151], v[204:207], v[78:81]
	v_mfma_f32_16x16x32_bf16 v[74:77], v[156:159], v[204:207], v[74:77]
	v_mfma_f32_16x16x32_bf16 v[126:129], v[152:155], v[184:187], v[126:129]
	v_mfma_f32_16x16x32_bf16 v[122:125], v[160:163], v[184:187], v[122:125]
	v_mfma_f32_16x16x32_bf16 v[110:113], v[152:155], v[192:195], v[110:113]
	v_mfma_f32_16x16x32_bf16 v[106:109], v[160:163], v[192:195], v[106:109]
	v_mfma_f32_16x16x32_bf16 v[94:97], v[152:155], v[200:203], v[94:97]
	v_mfma_f32_16x16x32_bf16 v[90:93], v[160:163], v[200:203], v[90:93]
	s_waitcnt lgkmcnt(0)
	v_mfma_f32_16x16x32_bf16 v[78:81], v[152:155], v[208:211], v[78:81]
	v_mfma_f32_16x16x32_bf16 v[74:77], v[160:163], v[208:211], v[74:77]
	s_setprio 0
	s_setprio 1
	v_mfma_f32_16x16x32_bf16 v[118:121], v[164:167], v[180:183], v[118:121]
	v_mfma_f32_16x16x32_bf16 v[114:117], v[172:175], v[180:183], v[114:117]
	v_mfma_f32_16x16x32_bf16 v[102:105], v[164:167], v[188:191], v[102:105]
	v_mfma_f32_16x16x32_bf16 v[98:101], v[172:175], v[188:191], v[98:101]
	v_mfma_f32_16x16x32_bf16 v[86:89], v[164:167], v[196:199], v[86:89]
	v_mfma_f32_16x16x32_bf16 v[82:85], v[172:175], v[196:199], v[82:85]
	v_mfma_f32_16x16x32_bf16 v[70:73], v[164:167], v[204:207], v[70:73]
	v_mfma_f32_16x16x32_bf16 v[66:69], v[172:175], v[204:207], v[66:69]
	v_mfma_f32_16x16x32_bf16 v[118:121], v[168:171], v[184:187], v[118:121]
	v_mfma_f32_16x16x32_bf16 v[114:117], v[176:179], v[184:187], v[114:117]
	v_mfma_f32_16x16x32_bf16 v[102:105], v[168:171], v[192:195], v[102:105]
	v_mfma_f32_16x16x32_bf16 v[98:101], v[176:179], v[192:195], v[98:101]
	v_mfma_f32_16x16x32_bf16 v[86:89], v[168:171], v[200:203], v[86:89]
	v_mfma_f32_16x16x32_bf16 v[82:85], v[176:179], v[200:203], v[82:85]
	s_setprio 2
	s_barrier
	v_mfma_f32_16x16x32_bf16 v[70:73], v[168:171], v[208:211], v[70:73]
	v_mfma_f32_16x16x32_bf16 v[66:69], v[176:179], v[208:211], v[66:69]
	s_setprio 0
	s_add_u32 s22, s20, 0x80
	s_addc_u32 s23, s21, 0
	s_mov_b32 s74, m0
	s_mov_b32 m0, s46
	s_nop 0
	global_load_lds_dwordx4 v139, s[22:23]
	s_mov_b32 m0, s74
	s_add_u32 s20, s20, 0x80080
	s_mov_b32 s74, m0
	s_mov_b32 m0, s47
	s_nop 0
	global_load_lds_dwordx4 v141, s[22:23]
	s_mov_b32 m0, s74
	s_addc_u32 s21, s21, 0
	s_mov_b32 s22, m0
	s_mov_b32 m0, s48
	s_nop 0
	global_load_lds_dwordx4 v139, s[20:21]
	s_mov_b32 m0, s22
	s_nop 0
	s_mov_b32 s22, m0
	s_mov_b32 m0, s49
	s_nop 0
	global_load_lds_dwordx4 v141, s[20:21]
	s_mov_b32 m0, s22
	ds_read_b128 v[180:183], v145 offset:49152
	ds_read_b128 v[184:187], v145 offset:50176
	ds_read_b128 v[188:191], v145 offset:51200
	ds_read_b128 v[192:195], v145 offset:52224
	ds_read_b128 v[196:199], v145 offset:53248
	ds_read_b128 v[200:203], v145 offset:54272
	ds_read_b128 v[204:207], v145 offset:55296
	ds_read_b128 v[208:211], v145 offset:56320
	s_waitcnt vmcnt(4)
	s_waitcnt lgkmcnt(0)
	s_barrier
	s_setprio 1
	s_waitcnt lgkmcnt(7)
	v_mfma_f32_16x16x32_bf16 v[62:65], v[148:151], v[180:183], v[62:65]
	v_mfma_f32_16x16x32_bf16 v[58:61], v[156:159], v[180:183], v[58:61]
	s_waitcnt lgkmcnt(5)
	v_mfma_f32_16x16x32_bf16 v[46:49], v[148:151], v[188:191], v[46:49]
	v_mfma_f32_16x16x32_bf16 v[42:45], v[156:159], v[188:191], v[42:45]
	s_waitcnt lgkmcnt(3)
	v_mfma_f32_16x16x32_bf16 v[30:33], v[148:151], v[196:199], v[30:33]
	v_mfma_f32_16x16x32_bf16 v[26:29], v[156:159], v[196:199], v[26:29]
	s_waitcnt lgkmcnt(1)
	v_mfma_f32_16x16x32_bf16 v[14:17], v[148:151], v[204:207], v[14:17]
	v_mfma_f32_16x16x32_bf16 v[10:13], v[156:159], v[204:207], v[10:13]
	v_mfma_f32_16x16x32_bf16 v[62:65], v[152:155], v[184:187], v[62:65]
	v_mfma_f32_16x16x32_bf16 v[58:61], v[160:163], v[184:187], v[58:61]
	v_mfma_f32_16x16x32_bf16 v[46:49], v[152:155], v[192:195], v[46:49]
	v_mfma_f32_16x16x32_bf16 v[42:45], v[160:163], v[192:195], v[42:45]
	v_mfma_f32_16x16x32_bf16 v[30:33], v[152:155], v[200:203], v[30:33]
	v_mfma_f32_16x16x32_bf16 v[26:29], v[160:163], v[200:203], v[26:29]
	s_waitcnt lgkmcnt(0)
	v_mfma_f32_16x16x32_bf16 v[14:17], v[152:155], v[208:211], v[14:17]
	v_mfma_f32_16x16x32_bf16 v[10:13], v[160:163], v[208:211], v[10:13]
	s_setprio 0
	s_setprio 1
	v_mfma_f32_16x16x32_bf16 v[54:57], v[164:167], v[180:183], v[54:57]
	v_mfma_f32_16x16x32_bf16 v[50:53], v[172:175], v[180:183], v[50:53]
	v_mfma_f32_16x16x32_bf16 v[38:41], v[164:167], v[188:191], v[38:41]
	v_mfma_f32_16x16x32_bf16 v[34:37], v[172:175], v[188:191], v[34:37]
	v_mfma_f32_16x16x32_bf16 v[22:25], v[164:167], v[196:199], v[22:25]
	v_mfma_f32_16x16x32_bf16 v[18:21], v[172:175], v[196:199], v[18:21]
	v_mfma_f32_16x16x32_bf16 v[6:9], v[164:167], v[204:207], v[6:9]
	v_mfma_f32_16x16x32_bf16 v[2:5], v[172:175], v[204:207], v[2:5]
	v_mfma_f32_16x16x32_bf16 v[54:57], v[168:171], v[184:187], v[54:57]
	v_mfma_f32_16x16x32_bf16 v[50:53], v[176:179], v[184:187], v[50:53]
	v_mfma_f32_16x16x32_bf16 v[38:41], v[168:171], v[192:195], v[38:41]
	v_mfma_f32_16x16x32_bf16 v[34:37], v[176:179], v[192:195], v[34:37]
	v_mfma_f32_16x16x32_bf16 v[22:25], v[168:171], v[200:203], v[22:25]
	v_mfma_f32_16x16x32_bf16 v[18:21], v[176:179], v[200:203], v[18:21]
	s_setprio 2
	s_barrier
	v_mfma_f32_16x16x32_bf16 v[6:9], v[168:171], v[208:211], v[6:9]
	v_mfma_f32_16x16x32_bf16 v[2:5], v[176:179], v[208:211], v[2:5]
	s_setprio 0
	s_add_i32 s73, s73, 2
	s_add_u32 s66, s66, 0x100
	s_addc_u32 s67, s67, 0
	s_add_u32 s18, s18, 0x100
	s_addc_u32 s19, s19, 0
	s_add_u32 s70, s70, 0x100
	s_addc_u32 s71, s71, 0
	s_cmp_gt_u32 s73, 29
	s_cbranch_scc0 .LBB0_1785
	s_and_b64 vcc, exec, s[6:7]
	s_cbranch_vccz .LBB0_1788
	s_barrier

.LBB0_1952:
	s_cmpk_eq_i32 s74, 0x52
	s_cselect_b32 s23, s11, s70
	s_cselect_b32 s22, s66, s67
	s_cselect_b32 s25, s13, s73
	s_cselect_b32 s24, s65, s71
	s_add_u32 s76, s20, 0xffffc000
	s_addc_u32 s77, s21, -1
	s_mov_b32 s75, m0
	s_mov_b32 m0, s58
	s_nop 0
	global_load_lds_dwordx4 v1, s[76:77]
	s_mov_b32 m0, s75
	s_nop 0
	s_mov_b32 s75, m0
	s_mov_b32 m0, s62
	s_nop 0
	global_load_lds_dwordx4 v177, s[76:77]
	s_mov_b32 m0, s75
	s_nop 0
	s_mov_b32 s75, m0
	s_mov_b32 m0, s59
	s_nop 0
	global_load_lds_dwordx4 v1, s[20:21]
	s_mov_b32 m0, s75
	s_nop 0
	s_mov_b32 s75, m0
	s_mov_b32 m0, s63
	s_nop 0
	global_load_lds_dwordx4 v177, s[20:21]
	s_mov_b32 m0, s75
	ds_read_b128 v[130:133], v181
	ds_read_b128 v[134:137], v181 offset:1024
	ds_read_b128 v[138:141], v181 offset:2048
	ds_read_b128 v[142:145], v181 offset:3072
	ds_read_b128 v[150:153], v182
	ds_read_b128 v[154:157], v182 offset:1024
	ds_read_b128 v[158:161], v182 offset:2048
	ds_read_b128 v[162:165], v182 offset:3072
	ds_read_b128 v[166:169], v183
	ds_read_b128 v[170:173], v183 offset:1024
	ds_read_b128 v[186:189], v183 offset:2048
	ds_read_b128 v[190:193], v183 offset:3072
	ds_read_b128 v[194:197], v183 offset:4096
	ds_read_b128 v[198:201], v183 offset:5120
	ds_read_b128 v[202:205], v183 offset:6144
	ds_read_b128 v[206:209], v183 offset:7168
	s_waitcnt vmcnt(8)
	s_waitcnt lgkmcnt(0)
	s_barrier
	s_setprio 1
	s_waitcnt lgkmcnt(7)
	v_mfma_f32_16x16x32_bf16 v[126:129], v[130:133], v[166:169], v[126:129]
	v_mfma_f32_16x16x32_bf16 v[122:125], v[138:141], v[166:169], v[122:125]
	s_waitcnt lgkmcnt(5)
	v_mfma_f32_16x16x32_bf16 v[118:121], v[130:133], v[186:189], v[118:121]
	v_mfma_f32_16x16x32_bf16 v[110:113], v[138:141], v[186:189], v[110:113]
	s_waitcnt lgkmcnt(3)
	v_mfma_f32_16x16x32_bf16 v[94:97], v[130:133], v[194:197], v[94:97]
	v_mfma_f32_16x16x32_bf16 v[90:93], v[138:141], v[194:197], v[90:93]
	s_waitcnt lgkmcnt(1)
	v_mfma_f32_16x16x32_bf16 v[86:89], v[130:133], v[202:205], v[86:89]
	v_mfma_f32_16x16x32_bf16 v[78:81], v[138:141], v[202:205], v[78:81]
	v_mfma_f32_16x16x32_bf16 v[126:129], v[134:137], v[170:173], v[126:129]
	v_mfma_f32_16x16x32_bf16 v[122:125], v[142:145], v[170:173], v[122:125]
	v_mfma_f32_16x16x32_bf16 v[118:121], v[134:137], v[190:193], v[118:121]
	v_mfma_f32_16x16x32_bf16 v[110:113], v[142:145], v[190:193], v[110:113]
	v_mfma_f32_16x16x32_bf16 v[94:97], v[134:137], v[198:201], v[94:97]
	v_mfma_f32_16x16x32_bf16 v[90:93], v[142:145], v[198:201], v[90:93]
	s_waitcnt lgkmcnt(0)
	v_mfma_f32_16x16x32_bf16 v[86:89], v[134:137], v[206:209], v[86:89]
	v_mfma_f32_16x16x32_bf16 v[78:81], v[142:145], v[206:209], v[78:81]
	s_setprio 0
	s_setprio 1
	v_mfma_f32_16x16x32_bf16 v[114:117], v[150:153], v[166:169], v[114:117]
	v_mfma_f32_16x16x32_bf16 v[106:109], v[158:161], v[166:169], v[106:109]
	v_mfma_f32_16x16x32_bf16 v[102:105], v[150:153], v[186:189], v[102:105]
	v_mfma_f32_16x16x32_bf16 v[98:101], v[158:161], v[186:189], v[98:101]
	v_mfma_f32_16x16x32_bf16 v[82:85], v[150:153], v[194:197], v[82:85]
	v_mfma_f32_16x16x32_bf16 v[74:77], v[158:161], v[194:197], v[74:77]
	v_mfma_f32_16x16x32_bf16 v[70:73], v[150:153], v[202:205], v[70:73]
	v_mfma_f32_16x16x32_bf16 v[66:69], v[158:161], v[202:205], v[66:69]
	v_mfma_f32_16x16x32_bf16 v[114:117], v[154:157], v[170:173], v[114:117]
	v_mfma_f32_16x16x32_bf16 v[106:109], v[162:165], v[170:173], v[106:109]
	v_mfma_f32_16x16x32_bf16 v[102:105], v[154:157], v[190:193], v[102:105]
	v_mfma_f32_16x16x32_bf16 v[98:101], v[162:165], v[190:193], v[98:101]
	v_mfma_f32_16x16x32_bf16 v[82:85], v[154:157], v[198:201], v[82:85]
	v_mfma_f32_16x16x32_bf16 v[74:77], v[162:165], v[198:201], v[74:77]
	s_setprio 2
	s_barrier
	v_mfma_f32_16x16x32_bf16 v[70:73], v[154:157], v[206:209], v[70:73]
	v_mfma_f32_16x16x32_bf16 v[66:69], v[162:165], v[206:209], v[66:69]
	s_setprio 0
	s_mov_b32 s75, m0
	s_mov_b32 m0, s35
	s_nop 0
	global_load_lds_dwordx4 v176, s[22:23]
	s_mov_b32 m0, s75
	s_add_u32 s76, s22, 0x4000
	s_mov_b32 s75, m0
	s_mov_b32 m0, s36
	s_nop 0
	global_load_lds_dwordx4 v178, s[22:23]
	s_mov_b32 m0, s75
	s_addc_u32 s77, s23, 0
	s_mov_b32 s75, m0
	s_mov_b32 m0, s37
	s_nop 0
	global_load_lds_dwordx4 v176, s[76:77]
	s_mov_b32 m0, s75
	s_nop 0
	s_mov_b32 s75, m0
	s_mov_b32 m0, s40
	s_nop 0
	global_load_lds_dwordx4 v178, s[76:77]
	s_mov_b32 m0, s75
	ds_read_b128 v[166:169], v183 offset:16384
	ds_read_b128 v[170:173], v183 offset:17408
	ds_read_b128 v[186:189], v183 offset:18432
	ds_read_b128 v[190:193], v183 offset:19456
	ds_read_b128 v[194:197], v183 offset:20480
	ds_read_b128 v[198:201], v183 offset:21504
	ds_read_b128 v[202:205], v183 offset:22528
	ds_read_b128 v[206:209], v183 offset:23552
	s_waitcnt vmcnt(4)
	s_waitcnt lgkmcnt(0)
	s_barrier
	s_setprio 1
	s_waitcnt lgkmcnt(7)
	v_mfma_f32_16x16x32_bf16 v[62:65], v[130:133], v[166:169], v[62:65]
	v_mfma_f32_16x16x32_bf16 v[58:61], v[138:141], v[166:169], v[58:61]
	s_waitcnt lgkmcnt(5)
	v_mfma_f32_16x16x32_bf16 v[46:49], v[130:133], v[186:189], v[46:49]
	v_mfma_f32_16x16x32_bf16 v[42:45], v[138:141], v[186:189], v[42:45]
	s_waitcnt lgkmcnt(3)
	v_mfma_f32_16x16x32_bf16 v[30:33], v[130:133], v[194:197], v[30:33]
	v_mfma_f32_16x16x32_bf16 v[26:29], v[138:141], v[194:197], v[26:29]
	s_waitcnt lgkmcnt(1)
	v_mfma_f32_16x16x32_bf16 v[14:17], v[130:133], v[202:205], v[14:17]
	v_mfma_f32_16x16x32_bf16 v[10:13], v[138:141], v[202:205], v[10:13]
	v_mfma_f32_16x16x32_bf16 v[62:65], v[134:137], v[170:173], v[62:65]
	v_mfma_f32_16x16x32_bf16 v[58:61], v[142:145], v[170:173], v[58:61]
	v_mfma_f32_16x16x32_bf16 v[46:49], v[134:137], v[190:193], v[46:49]
	v_mfma_f32_16x16x32_bf16 v[42:45], v[142:145], v[190:193], v[42:45]
	v_mfma_f32_16x16x32_bf16 v[30:33], v[134:137], v[198:201], v[30:33]
	v_mfma_f32_16x16x32_bf16 v[26:29], v[142:145], v[198:201], v[26:29]
	s_waitcnt lgkmcnt(0)
	v_mfma_f32_16x16x32_bf16 v[14:17], v[134:137], v[206:209], v[14:17]
	v_mfma_f32_16x16x32_bf16 v[10:13], v[142:145], v[206:209], v[10:13]
	s_setprio 0
	s_setprio 1
	v_mfma_f32_16x16x32_bf16 v[54:57], v[150:153], v[166:169], v[54:57]
	v_mfma_f32_16x16x32_bf16 v[50:53], v[158:161], v[166:169], v[50:53]
	v_mfma_f32_16x16x32_bf16 v[38:41], v[150:153], v[186:189], v[38:41]
	v_mfma_f32_16x16x32_bf16 v[34:37], v[158:161], v[186:189], v[34:37]
	v_mfma_f32_16x16x32_bf16 v[22:25], v[150:153], v[194:197], v[22:25]
	v_mfma_f32_16x16x32_bf16 v[18:21], v[158:161], v[194:197], v[18:21]
	v_mfma_f32_16x16x32_bf16 v[6:9], v[150:153], v[202:205], v[6:9]
	v_mfma_f32_16x16x32_bf16 v[2:5], v[158:161], v[202:205], v[2:5]
	v_mfma_f32_16x16x32_bf16 v[54:57], v[154:157], v[170:173], v[54:57]
	v_mfma_f32_16x16x32_bf16 v[50:53], v[162:165], v[170:173], v[50:53]
	v_mfma_f32_16x16x32_bf16 v[38:41], v[154:157], v[190:193], v[38:41]
	v_mfma_f32_16x16x32_bf16 v[34:37], v[162:165], v[190:193], v[34:37]
	v_mfma_f32_16x16x32_bf16 v[22:25], v[154:157], v[198:201], v[22:25]
	v_mfma_f32_16x16x32_bf16 v[18:21], v[162:165], v[198:201], v[18:21]
	s_setprio 2
	s_barrier
	v_mfma_f32_16x16x32_bf16 v[6:9], v[154:157], v[206:209], v[6:9]
	v_mfma_f32_16x16x32_bf16 v[2:5], v[162:165], v[206:209], v[2:5]
	s_setprio 0
	s_mov_b32 s75, m0
	s_mov_b32 m0, s34
	s_nop 0
	global_load_lds_dwordx4 v1, s[24:25]
	s_mov_b32 m0, s75
	s_nop 0
	s_mov_b32 s75, m0
	s_mov_b32 m0, s41
	s_nop 0
	global_load_lds_dwordx4 v177, s[24:25]
	s_mov_b32 m0, s75
	s_add_u32 s24, s24, 0x4000
	s_addc_u32 s25, s25, 0
	s_mov_b32 s75, m0
	s_mov_b32 m0, s42
	s_nop 0
	global_load_lds_dwordx4 v1, s[24:25]
	s_mov_b32 m0, s75
	s_nop 0
	s_mov_b32 s75, m0
	s_mov_b32 m0, s43
	s_nop 0
	global_load_lds_dwordx4 v177, s[24:25]
	s_mov_b32 m0, s75
	ds_read_b128 v[130:133], v184
	ds_read_b128 v[134:137], v184 offset:1024
	ds_read_b128 v[138:141], v184 offset:2048
	ds_read_b128 v[142:145], v184 offset:3072
	ds_read_b128 v[150:153], v185
	ds_read_b128 v[154:157], v185 offset:1024
	ds_read_b128 v[158:161], v185 offset:2048
	ds_read_b128 v[162:165], v185 offset:3072
	ds_read_b128 v[166:169], v183 offset:32768
	ds_read_b128 v[170:173], v183 offset:33792
	ds_read_b128 v[186:189], v183 offset:34816
	ds_read_b128 v[190:193], v183 offset:35840
	ds_read_b128 v[194:197], v183 offset:36864
	ds_read_b128 v[198:201], v183 offset:37888
	ds_read_b128 v[202:205], v183 offset:38912
	ds_read_b128 v[206:209], v183 offset:39936
	s_waitcnt vmcnt(8)
	s_waitcnt lgkmcnt(0)
	s_barrier
	s_setprio 1
	s_waitcnt lgkmcnt(7)
	v_mfma_f32_16x16x32_bf16 v[126:129], v[130:133], v[166:169], v[126:129]
	v_mfma_f32_16x16x32_bf16 v[122:125], v[138:141], v[166:169], v[122:125]
	s_waitcnt lgkmcnt(5)
	v_mfma_f32_16x16x32_bf16 v[118:121], v[130:133], v[186:189], v[118:121]
	v_mfma_f32_16x16x32_bf16 v[110:113], v[138:141], v[186:189], v[110:113]
	s_waitcnt lgkmcnt(3)
	v_mfma_f32_16x16x32_bf16 v[94:97], v[130:133], v[194:197], v[94:97]
	v_mfma_f32_16x16x32_bf16 v[90:93], v[138:141], v[194:197], v[90:93]
	s_waitcnt lgkmcnt(1)
	v_mfma_f32_16x16x32_bf16 v[86:89], v[130:133], v[202:205], v[86:89]
	v_mfma_f32_16x16x32_bf16 v[78:81], v[138:141], v[202:205], v[78:81]
	v_mfma_f32_16x16x32_bf16 v[126:129], v[134:137], v[170:173], v[126:129]
	v_mfma_f32_16x16x32_bf16 v[122:125], v[142:145], v[170:173], v[122:125]
	v_mfma_f32_16x16x32_bf16 v[118:121], v[134:137], v[190:193], v[118:121]
	v_mfma_f32_16x16x32_bf16 v[110:113], v[142:145], v[190:193], v[110:113]
	v_mfma_f32_16x16x32_bf16 v[94:97], v[134:137], v[198:201], v[94:97]
	v_mfma_f32_16x16x32_bf16 v[90:93], v[142:145], v[198:201], v[90:93]
	s_waitcnt lgkmcnt(0)
	v_mfma_f32_16x16x32_bf16 v[86:89], v[134:137], v[206:209], v[86:89]
	v_mfma_f32_16x16x32_bf16 v[78:81], v[142:145], v[206:209], v[78:81]
	s_setprio 0
	s_setprio 1
	v_mfma_f32_16x16x32_bf16 v[114:117], v[150:153], v[166:169], v[114:117]
	v_mfma_f32_16x16x32_bf16 v[106:109], v[158:161], v[166:169], v[106:109]
	v_mfma_f32_16x16x32_bf16 v[102:105], v[150:153], v[186:189], v[102:105]
	v_mfma_f32_16x16x32_bf16 v[98:101], v[158:161], v[186:189], v[98:101]
	v_mfma_f32_16x16x32_bf16 v[82:85], v[150:153], v[194:197], v[82:85]
	v_mfma_f32_16x16x32_bf16 v[74:77], v[158:161], v[194:197], v[74:77]
	v_mfma_f32_16x16x32_bf16 v[70:73], v[150:153], v[202:205], v[70:73]
	v_mfma_f32_16x16x32_bf16 v[66:69], v[158:161], v[202:205], v[66:69]
	v_mfma_f32_16x16x32_bf16 v[114:117], v[154:157], v[170:173], v[114:117]
	v_mfma_f32_16x16x32_bf16 v[106:109], v[162:165], v[170:173], v[106:109]
	v_mfma_f32_16x16x32_bf16 v[102:105], v[154:157], v[190:193], v[102:105]
	v_mfma_f32_16x16x32_bf16 v[98:101], v[162:165], v[190:193], v[98:101]
	v_mfma_f32_16x16x32_bf16 v[82:85], v[154:157], v[198:201], v[82:85]
	v_mfma_f32_16x16x32_bf16 v[74:77], v[162:165], v[198:201], v[74:77]
	s_setprio 2
	s_barrier
	v_mfma_f32_16x16x32_bf16 v[70:73], v[154:157], v[206:209], v[70:73]
	v_mfma_f32_16x16x32_bf16 v[66:69], v[162:165], v[206:209], v[66:69]
	s_setprio 0
	s_add_u32 s24, s22, 0x40000
	s_addc_u32 s25, s23, 0
	s_mov_b32 s75, m0
	s_mov_b32 m0, s46
	s_nop 0
	global_load_lds_dwordx4 v176, s[24:25]
	s_mov_b32 m0, s75
	s_add_u32 s22, s22, 0x44000
	s_mov_b32 s75, m0
	s_mov_b32 m0, s47
	s_nop 0
	global_load_lds_dwordx4 v178, s[24:25]
	s_mov_b32 m0, s75
	s_addc_u32 s23, s23, 0
	s_mov_b32 s24, m0
	s_mov_b32 m0, s48
	s_nop 0
	global_load_lds_dwordx4 v176, s[22:23]
	s_mov_b32 m0, s24
	s_nop 0
	s_mov_b32 s24, m0
	s_mov_b32 m0, s49
	s_nop 0
	global_load_lds_dwordx4 v178, s[22:23]
	s_mov_b32 m0, s24
	ds_read_b128 v[166:169], v183 offset:49152
	ds_read_b128 v[170:173], v183 offset:50176
	ds_read_b128 v[186:189], v183 offset:51200
	ds_read_b128 v[190:193], v183 offset:52224
	ds_read_b128 v[194:197], v183 offset:53248
	ds_read_b128 v[198:201], v183 offset:54272
	ds_read_b128 v[202:205], v183 offset:55296
	ds_read_b128 v[206:209], v183 offset:56320
	s_waitcnt vmcnt(4)
	s_waitcnt lgkmcnt(0)
	s_barrier
	s_setprio 1
	s_waitcnt lgkmcnt(7)
	v_mfma_f32_16x16x32_bf16 v[62:65], v[130:133], v[166:169], v[62:65]
	v_mfma_f32_16x16x32_bf16 v[58:61], v[138:141], v[166:169], v[58:61]
	s_waitcnt lgkmcnt(5)
	v_mfma_f32_16x16x32_bf16 v[46:49], v[130:133], v[186:189], v[46:49]
	v_mfma_f32_16x16x32_bf16 v[42:45], v[138:141], v[186:189], v[42:45]
	s_waitcnt lgkmcnt(3)
	v_mfma_f32_16x16x32_bf16 v[30:33], v[130:133], v[194:197], v[30:33]
	v_mfma_f32_16x16x32_bf16 v[26:29], v[138:141], v[194:197], v[26:29]
	s_waitcnt lgkmcnt(1)
	v_mfma_f32_16x16x32_bf16 v[14:17], v[130:133], v[202:205], v[14:17]
	v_mfma_f32_16x16x32_bf16 v[10:13], v[138:141], v[202:205], v[10:13]
	v_mfma_f32_16x16x32_bf16 v[62:65], v[134:137], v[170:173], v[62:65]
	v_mfma_f32_16x16x32_bf16 v[58:61], v[142:145], v[170:173], v[58:61]
	v_mfma_f32_16x16x32_bf16 v[46:49], v[134:137], v[190:193], v[46:49]
	v_mfma_f32_16x16x32_bf16 v[42:45], v[142:145], v[190:193], v[42:45]
	v_mfma_f32_16x16x32_bf16 v[30:33], v[134:137], v[198:201], v[30:33]
	v_mfma_f32_16x16x32_bf16 v[26:29], v[142:145], v[198:201], v[26:29]
	s_waitcnt lgkmcnt(0)
	v_mfma_f32_16x16x32_bf16 v[14:17], v[134:137], v[206:209], v[14:17]
	v_mfma_f32_16x16x32_bf16 v[10:13], v[142:145], v[206:209], v[10:13]
	s_setprio 0
	s_setprio 1
	v_mfma_f32_16x16x32_bf16 v[54:57], v[150:153], v[166:169], v[54:57]
	v_mfma_f32_16x16x32_bf16 v[50:53], v[158:161], v[166:169], v[50:53]
	v_mfma_f32_16x16x32_bf16 v[38:41], v[150:153], v[186:189], v[38:41]
	v_mfma_f32_16x16x32_bf16 v[34:37], v[158:161], v[186:189], v[34:37]
	v_mfma_f32_16x16x32_bf16 v[22:25], v[150:153], v[194:197], v[22:25]
	v_mfma_f32_16x16x32_bf16 v[18:21], v[158:161], v[194:197], v[18:21]
	v_mfma_f32_16x16x32_bf16 v[6:9], v[150:153], v[202:205], v[6:9]
	v_mfma_f32_16x16x32_bf16 v[2:5], v[158:161], v[202:205], v[2:5]
	v_mfma_f32_16x16x32_bf16 v[54:57], v[154:157], v[170:173], v[54:57]
	v_mfma_f32_16x16x32_bf16 v[50:53], v[162:165], v[170:173], v[50:53]
	v_mfma_f32_16x16x32_bf16 v[38:41], v[154:157], v[190:193], v[38:41]
	v_mfma_f32_16x16x32_bf16 v[34:37], v[162:165], v[190:193], v[34:37]
	v_mfma_f32_16x16x32_bf16 v[22:25], v[154:157], v[198:201], v[22:25]
	v_mfma_f32_16x16x32_bf16 v[18:21], v[162:165], v[198:201], v[18:21]
	s_setprio 2
	s_barrier
	v_mfma_f32_16x16x32_bf16 v[6:9], v[154:157], v[206:209], v[6:9]
	v_mfma_f32_16x16x32_bf16 v[2:5], v[162:165], v[206:209], v[2:5]
	s_setprio 0
	s_add_i32 s74, s74, 2
	s_add_u32 s67, s67, 0x80000
	s_addc_u32 s70, s70, 0
	s_add_u32 s20, s20, 0x400000
	s_addc_u32 s21, s21, 0
	s_add_u32 s71, s71, 0x400000
	s_addc_u32 s73, s73, 0
	s_cmpk_gt_u32 s74, 0x53
	s_cbranch_scc0 .LBB0_1952
	s_and_b64 vcc, exec, s[8:9]
	s_cbranch_vccz .LBB0_1955
	s_barrier

.LBB0_2146:
	s_cmp_eq_u32 s81, 28
	s_cselect_b32 s37, s23, s78
	s_cselect_b32 s36, s31, s77
	s_cselect_b32 s41, s5, s80
	s_cselect_b32 s40, s25, s79
	s_add_u32 s82, s34, 0xfff80000
	s_addc_u32 s83, s35, -1
	s_mov_b32 s86, m0
	s_mov_b32 m0, s70
	s_nop 0
	global_load_lds_dwordx4 v1, s[82:83]
	s_mov_b32 m0, s86
	s_nop 0
	s_mov_b32 s86, m0
	s_mov_b32 m0, s73
	s_nop 0
	global_load_lds_dwordx4 v177, s[82:83]
	s_mov_b32 m0, s86
	s_mov_b32 s82, m0
	s_mov_b32 m0, s71
	s_nop 0
	global_load_lds_dwordx4 v1, s[34:35]
	s_mov_b32 m0, s82
	s_nop 0
	s_mov_b32 s82, m0
	s_mov_b32 m0, s74
	s_nop 0
	global_load_lds_dwordx4 v177, s[34:35]
	s_mov_b32 m0, s82
	ds_read_b128 v[42:45], v181
	ds_read_b128 v[46:49], v181 offset:1024
	ds_read_b128 v[58:61], v181 offset:2048
	ds_read_b128 v[62:65], v181 offset:3072
	ds_read_b128 v[146:149], v182
	ds_read_b128 v[150:153], v182 offset:1024
	ds_read_b128 v[154:157], v182 offset:2048
	ds_read_b128 v[158:161], v182 offset:3072
	ds_read_b128 v[170:173], v183
	ds_read_b128 v[188:191], v183 offset:1024
	ds_read_b128 v[192:195], v183 offset:2048
	ds_read_b128 v[196:199], v183 offset:3072
	ds_read_b128 v[200:203], v183 offset:4096
	ds_read_b128 v[204:207], v183 offset:5120
	ds_read_b128 v[208:211], v183 offset:6144
	ds_read_b128 v[212:215], v183 offset:7168
	s_waitcnt vmcnt(8)
	s_waitcnt lgkmcnt(0)
	s_barrier
	s_setprio 1
	s_waitcnt lgkmcnt(7)
	v_mfma_f32_16x16x32_bf16 v[142:145], v[42:45], v[170:173], v[142:145]
	v_mfma_f32_16x16x32_bf16 v[138:141], v[58:61], v[170:173], v[138:141]
	s_waitcnt lgkmcnt(5)
	v_mfma_f32_16x16x32_bf16 v[126:129], v[42:45], v[192:195], v[126:129]
	v_mfma_f32_16x16x32_bf16 v[122:125], v[58:61], v[192:195], v[122:125]
	s_waitcnt lgkmcnt(3)
	v_mfma_f32_16x16x32_bf16 v[110:113], v[42:45], v[200:203], v[110:113]
	v_mfma_f32_16x16x32_bf16 v[106:109], v[58:61], v[200:203], v[106:109]
	s_waitcnt lgkmcnt(1)
	v_mfma_f32_16x16x32_bf16 v[94:97], v[42:45], v[208:211], v[94:97]
	v_mfma_f32_16x16x32_bf16 v[90:93], v[58:61], v[208:211], v[90:93]
	v_mfma_f32_16x16x32_bf16 v[142:145], v[46:49], v[188:191], v[142:145]
	v_mfma_f32_16x16x32_bf16 v[138:141], v[62:65], v[188:191], v[138:141]
	v_mfma_f32_16x16x32_bf16 v[126:129], v[46:49], v[196:199], v[126:129]
	v_mfma_f32_16x16x32_bf16 v[122:125], v[62:65], v[196:199], v[122:125]
	v_mfma_f32_16x16x32_bf16 v[110:113], v[46:49], v[204:207], v[110:113]
	v_mfma_f32_16x16x32_bf16 v[106:109], v[62:65], v[204:207], v[106:109]
	s_waitcnt lgkmcnt(0)
	v_mfma_f32_16x16x32_bf16 v[94:97], v[46:49], v[212:215], v[94:97]
	v_mfma_f32_16x16x32_bf16 v[90:93], v[62:65], v[212:215], v[90:93]
	s_setprio 0
	s_setprio 1
	v_mfma_f32_16x16x32_bf16 v[134:137], v[146:149], v[170:173], v[134:137]
	v_mfma_f32_16x16x32_bf16 v[130:133], v[154:157], v[170:173], v[130:133]
	v_mfma_f32_16x16x32_bf16 v[118:121], v[146:149], v[192:195], v[118:121]
	v_mfma_f32_16x16x32_bf16 v[114:117], v[154:157], v[192:195], v[114:117]
	v_mfma_f32_16x16x32_bf16 v[102:105], v[146:149], v[200:203], v[102:105]
	v_mfma_f32_16x16x32_bf16 v[98:101], v[154:157], v[200:203], v[98:101]
	v_mfma_f32_16x16x32_bf16 v[86:89], v[146:149], v[208:211], v[86:89]
	v_mfma_f32_16x16x32_bf16 v[82:85], v[154:157], v[208:211], v[82:85]
	v_mfma_f32_16x16x32_bf16 v[134:137], v[150:153], v[188:191], v[134:137]
	v_mfma_f32_16x16x32_bf16 v[130:133], v[158:161], v[188:191], v[130:133]
	v_mfma_f32_16x16x32_bf16 v[118:121], v[150:153], v[196:199], v[118:121]
	v_mfma_f32_16x16x32_bf16 v[114:117], v[158:161], v[196:199], v[114:117]
	v_mfma_f32_16x16x32_bf16 v[102:105], v[150:153], v[204:207], v[102:105]
	v_mfma_f32_16x16x32_bf16 v[98:101], v[158:161], v[204:207], v[98:101]
	s_setprio 2
	s_barrier
	v_mfma_f32_16x16x32_bf16 v[86:89], v[150:153], v[212:215], v[86:89]
	v_mfma_f32_16x16x32_bf16 v[82:85], v[158:161], v[212:215], v[82:85]
	s_setprio 0
	s_mov_b32 s82, m0
	s_mov_b32 m0, s49
	s_nop 0
	global_load_lds_dwordx4 v176, s[36:37]
	s_mov_b32 m0, s82
	s_nop 0
	s_mov_b32 s82, m0
	s_mov_b32 m0, s56
	s_nop 0
	global_load_lds_dwordx4 v178, s[36:37]
	s_mov_b32 m0, s82
	s_add_u32 s82, s36, 0x80000
	s_addc_u32 s83, s37, 0
	s_mov_b32 s86, m0
	s_mov_b32 m0, s57
	s_nop 0
	global_load_lds_dwordx4 v176, s[82:83]
	s_mov_b32 m0, s86
	s_nop 0
	s_mov_b32 s86, m0
	s_mov_b32 m0, s58
	s_nop 0
	global_load_lds_dwordx4 v178, s[82:83]
	s_mov_b32 m0, s86
	ds_read_b128 v[170:173], v183 offset:16384
	ds_read_b128 v[188:191], v183 offset:17408
	ds_read_b128 v[192:195], v183 offset:18432
	ds_read_b128 v[196:199], v183 offset:19456
	ds_read_b128 v[200:203], v183 offset:20480
	ds_read_b128 v[204:207], v183 offset:21504
	ds_read_b128 v[208:211], v183 offset:22528
	ds_read_b128 v[212:215], v183 offset:23552
	s_waitcnt vmcnt(4)
	s_waitcnt lgkmcnt(0)
	s_barrier
	s_setprio 1
	s_waitcnt lgkmcnt(7)
	v_mfma_f32_16x16x32_bf16 v[78:81], v[42:45], v[170:173], v[78:81]
	v_mfma_f32_16x16x32_bf16 v[74:77], v[58:61], v[170:173], v[74:77]
	s_waitcnt lgkmcnt(5)
	v_mfma_f32_16x16x32_bf16 v[54:57], v[42:45], v[192:195], v[54:57]
	v_mfma_f32_16x16x32_bf16 v[50:53], v[58:61], v[192:195], v[50:53]
	s_waitcnt lgkmcnt(3)
	v_mfma_f32_16x16x32_bf16 v[30:33], v[42:45], v[200:203], v[30:33]
	v_mfma_f32_16x16x32_bf16 v[26:29], v[58:61], v[200:203], v[26:29]
	s_waitcnt lgkmcnt(1)
	v_mfma_f32_16x16x32_bf16 v[14:17], v[42:45], v[208:211], v[14:17]
	v_mfma_f32_16x16x32_bf16 v[10:13], v[58:61], v[208:211], v[10:13]
	v_mfma_f32_16x16x32_bf16 v[78:81], v[46:49], v[188:191], v[78:81]
	v_mfma_f32_16x16x32_bf16 v[74:77], v[62:65], v[188:191], v[74:77]
	v_mfma_f32_16x16x32_bf16 v[54:57], v[46:49], v[196:199], v[54:57]
	v_mfma_f32_16x16x32_bf16 v[50:53], v[62:65], v[196:199], v[50:53]
	v_mfma_f32_16x16x32_bf16 v[30:33], v[46:49], v[204:207], v[30:33]
	v_mfma_f32_16x16x32_bf16 v[26:29], v[62:65], v[204:207], v[26:29]
	s_waitcnt lgkmcnt(0)
	v_mfma_f32_16x16x32_bf16 v[14:17], v[46:49], v[212:215], v[14:17]
	v_mfma_f32_16x16x32_bf16 v[10:13], v[62:65], v[212:215], v[10:13]
	s_setprio 0
	s_setprio 1
	v_mfma_f32_16x16x32_bf16 v[38:41], v[146:149], v[192:195], v[38:41]
	v_mfma_f32_16x16x32_bf16 v[34:37], v[154:157], v[192:195], v[34:37]
	v_mfma_f32_16x16x32_bf16 v[22:25], v[146:149], v[200:203], v[22:25]
	v_mfma_f32_16x16x32_bf16 v[18:21], v[154:157], v[200:203], v[18:21]
	v_mfma_f32_16x16x32_bf16 v[6:9], v[146:149], v[208:211], v[6:9]
	v_mfma_f32_16x16x32_bf16 v[2:5], v[154:157], v[208:211], v[2:5]
	v_mfma_f32_16x16x32_bf16 v[42:45], v[146:149], v[170:173], v[70:73]
	v_mfma_f32_16x16x32_bf16 v[46:49], v[154:157], v[170:173], v[66:69]
	v_mfma_f32_16x16x32_bf16 v[38:41], v[150:153], v[196:199], v[38:41]
	v_mfma_f32_16x16x32_bf16 v[34:37], v[158:161], v[196:199], v[34:37]
	v_mfma_f32_16x16x32_bf16 v[22:25], v[150:153], v[204:207], v[22:25]
	v_mfma_f32_16x16x32_bf16 v[18:21], v[158:161], v[204:207], v[18:21]
	v_mfma_f32_16x16x32_bf16 v[6:9], v[150:153], v[212:215], v[6:9]
	v_mfma_f32_16x16x32_bf16 v[2:5], v[158:161], v[212:215], v[2:5]
	s_setprio 2
	s_barrier
	v_mfma_f32_16x16x32_bf16 v[42:45], v[150:153], v[188:191], v[42:45]
	v_mfma_f32_16x16x32_bf16 v[46:49], v[158:161], v[188:191], v[46:49]
	s_setprio 0
	s_mov_b32 s82, m0
	s_mov_b32 m0, s48
	s_nop 0
	global_load_lds_dwordx4 v1, s[40:41]
	s_mov_b32 m0, s82
	s_nop 0
	s_mov_b32 s82, m0
	s_mov_b32 m0, s59
	s_nop 0
	global_load_lds_dwordx4 v177, s[40:41]
	s_mov_b32 m0, s82
	s_add_u32 s40, s40, 0x80000
	s_addc_u32 s41, s41, 0
	s_mov_b32 s82, m0
	s_mov_b32 m0, s62
	s_nop 0
	global_load_lds_dwordx4 v1, s[40:41]
	s_mov_b32 m0, s82
	s_nop 0
	s_mov_b32 s82, m0
	s_mov_b32 m0, s63
	s_nop 0
	global_load_lds_dwordx4 v177, s[40:41]
	s_mov_b32 m0, s82
	ds_read_b128 v[58:61], v184
	ds_read_b128 v[62:65], v184 offset:1024
	ds_read_b128 v[66:69], v184 offset:2048
	ds_read_b128 v[70:73], v184 offset:3072
	ds_read_b128 v[146:149], v185
	ds_read_b128 v[150:153], v185 offset:1024
	ds_read_b128 v[154:157], v185 offset:2048
	ds_read_b128 v[158:161], v185 offset:3072
	ds_read_b128 v[170:173], v183 offset:32768
	ds_read_b128 v[188:191], v183 offset:33792
	ds_read_b128 v[192:195], v183 offset:34816
	ds_read_b128 v[196:199], v183 offset:35840
	ds_read_b128 v[200:203], v183 offset:36864
	ds_read_b128 v[204:207], v183 offset:37888
	ds_read_b128 v[208:211], v183 offset:38912
	ds_read_b128 v[212:215], v183 offset:39936
	s_waitcnt vmcnt(8)
	s_waitcnt lgkmcnt(0)
	s_barrier
	s_setprio 1
	s_waitcnt lgkmcnt(7)
	v_mfma_f32_16x16x32_bf16 v[142:145], v[58:61], v[170:173], v[142:145]
	v_mfma_f32_16x16x32_bf16 v[138:141], v[66:69], v[170:173], v[138:141]
	s_waitcnt lgkmcnt(5)
	v_mfma_f32_16x16x32_bf16 v[126:129], v[58:61], v[192:195], v[126:129]
	v_mfma_f32_16x16x32_bf16 v[122:125], v[66:69], v[192:195], v[122:125]
	s_waitcnt lgkmcnt(3)
	v_mfma_f32_16x16x32_bf16 v[110:113], v[58:61], v[200:203], v[110:113]
	v_mfma_f32_16x16x32_bf16 v[106:109], v[66:69], v[200:203], v[106:109]
	s_waitcnt lgkmcnt(1)
	v_mfma_f32_16x16x32_bf16 v[94:97], v[58:61], v[208:211], v[94:97]
	v_mfma_f32_16x16x32_bf16 v[90:93], v[66:69], v[208:211], v[90:93]
	v_mfma_f32_16x16x32_bf16 v[142:145], v[62:65], v[188:191], v[142:145]
	v_mfma_f32_16x16x32_bf16 v[138:141], v[70:73], v[188:191], v[138:141]
	v_mfma_f32_16x16x32_bf16 v[126:129], v[62:65], v[196:199], v[126:129]
	v_mfma_f32_16x16x32_bf16 v[122:125], v[70:73], v[196:199], v[122:125]
	v_mfma_f32_16x16x32_bf16 v[110:113], v[62:65], v[204:207], v[110:113]
	v_mfma_f32_16x16x32_bf16 v[106:109], v[70:73], v[204:207], v[106:109]
	s_waitcnt lgkmcnt(0)
	v_mfma_f32_16x16x32_bf16 v[94:97], v[62:65], v[212:215], v[94:97]
	v_mfma_f32_16x16x32_bf16 v[90:93], v[70:73], v[212:215], v[90:93]
	s_setprio 0
	s_setprio 1
	v_mfma_f32_16x16x32_bf16 v[134:137], v[146:149], v[170:173], v[134:137]
	v_mfma_f32_16x16x32_bf16 v[130:133], v[154:157], v[170:173], v[130:133]
	v_mfma_f32_16x16x32_bf16 v[118:121], v[146:149], v[192:195], v[118:121]
	v_mfma_f32_16x16x32_bf16 v[114:117], v[154:157], v[192:195], v[114:117]
	v_mfma_f32_16x16x32_bf16 v[102:105], v[146:149], v[200:203], v[102:105]
	v_mfma_f32_16x16x32_bf16 v[98:101], v[154:157], v[200:203], v[98:101]
	v_mfma_f32_16x16x32_bf16 v[86:89], v[146:149], v[208:211], v[86:89]
	v_mfma_f32_16x16x32_bf16 v[82:85], v[154:157], v[208:211], v[82:85]
	v_mfma_f32_16x16x32_bf16 v[134:137], v[150:153], v[188:191], v[134:137]
	v_mfma_f32_16x16x32_bf16 v[130:133], v[158:161], v[188:191], v[130:133]
	v_mfma_f32_16x16x32_bf16 v[118:121], v[150:153], v[196:199], v[118:121]
	v_mfma_f32_16x16x32_bf16 v[114:117], v[158:161], v[196:199], v[114:117]
	v_mfma_f32_16x16x32_bf16 v[102:105], v[150:153], v[204:207], v[102:105]
	v_mfma_f32_16x16x32_bf16 v[98:101], v[158:161], v[204:207], v[98:101]
	s_setprio 2
	s_barrier
	v_mfma_f32_16x16x32_bf16 v[86:89], v[150:153], v[212:215], v[86:89]
	v_mfma_f32_16x16x32_bf16 v[82:85], v[158:161], v[212:215], v[82:85]
	s_setprio 0
	s_add_u32 s40, s36, 0x80
	s_addc_u32 s41, s37, 0
	s_mov_b32 s82, m0
	s_mov_b32 m0, s64
	s_nop 0
	global_load_lds_dwordx4 v176, s[40:41]
	s_mov_b32 m0, s82
	s_add_u32 s36, s36, 0x80080
	s_mov_b32 s82, m0
	s_mov_b32 m0, s65
	s_nop 0
	global_load_lds_dwordx4 v178, s[40:41]
	s_mov_b32 m0, s82
	s_addc_u32 s37, s37, 0
	s_mov_b32 s40, m0
	s_mov_b32 m0, s66
	s_nop 0
	global_load_lds_dwordx4 v176, s[36:37]
	s_mov_b32 m0, s40
	s_nop 0
	s_mov_b32 s40, m0
	s_mov_b32 m0, s67
	s_nop 0
	global_load_lds_dwordx4 v178, s[36:37]
	s_mov_b32 m0, s40
	ds_read_b128 v[170:173], v183 offset:49152
	ds_read_b128 v[188:191], v183 offset:50176
	ds_read_b128 v[192:195], v183 offset:51200
	ds_read_b128 v[196:199], v183 offset:52224
	ds_read_b128 v[200:203], v183 offset:53248
	ds_read_b128 v[204:207], v183 offset:54272
	ds_read_b128 v[208:211], v183 offset:55296
	ds_read_b128 v[212:215], v183 offset:56320
	s_waitcnt vmcnt(4)
	s_waitcnt lgkmcnt(0)
	s_barrier
	s_setprio 1
	s_waitcnt lgkmcnt(7)
	v_mfma_f32_16x16x32_bf16 v[78:81], v[58:61], v[170:173], v[78:81]
	v_mfma_f32_16x16x32_bf16 v[74:77], v[66:69], v[170:173], v[74:77]
	s_waitcnt lgkmcnt(5)
	v_mfma_f32_16x16x32_bf16 v[54:57], v[58:61], v[192:195], v[54:57]
	v_mfma_f32_16x16x32_bf16 v[50:53], v[66:69], v[192:195], v[50:53]
	s_waitcnt lgkmcnt(3)
	v_mfma_f32_16x16x32_bf16 v[30:33], v[58:61], v[200:203], v[30:33]
	v_mfma_f32_16x16x32_bf16 v[26:29], v[66:69], v[200:203], v[26:29]
	s_waitcnt lgkmcnt(1)
	v_mfma_f32_16x16x32_bf16 v[14:17], v[58:61], v[208:211], v[14:17]
	v_mfma_f32_16x16x32_bf16 v[10:13], v[66:69], v[208:211], v[10:13]
	v_mfma_f32_16x16x32_bf16 v[78:81], v[62:65], v[188:191], v[78:81]
	v_mfma_f32_16x16x32_bf16 v[74:77], v[70:73], v[188:191], v[74:77]
	v_mfma_f32_16x16x32_bf16 v[54:57], v[62:65], v[196:199], v[54:57]
	v_mfma_f32_16x16x32_bf16 v[50:53], v[70:73], v[196:199], v[50:53]
	v_mfma_f32_16x16x32_bf16 v[30:33], v[62:65], v[204:207], v[30:33]
	v_mfma_f32_16x16x32_bf16 v[26:29], v[70:73], v[204:207], v[26:29]
	s_waitcnt lgkmcnt(0)
	v_mfma_f32_16x16x32_bf16 v[14:17], v[62:65], v[212:215], v[14:17]
	v_mfma_f32_16x16x32_bf16 v[10:13], v[70:73], v[212:215], v[10:13]
	s_setprio 0
	s_setprio 1
	v_mfma_f32_16x16x32_bf16 v[42:45], v[146:149], v[170:173], v[42:45]
	v_mfma_f32_16x16x32_bf16 v[70:73], v[150:153], v[188:191], v[42:45]
	v_mfma_f32_16x16x32_bf16 v[42:45], v[154:157], v[170:173], v[46:49]
	v_mfma_f32_16x16x32_bf16 v[38:41], v[146:149], v[192:195], v[38:41]
	v_mfma_f32_16x16x32_bf16 v[34:37], v[154:157], v[192:195], v[34:37]
	v_mfma_f32_16x16x32_bf16 v[22:25], v[146:149], v[200:203], v[22:25]
	v_mfma_f32_16x16x32_bf16 v[18:21], v[154:157], v[200:203], v[18:21]
	v_mfma_f32_16x16x32_bf16 v[6:9], v[146:149], v[208:211], v[6:9]
	v_mfma_f32_16x16x32_bf16 v[2:5], v[154:157], v[208:211], v[2:5]
	v_mfma_f32_16x16x32_bf16 v[66:69], v[158:161], v[188:191], v[42:45]
	v_mfma_f32_16x16x32_bf16 v[38:41], v[150:153], v[196:199], v[38:41]
	v_mfma_f32_16x16x32_bf16 v[34:37], v[158:161], v[196:199], v[34:37]
	v_mfma_f32_16x16x32_bf16 v[22:25], v[150:153], v[204:207], v[22:25]
	v_mfma_f32_16x16x32_bf16 v[18:21], v[158:161], v[204:207], v[18:21]
	s_setprio 2
	s_barrier
	v_mfma_f32_16x16x32_bf16 v[6:9], v[150:153], v[212:215], v[6:9]
	v_mfma_f32_16x16x32_bf16 v[2:5], v[158:161], v[212:215], v[2:5]
	s_setprio 0
	s_add_i32 s81, s81, 2
	s_add_u32 s77, s77, 0x100
	s_addc_u32 s78, s78, 0
	s_add_u32 s34, s34, 0x100
	s_addc_u32 s35, s35, 0
	s_add_u32 s79, s79, 0x100
	s_addc_u32 s80, s80, 0
	s_cmp_gt_u32 s81, 29
	s_cbranch_scc0 .LBB0_2146
	s_and_b64 vcc, exec, s[14:15]
	s_cbranch_vccz .LBB0_2149
	s_barrier

.LBB0_2410:
	s_cmp_eq_u32 s78, 28
	s_cselect_b32 s27, s15, s75
	s_cselect_b32 s26, s73, s74
	s_cselect_b32 s29, s17, s77
	s_cselect_b32 s28, s71, s76
	s_add_u32 s80, s24, 0xfff80000
	s_addc_u32 s81, s25, -1
	s_mov_b32 s79, m0
	s_mov_b32 m0, s64
	s_nop 0
	global_load_lds_dwordx4 v1, s[80:81]
	s_mov_b32 m0, s79
	s_nop 0
	s_mov_b32 s79, m0
	s_mov_b32 m0, s66
	s_nop 0
	global_load_lds_dwordx4 v177, s[80:81]
	s_mov_b32 m0, s79
	s_nop 0
	s_mov_b32 s79, m0
	s_mov_b32 m0, s65
	s_nop 0
	global_load_lds_dwordx4 v1, s[24:25]
	s_mov_b32 m0, s79
	s_nop 0
	s_mov_b32 s79, m0
	s_mov_b32 m0, s67
	s_nop 0
	global_load_lds_dwordx4 v177, s[24:25]
	s_mov_b32 m0, s79
	ds_read_b128 v[130:133], v181
	ds_read_b128 v[134:137], v181 offset:1024
	ds_read_b128 v[138:141], v181 offset:2048
	ds_read_b128 v[142:145], v181 offset:3072
	ds_read_b128 v[146:149], v182
	ds_read_b128 v[150:153], v182 offset:1024
	ds_read_b128 v[154:157], v182 offset:2048
	ds_read_b128 v[158:161], v182 offset:3072
	ds_read_b128 v[166:169], v183
	ds_read_b128 v[170:173], v183 offset:1024
	ds_read_b128 v[186:189], v183 offset:2048
	ds_read_b128 v[190:193], v183 offset:3072
	ds_read_b128 v[194:197], v183 offset:4096
	ds_read_b128 v[198:201], v183 offset:5120
	ds_read_b128 v[202:205], v183 offset:6144
	ds_read_b128 v[206:209], v183 offset:7168
	s_waitcnt vmcnt(8)
	s_waitcnt lgkmcnt(0)
	s_barrier
	s_setprio 1
	s_waitcnt lgkmcnt(7)
	v_mfma_f32_16x16x32_bf16 v[126:129], v[130:133], v[166:169], v[126:129]
	v_mfma_f32_16x16x32_bf16 v[122:125], v[138:141], v[166:169], v[122:125]
	s_waitcnt lgkmcnt(5)
	v_mfma_f32_16x16x32_bf16 v[118:121], v[130:133], v[186:189], v[118:121]
	v_mfma_f32_16x16x32_bf16 v[114:117], v[138:141], v[186:189], v[114:117]
	s_waitcnt lgkmcnt(3)
	v_mfma_f32_16x16x32_bf16 v[94:97], v[130:133], v[194:197], v[94:97]
	v_mfma_f32_16x16x32_bf16 v[90:93], v[138:141], v[194:197], v[90:93]
	s_waitcnt lgkmcnt(1)
	v_mfma_f32_16x16x32_bf16 v[86:89], v[130:133], v[202:205], v[86:89]
	v_mfma_f32_16x16x32_bf16 v[78:81], v[138:141], v[202:205], v[78:81]
	v_mfma_f32_16x16x32_bf16 v[126:129], v[134:137], v[170:173], v[126:129]
	v_mfma_f32_16x16x32_bf16 v[122:125], v[142:145], v[170:173], v[122:125]
	v_mfma_f32_16x16x32_bf16 v[118:121], v[134:137], v[190:193], v[118:121]
	v_mfma_f32_16x16x32_bf16 v[114:117], v[142:145], v[190:193], v[114:117]
	v_mfma_f32_16x16x32_bf16 v[94:97], v[134:137], v[198:201], v[94:97]
	v_mfma_f32_16x16x32_bf16 v[90:93], v[142:145], v[198:201], v[90:93]
	s_waitcnt lgkmcnt(0)
	v_mfma_f32_16x16x32_bf16 v[86:89], v[134:137], v[206:209], v[86:89]
	v_mfma_f32_16x16x32_bf16 v[78:81], v[142:145], v[206:209], v[78:81]
	s_setprio 0
	s_setprio 1
	v_mfma_f32_16x16x32_bf16 v[110:113], v[146:149], v[166:169], v[110:113]
	v_mfma_f32_16x16x32_bf16 v[106:109], v[154:157], v[166:169], v[106:109]
	v_mfma_f32_16x16x32_bf16 v[102:105], v[146:149], v[186:189], v[102:105]
	v_mfma_f32_16x16x32_bf16 v[98:101], v[154:157], v[186:189], v[98:101]
	v_mfma_f32_16x16x32_bf16 v[82:85], v[146:149], v[194:197], v[82:85]
	v_mfma_f32_16x16x32_bf16 v[74:77], v[154:157], v[194:197], v[74:77]
	v_mfma_f32_16x16x32_bf16 v[70:73], v[146:149], v[202:205], v[70:73]
	v_mfma_f32_16x16x32_bf16 v[66:69], v[154:157], v[202:205], v[66:69]
	v_mfma_f32_16x16x32_bf16 v[110:113], v[150:153], v[170:173], v[110:113]
	v_mfma_f32_16x16x32_bf16 v[106:109], v[158:161], v[170:173], v[106:109]
	v_mfma_f32_16x16x32_bf16 v[102:105], v[150:153], v[190:193], v[102:105]
	v_mfma_f32_16x16x32_bf16 v[98:101], v[158:161], v[190:193], v[98:101]
	v_mfma_f32_16x16x32_bf16 v[82:85], v[150:153], v[198:201], v[82:85]
	v_mfma_f32_16x16x32_bf16 v[74:77], v[158:161], v[198:201], v[74:77]
	s_setprio 2
	s_barrier
	v_mfma_f32_16x16x32_bf16 v[70:73], v[150:153], v[206:209], v[70:73]
	v_mfma_f32_16x16x32_bf16 v[66:69], v[158:161], v[206:209], v[66:69]
	s_setprio 0
	s_mov_b32 s79, m0
	s_mov_b32 m0, s41
	s_nop 0
	global_load_lds_dwordx4 v176, s[26:27]
	s_mov_b32 m0, s79
	s_add_u32 s80, s26, 0x80000
	s_mov_b32 s79, m0
	s_mov_b32 m0, s42
	s_nop 0
	global_load_lds_dwordx4 v178, s[26:27]
	s_mov_b32 m0, s79
	s_addc_u32 s81, s27, 0
	s_mov_b32 s79, m0
	s_mov_b32 m0, s43
	s_nop 0
	global_load_lds_dwordx4 v176, s[80:81]
	s_mov_b32 m0, s79
	s_nop 0
	s_mov_b32 s79, m0
	s_mov_b32 m0, s46
	s_nop 0
	global_load_lds_dwordx4 v178, s[80:81]
	s_mov_b32 m0, s79
	ds_read_b128 v[166:169], v183 offset:16384
	ds_read_b128 v[170:173], v183 offset:17408
	ds_read_b128 v[186:189], v183 offset:18432
	ds_read_b128 v[190:193], v183 offset:19456
	ds_read_b128 v[194:197], v183 offset:20480
	ds_read_b128 v[198:201], v183 offset:21504
	ds_read_b128 v[202:205], v183 offset:22528
	ds_read_b128 v[206:209], v183 offset:23552
	s_waitcnt vmcnt(4)
	s_waitcnt lgkmcnt(0)
	s_barrier
	s_setprio 1
	s_waitcnt lgkmcnt(7)
	v_mfma_f32_16x16x32_bf16 v[62:65], v[130:133], v[166:169], v[62:65]
	v_mfma_f32_16x16x32_bf16 v[58:61], v[138:141], v[166:169], v[58:61]
	s_waitcnt lgkmcnt(5)
	v_mfma_f32_16x16x32_bf16 v[46:49], v[130:133], v[186:189], v[46:49]
	v_mfma_f32_16x16x32_bf16 v[42:45], v[138:141], v[186:189], v[42:45]
	s_waitcnt lgkmcnt(3)
	v_mfma_f32_16x16x32_bf16 v[30:33], v[130:133], v[194:197], v[30:33]
	v_mfma_f32_16x16x32_bf16 v[26:29], v[138:141], v[194:197], v[26:29]
	s_waitcnt lgkmcnt(1)
	v_mfma_f32_16x16x32_bf16 v[14:17], v[130:133], v[202:205], v[14:17]
	v_mfma_f32_16x16x32_bf16 v[10:13], v[138:141], v[202:205], v[10:13]
	v_mfma_f32_16x16x32_bf16 v[62:65], v[134:137], v[170:173], v[62:65]
	v_mfma_f32_16x16x32_bf16 v[58:61], v[142:145], v[170:173], v[58:61]
	v_mfma_f32_16x16x32_bf16 v[46:49], v[134:137], v[190:193], v[46:49]
	v_mfma_f32_16x16x32_bf16 v[42:45], v[142:145], v[190:193], v[42:45]
	v_mfma_f32_16x16x32_bf16 v[30:33], v[134:137], v[198:201], v[30:33]
	v_mfma_f32_16x16x32_bf16 v[26:29], v[142:145], v[198:201], v[26:29]
	s_waitcnt lgkmcnt(0)
	v_mfma_f32_16x16x32_bf16 v[14:17], v[134:137], v[206:209], v[14:17]
	v_mfma_f32_16x16x32_bf16 v[10:13], v[142:145], v[206:209], v[10:13]
	s_setprio 0
	s_setprio 1
	v_mfma_f32_16x16x32_bf16 v[54:57], v[146:149], v[166:169], v[54:57]
	v_mfma_f32_16x16x32_bf16 v[50:53], v[154:157], v[166:169], v[50:53]
	v_mfma_f32_16x16x32_bf16 v[38:41], v[146:149], v[186:189], v[38:41]
	v_mfma_f32_16x16x32_bf16 v[34:37], v[154:157], v[186:189], v[34:37]
	v_mfma_f32_16x16x32_bf16 v[22:25], v[146:149], v[194:197], v[22:25]
	v_mfma_f32_16x16x32_bf16 v[18:21], v[154:157], v[194:197], v[18:21]
	v_mfma_f32_16x16x32_bf16 v[6:9], v[146:149], v[202:205], v[6:9]
	v_mfma_f32_16x16x32_bf16 v[2:5], v[154:157], v[202:205], v[2:5]
	v_mfma_f32_16x16x32_bf16 v[54:57], v[150:153], v[170:173], v[54:57]
	v_mfma_f32_16x16x32_bf16 v[50:53], v[158:161], v[170:173], v[50:53]
	v_mfma_f32_16x16x32_bf16 v[38:41], v[150:153], v[190:193], v[38:41]
	v_mfma_f32_16x16x32_bf16 v[34:37], v[158:161], v[190:193], v[34:37]
	v_mfma_f32_16x16x32_bf16 v[22:25], v[150:153], v[198:201], v[22:25]
	v_mfma_f32_16x16x32_bf16 v[18:21], v[158:161], v[198:201], v[18:21]
	s_setprio 2
	s_barrier
	v_mfma_f32_16x16x32_bf16 v[6:9], v[150:153], v[206:209], v[6:9]
	v_mfma_f32_16x16x32_bf16 v[2:5], v[158:161], v[206:209], v[2:5]
	s_setprio 0
	s_mov_b32 s79, m0
	s_mov_b32 m0, s40
	s_nop 0
	global_load_lds_dwordx4 v1, s[28:29]
	s_mov_b32 m0, s79
	s_nop 0
	s_mov_b32 s79, m0
	s_mov_b32 m0, s47
	s_nop 0
	global_load_lds_dwordx4 v177, s[28:29]
	s_mov_b32 m0, s79
	s_add_u32 s28, s28, 0x80000
	s_addc_u32 s29, s29, 0
	s_mov_b32 s79, m0
	s_mov_b32 m0, s48
	s_nop 0
	global_load_lds_dwordx4 v1, s[28:29]
	s_mov_b32 m0, s79
	s_nop 0
	s_mov_b32 s79, m0
	s_mov_b32 m0, s49
	s_nop 0
	global_load_lds_dwordx4 v177, s[28:29]
	s_mov_b32 m0, s79
	ds_read_b128 v[130:133], v184
	ds_read_b128 v[134:137], v184 offset:1024
	ds_read_b128 v[138:141], v184 offset:2048
	ds_read_b128 v[142:145], v184 offset:3072
	ds_read_b128 v[146:149], v185
	ds_read_b128 v[150:153], v185 offset:1024
	ds_read_b128 v[154:157], v185 offset:2048
	ds_read_b128 v[158:161], v185 offset:3072
	ds_read_b128 v[166:169], v183 offset:32768
	ds_read_b128 v[170:173], v183 offset:33792
	ds_read_b128 v[186:189], v183 offset:34816
	ds_read_b128 v[190:193], v183 offset:35840
	ds_read_b128 v[194:197], v183 offset:36864
	ds_read_b128 v[198:201], v183 offset:37888
	ds_read_b128 v[202:205], v183 offset:38912
	ds_read_b128 v[206:209], v183 offset:39936
	s_waitcnt vmcnt(8)
	s_waitcnt lgkmcnt(0)
	s_barrier
	s_setprio 1
	s_waitcnt lgkmcnt(7)
	v_mfma_f32_16x16x32_bf16 v[126:129], v[130:133], v[166:169], v[126:129]
	v_mfma_f32_16x16x32_bf16 v[122:125], v[138:141], v[166:169], v[122:125]
	s_waitcnt lgkmcnt(5)
	v_mfma_f32_16x16x32_bf16 v[118:121], v[130:133], v[186:189], v[118:121]
	v_mfma_f32_16x16x32_bf16 v[114:117], v[138:141], v[186:189], v[114:117]
	s_waitcnt lgkmcnt(3)
	v_mfma_f32_16x16x32_bf16 v[94:97], v[130:133], v[194:197], v[94:97]
	v_mfma_f32_16x16x32_bf16 v[90:93], v[138:141], v[194:197], v[90:93]
	s_waitcnt lgkmcnt(1)
	v_mfma_f32_16x16x32_bf16 v[86:89], v[130:133], v[202:205], v[86:89]
	v_mfma_f32_16x16x32_bf16 v[78:81], v[138:141], v[202:205], v[78:81]
	v_mfma_f32_16x16x32_bf16 v[126:129], v[134:137], v[170:173], v[126:129]
	v_mfma_f32_16x16x32_bf16 v[122:125], v[142:145], v[170:173], v[122:125]
	v_mfma_f32_16x16x32_bf16 v[118:121], v[134:137], v[190:193], v[118:121]
	v_mfma_f32_16x16x32_bf16 v[114:117], v[142:145], v[190:193], v[114:117]
	v_mfma_f32_16x16x32_bf16 v[94:97], v[134:137], v[198:201], v[94:97]
	v_mfma_f32_16x16x32_bf16 v[90:93], v[142:145], v[198:201], v[90:93]
	s_waitcnt lgkmcnt(0)
	v_mfma_f32_16x16x32_bf16 v[86:89], v[134:137], v[206:209], v[86:89]
	v_mfma_f32_16x16x32_bf16 v[78:81], v[142:145], v[206:209], v[78:81]
	s_setprio 0
	s_setprio 1
	v_mfma_f32_16x16x32_bf16 v[110:113], v[146:149], v[166:169], v[110:113]
	v_mfma_f32_16x16x32_bf16 v[106:109], v[154:157], v[166:169], v[106:109]
	v_mfma_f32_16x16x32_bf16 v[102:105], v[146:149], v[186:189], v[102:105]
	v_mfma_f32_16x16x32_bf16 v[98:101], v[154:157], v[186:189], v[98:101]
	v_mfma_f32_16x16x32_bf16 v[82:85], v[146:149], v[194:197], v[82:85]
	v_mfma_f32_16x16x32_bf16 v[74:77], v[154:157], v[194:197], v[74:77]
	v_mfma_f32_16x16x32_bf16 v[70:73], v[146:149], v[202:205], v[70:73]
	v_mfma_f32_16x16x32_bf16 v[66:69], v[154:157], v[202:205], v[66:69]
	v_mfma_f32_16x16x32_bf16 v[110:113], v[150:153], v[170:173], v[110:113]
	v_mfma_f32_16x16x32_bf16 v[106:109], v[158:161], v[170:173], v[106:109]
	v_mfma_f32_16x16x32_bf16 v[102:105], v[150:153], v[190:193], v[102:105]
	v_mfma_f32_16x16x32_bf16 v[98:101], v[158:161], v[190:193], v[98:101]
	v_mfma_f32_16x16x32_bf16 v[82:85], v[150:153], v[198:201], v[82:85]
	v_mfma_f32_16x16x32_bf16 v[74:77], v[158:161], v[198:201], v[74:77]
	s_setprio 2
	s_barrier
	v_mfma_f32_16x16x32_bf16 v[70:73], v[150:153], v[206:209], v[70:73]
	v_mfma_f32_16x16x32_bf16 v[66:69], v[158:161], v[206:209], v[66:69]
	s_setprio 0
	s_add_u32 s28, s26, 0x80
	s_addc_u32 s29, s27, 0
	s_mov_b32 s79, m0
	s_mov_b32 m0, s56
	s_nop 0
	global_load_lds_dwordx4 v176, s[28:29]
	s_mov_b32 m0, s79
	s_add_u32 s26, s26, 0x80080
	s_mov_b32 s79, m0
	s_mov_b32 m0, s57
	s_nop 0
	global_load_lds_dwordx4 v178, s[28:29]
	s_mov_b32 m0, s79
	s_addc_u32 s27, s27, 0
	s_mov_b32 s28, m0
	s_mov_b32 m0, s58
	s_nop 0
	global_load_lds_dwordx4 v176, s[26:27]
	s_mov_b32 m0, s28
	s_nop 0
	s_mov_b32 s28, m0
	s_mov_b32 m0, s59
	s_nop 0
	global_load_lds_dwordx4 v178, s[26:27]
	s_mov_b32 m0, s28
	ds_read_b128 v[166:169], v183 offset:49152
	ds_read_b128 v[170:173], v183 offset:50176
	ds_read_b128 v[186:189], v183 offset:51200
	ds_read_b128 v[190:193], v183 offset:52224
	ds_read_b128 v[194:197], v183 offset:53248
	ds_read_b128 v[198:201], v183 offset:54272
	ds_read_b128 v[202:205], v183 offset:55296
	ds_read_b128 v[206:209], v183 offset:56320
	s_waitcnt vmcnt(4)
	s_waitcnt lgkmcnt(0)
	s_barrier
	s_setprio 1
	s_waitcnt lgkmcnt(7)
	v_mfma_f32_16x16x32_bf16 v[62:65], v[130:133], v[166:169], v[62:65]
	v_mfma_f32_16x16x32_bf16 v[58:61], v[138:141], v[166:169], v[58:61]
	s_waitcnt lgkmcnt(5)
	v_mfma_f32_16x16x32_bf16 v[46:49], v[130:133], v[186:189], v[46:49]
	v_mfma_f32_16x16x32_bf16 v[42:45], v[138:141], v[186:189], v[42:45]
	s_waitcnt lgkmcnt(3)
	v_mfma_f32_16x16x32_bf16 v[30:33], v[130:133], v[194:197], v[30:33]
	v_mfma_f32_16x16x32_bf16 v[26:29], v[138:141], v[194:197], v[26:29]
	s_waitcnt lgkmcnt(1)
	v_mfma_f32_16x16x32_bf16 v[14:17], v[130:133], v[202:205], v[14:17]
	v_mfma_f32_16x16x32_bf16 v[10:13], v[138:141], v[202:205], v[10:13]
	v_mfma_f32_16x16x32_bf16 v[62:65], v[134:137], v[170:173], v[62:65]
	v_mfma_f32_16x16x32_bf16 v[58:61], v[142:145], v[170:173], v[58:61]
	v_mfma_f32_16x16x32_bf16 v[46:49], v[134:137], v[190:193], v[46:49]
	v_mfma_f32_16x16x32_bf16 v[42:45], v[142:145], v[190:193], v[42:45]
	v_mfma_f32_16x16x32_bf16 v[30:33], v[134:137], v[198:201], v[30:33]
	v_mfma_f32_16x16x32_bf16 v[26:29], v[142:145], v[198:201], v[26:29]
	s_waitcnt lgkmcnt(0)
	v_mfma_f32_16x16x32_bf16 v[14:17], v[134:137], v[206:209], v[14:17]
	v_mfma_f32_16x16x32_bf16 v[10:13], v[142:145], v[206:209], v[10:13]
	s_setprio 0
	s_setprio 1
	v_mfma_f32_16x16x32_bf16 v[54:57], v[146:149], v[166:169], v[54:57]
	v_mfma_f32_16x16x32_bf16 v[50:53], v[154:157], v[166:169], v[50:53]
	v_mfma_f32_16x16x32_bf16 v[38:41], v[146:149], v[186:189], v[38:41]
	v_mfma_f32_16x16x32_bf16 v[34:37], v[154:157], v[186:189], v[34:37]
	v_mfma_f32_16x16x32_bf16 v[22:25], v[146:149], v[194:197], v[22:25]
	v_mfma_f32_16x16x32_bf16 v[18:21], v[154:157], v[194:197], v[18:21]
	v_mfma_f32_16x16x32_bf16 v[6:9], v[146:149], v[202:205], v[6:9]
	v_mfma_f32_16x16x32_bf16 v[2:5], v[154:157], v[202:205], v[2:5]
	v_mfma_f32_16x16x32_bf16 v[54:57], v[150:153], v[170:173], v[54:57]
	v_mfma_f32_16x16x32_bf16 v[50:53], v[158:161], v[170:173], v[50:53]
	v_mfma_f32_16x16x32_bf16 v[38:41], v[150:153], v[190:193], v[38:41]
	v_mfma_f32_16x16x32_bf16 v[34:37], v[158:161], v[190:193], v[34:37]
	v_mfma_f32_16x16x32_bf16 v[22:25], v[150:153], v[198:201], v[22:25]
	v_mfma_f32_16x16x32_bf16 v[18:21], v[158:161], v[198:201], v[18:21]
	s_setprio 2
	s_barrier
	v_mfma_f32_16x16x32_bf16 v[6:9], v[150:153], v[206:209], v[6:9]
	v_mfma_f32_16x16x32_bf16 v[2:5], v[158:161], v[206:209], v[2:5]
	s_setprio 0
	s_add_i32 s78, s78, 2
	s_add_u32 s74, s74, 0x100
	s_addc_u32 s75, s75, 0
	s_add_u32 s24, s24, 0x100
	s_addc_u32 s25, s25, 0
	s_add_u32 s76, s76, 0x100
	s_addc_u32 s77, s77, 0
	s_cmp_gt_u32 s78, 29
	s_cbranch_scc0 .LBB0_2410
	s_and_b64 vcc, exec, s[8:9]
	s_cbranch_vccz .LBB0_2413
	s_barrier

.LBB0_2594:
	s_cmp_eq_u32 s70, 28
	s_cselect_b32 s21, s9, s65
	s_cselect_b32 s20, s63, s64
	s_cselect_b32 s23, s11, s67
	s_cselect_b32 s22, s62, s66
	s_add_u32 s74, s18, 0xfff80000
	s_addc_u32 s75, s19, -1
	s_mov_b32 s71, m0
	s_mov_b32 m0, s48
	s_nop 0
	global_load_lds_dwordx4 v138, s[74:75]
	s_mov_b32 m0, s71
	s_nop 0
	s_mov_b32 s71, m0
	s_mov_b32 m0, s57
	s_nop 0
	global_load_lds_dwordx4 v140, s[74:75]
	s_mov_b32 m0, s71
	s_nop 0
	s_mov_b32 s71, m0
	s_mov_b32 m0, s49
	s_nop 0
	global_load_lds_dwordx4 v138, s[18:19]
	s_mov_b32 m0, s71
	s_nop 0
	s_mov_b32 s71, m0
	s_mov_b32 m0, s58
	s_nop 0
	global_load_lds_dwordx4 v140, s[18:19]
	s_mov_b32 m0, s71
	ds_read_b128 v[148:151], v143
	ds_read_b128 v[152:155], v143 offset:1024
	ds_read_b128 v[156:159], v143 offset:2048
	ds_read_b128 v[160:163], v143 offset:3072
	ds_read_b128 v[164:167], v144
	ds_read_b128 v[168:171], v144 offset:1024
	ds_read_b128 v[172:175], v144 offset:2048
	ds_read_b128 v[176:179], v144 offset:3072
	ds_read_b128 v[180:183], v145
	ds_read_b128 v[184:187], v145 offset:1024
	ds_read_b128 v[188:191], v145 offset:2048
	ds_read_b128 v[192:195], v145 offset:3072
	ds_read_b128 v[196:199], v145 offset:4096
	ds_read_b128 v[200:203], v145 offset:5120
	ds_read_b128 v[204:207], v145 offset:6144
	ds_read_b128 v[208:211], v145 offset:7168
	s_waitcnt vmcnt(8)
	s_waitcnt lgkmcnt(0)
	s_barrier
	s_setprio 1
	s_waitcnt lgkmcnt(7)
	v_mfma_f32_16x16x32_bf16 v[126:129], v[148:151], v[180:183], v[126:129]
	v_mfma_f32_16x16x32_bf16 v[122:125], v[156:159], v[180:183], v[122:125]
	s_waitcnt lgkmcnt(5)
	v_mfma_f32_16x16x32_bf16 v[110:113], v[148:151], v[188:191], v[110:113]
	v_mfma_f32_16x16x32_bf16 v[106:109], v[156:159], v[188:191], v[106:109]
	s_waitcnt lgkmcnt(3)
	v_mfma_f32_16x16x32_bf16 v[94:97], v[148:151], v[196:199], v[94:97]
	v_mfma_f32_16x16x32_bf16 v[90:93], v[156:159], v[196:199], v[90:93]
	s_waitcnt lgkmcnt(1)
	v_mfma_f32_16x16x32_bf16 v[78:81], v[148:151], v[204:207], v[78:81]
	v_mfma_f32_16x16x32_bf16 v[74:77], v[156:159], v[204:207], v[74:77]
	v_mfma_f32_16x16x32_bf16 v[126:129], v[152:155], v[184:187], v[126:129]
	v_mfma_f32_16x16x32_bf16 v[122:125], v[160:163], v[184:187], v[122:125]
	v_mfma_f32_16x16x32_bf16 v[110:113], v[152:155], v[192:195], v[110:113]
	v_mfma_f32_16x16x32_bf16 v[106:109], v[160:163], v[192:195], v[106:109]
	v_mfma_f32_16x16x32_bf16 v[94:97], v[152:155], v[200:203], v[94:97]
	v_mfma_f32_16x16x32_bf16 v[90:93], v[160:163], v[200:203], v[90:93]
	s_waitcnt lgkmcnt(0)
	v_mfma_f32_16x16x32_bf16 v[78:81], v[152:155], v[208:211], v[78:81]
	v_mfma_f32_16x16x32_bf16 v[74:77], v[160:163], v[208:211], v[74:77]
	s_setprio 0
	s_setprio 1
	v_mfma_f32_16x16x32_bf16 v[118:121], v[164:167], v[180:183], v[118:121]
	v_mfma_f32_16x16x32_bf16 v[114:117], v[172:175], v[180:183], v[114:117]
	v_mfma_f32_16x16x32_bf16 v[102:105], v[164:167], v[188:191], v[102:105]
	v_mfma_f32_16x16x32_bf16 v[98:101], v[172:175], v[188:191], v[98:101]
	v_mfma_f32_16x16x32_bf16 v[86:89], v[164:167], v[196:199], v[86:89]
	v_mfma_f32_16x16x32_bf16 v[82:85], v[172:175], v[196:199], v[82:85]
	v_mfma_f32_16x16x32_bf16 v[70:73], v[164:167], v[204:207], v[70:73]
	v_mfma_f32_16x16x32_bf16 v[66:69], v[172:175], v[204:207], v[66:69]
	v_mfma_f32_16x16x32_bf16 v[118:121], v[168:171], v[184:187], v[118:121]
	v_mfma_f32_16x16x32_bf16 v[114:117], v[176:179], v[184:187], v[114:117]
	v_mfma_f32_16x16x32_bf16 v[102:105], v[168:171], v[192:195], v[102:105]
	v_mfma_f32_16x16x32_bf16 v[98:101], v[176:179], v[192:195], v[98:101]
	v_mfma_f32_16x16x32_bf16 v[86:89], v[168:171], v[200:203], v[86:89]
	v_mfma_f32_16x16x32_bf16 v[82:85], v[176:179], v[200:203], v[82:85]
	s_setprio 2
	s_barrier
	v_mfma_f32_16x16x32_bf16 v[70:73], v[168:171], v[208:211], v[70:73]
	v_mfma_f32_16x16x32_bf16 v[66:69], v[176:179], v[208:211], v[66:69]
	s_setprio 0
	s_mov_b32 s71, m0
	s_mov_b32 m0, s35
	s_nop 0
	global_load_lds_dwordx4 v139, s[20:21]
	s_mov_b32 m0, s71
	s_add_u32 s74, s20, 0x80000
	s_mov_b32 s71, m0
	s_mov_b32 m0, s36
	s_nop 0
	global_load_lds_dwordx4 v141, s[20:21]
	s_mov_b32 m0, s71
	s_addc_u32 s75, s21, 0
	s_mov_b32 s71, m0
	s_mov_b32 m0, s37
	s_nop 0
	global_load_lds_dwordx4 v139, s[74:75]
	s_mov_b32 m0, s71
	s_nop 0
	s_mov_b32 s71, m0
	s_mov_b32 m0, s40
	s_nop 0
	global_load_lds_dwordx4 v141, s[74:75]
	s_mov_b32 m0, s71
	ds_read_b128 v[180:183], v145 offset:16384
	ds_read_b128 v[184:187], v145 offset:17408
	ds_read_b128 v[188:191], v145 offset:18432
	ds_read_b128 v[192:195], v145 offset:19456
	ds_read_b128 v[196:199], v145 offset:20480
	ds_read_b128 v[200:203], v145 offset:21504
	ds_read_b128 v[204:207], v145 offset:22528
	ds_read_b128 v[208:211], v145 offset:23552
	s_waitcnt vmcnt(4)
	s_waitcnt lgkmcnt(0)
	s_barrier
	s_setprio 1
	s_waitcnt lgkmcnt(7)
	v_mfma_f32_16x16x32_bf16 v[62:65], v[148:151], v[180:183], v[62:65]
	v_mfma_f32_16x16x32_bf16 v[58:61], v[156:159], v[180:183], v[58:61]
	s_waitcnt lgkmcnt(5)
	v_mfma_f32_16x16x32_bf16 v[46:49], v[148:151], v[188:191], v[46:49]
	v_mfma_f32_16x16x32_bf16 v[42:45], v[156:159], v[188:191], v[42:45]
	s_waitcnt lgkmcnt(3)
	v_mfma_f32_16x16x32_bf16 v[30:33], v[148:151], v[196:199], v[30:33]
	v_mfma_f32_16x16x32_bf16 v[26:29], v[156:159], v[196:199], v[26:29]
	s_waitcnt lgkmcnt(1)
	v_mfma_f32_16x16x32_bf16 v[14:17], v[148:151], v[204:207], v[14:17]
	v_mfma_f32_16x16x32_bf16 v[10:13], v[156:159], v[204:207], v[10:13]
	v_mfma_f32_16x16x32_bf16 v[62:65], v[152:155], v[184:187], v[62:65]
	v_mfma_f32_16x16x32_bf16 v[58:61], v[160:163], v[184:187], v[58:61]
	v_mfma_f32_16x16x32_bf16 v[46:49], v[152:155], v[192:195], v[46:49]
	v_mfma_f32_16x16x32_bf16 v[42:45], v[160:163], v[192:195], v[42:45]
	v_mfma_f32_16x16x32_bf16 v[30:33], v[152:155], v[200:203], v[30:33]
	v_mfma_f32_16x16x32_bf16 v[26:29], v[160:163], v[200:203], v[26:29]
	s_waitcnt lgkmcnt(0)
	v_mfma_f32_16x16x32_bf16 v[14:17], v[152:155], v[208:211], v[14:17]
	v_mfma_f32_16x16x32_bf16 v[10:13], v[160:163], v[208:211], v[10:13]
	s_setprio 0
	s_setprio 1
	v_mfma_f32_16x16x32_bf16 v[54:57], v[164:167], v[180:183], v[54:57]
	v_mfma_f32_16x16x32_bf16 v[50:53], v[172:175], v[180:183], v[50:53]
	v_mfma_f32_16x16x32_bf16 v[38:41], v[164:167], v[188:191], v[38:41]
	v_mfma_f32_16x16x32_bf16 v[34:37], v[172:175], v[188:191], v[34:37]
	v_mfma_f32_16x16x32_bf16 v[22:25], v[164:167], v[196:199], v[22:25]
	v_mfma_f32_16x16x32_bf16 v[18:21], v[172:175], v[196:199], v[18:21]
	v_mfma_f32_16x16x32_bf16 v[6:9], v[164:167], v[204:207], v[6:9]
	v_mfma_f32_16x16x32_bf16 v[2:5], v[172:175], v[204:207], v[2:5]
	v_mfma_f32_16x16x32_bf16 v[54:57], v[168:171], v[184:187], v[54:57]
	v_mfma_f32_16x16x32_bf16 v[50:53], v[176:179], v[184:187], v[50:53]
	v_mfma_f32_16x16x32_bf16 v[38:41], v[168:171], v[192:195], v[38:41]
	v_mfma_f32_16x16x32_bf16 v[34:37], v[176:179], v[192:195], v[34:37]
	v_mfma_f32_16x16x32_bf16 v[22:25], v[168:171], v[200:203], v[22:25]
	v_mfma_f32_16x16x32_bf16 v[18:21], v[176:179], v[200:203], v[18:21]
	s_setprio 2
	s_barrier
	v_mfma_f32_16x16x32_bf16 v[6:9], v[168:171], v[208:211], v[6:9]
	v_mfma_f32_16x16x32_bf16 v[2:5], v[176:179], v[208:211], v[2:5]
	s_setprio 0
	s_mov_b32 s71, m0
	s_mov_b32 m0, s31
	s_nop 0
	global_load_lds_dwordx4 v138, s[22:23]
	s_mov_b32 m0, s71
	s_nop 0
	s_mov_b32 s71, m0
	s_mov_b32 m0, s41
	s_nop 0
	global_load_lds_dwordx4 v140, s[22:23]
	s_mov_b32 m0, s71
	s_add_u32 s22, s22, 0x80000
	s_addc_u32 s23, s23, 0
	s_mov_b32 s71, m0
	s_mov_b32 m0, s42
	s_nop 0
	global_load_lds_dwordx4 v138, s[22:23]
	s_mov_b32 m0, s71
	s_nop 0
	s_mov_b32 s71, m0
	s_mov_b32 m0, s43
	s_nop 0
	global_load_lds_dwordx4 v140, s[22:23]
	s_mov_b32 m0, s71
	ds_read_b128 v[148:151], v146
	ds_read_b128 v[152:155], v146 offset:1024
	ds_read_b128 v[156:159], v146 offset:2048
	ds_read_b128 v[160:163], v146 offset:3072
	ds_read_b128 v[164:167], v147
	ds_read_b128 v[168:171], v147 offset:1024
	ds_read_b128 v[172:175], v147 offset:2048
	ds_read_b128 v[176:179], v147 offset:3072
	ds_read_b128 v[180:183], v145 offset:32768
	ds_read_b128 v[184:187], v145 offset:33792
	ds_read_b128 v[188:191], v145 offset:34816
	ds_read_b128 v[192:195], v145 offset:35840
	ds_read_b128 v[196:199], v145 offset:36864
	ds_read_b128 v[200:203], v145 offset:37888
	ds_read_b128 v[204:207], v145 offset:38912
	ds_read_b128 v[208:211], v145 offset:39936
	s_waitcnt vmcnt(8)
	s_waitcnt lgkmcnt(0)
	s_barrier
	s_setprio 1
	s_waitcnt lgkmcnt(7)
	v_mfma_f32_16x16x32_bf16 v[126:129], v[148:151], v[180:183], v[126:129]
	v_mfma_f32_16x16x32_bf16 v[122:125], v[156:159], v[180:183], v[122:125]
	s_waitcnt lgkmcnt(5)
	v_mfma_f32_16x16x32_bf16 v[110:113], v[148:151], v[188:191], v[110:113]
	v_mfma_f32_16x16x32_bf16 v[106:109], v[156:159], v[188:191], v[106:109]
	s_waitcnt lgkmcnt(3)
	v_mfma_f32_16x16x32_bf16 v[94:97], v[148:151], v[196:199], v[94:97]
	v_mfma_f32_16x16x32_bf16 v[90:93], v[156:159], v[196:199], v[90:93]
	s_waitcnt lgkmcnt(1)
	v_mfma_f32_16x16x32_bf16 v[78:81], v[148:151], v[204:207], v[78:81]
	v_mfma_f32_16x16x32_bf16 v[74:77], v[156:159], v[204:207], v[74:77]
	v_mfma_f32_16x16x32_bf16 v[126:129], v[152:155], v[184:187], v[126:129]
	v_mfma_f32_16x16x32_bf16 v[122:125], v[160:163], v[184:187], v[122:125]
	v_mfma_f32_16x16x32_bf16 v[110:113], v[152:155], v[192:195], v[110:113]
	v_mfma_f32_16x16x32_bf16 v[106:109], v[160:163], v[192:195], v[106:109]
	v_mfma_f32_16x16x32_bf16 v[94:97], v[152:155], v[200:203], v[94:97]
	v_mfma_f32_16x16x32_bf16 v[90:93], v[160:163], v[200:203], v[90:93]
	s_waitcnt lgkmcnt(0)
	v_mfma_f32_16x16x32_bf16 v[78:81], v[152:155], v[208:211], v[78:81]
	v_mfma_f32_16x16x32_bf16 v[74:77], v[160:163], v[208:211], v[74:77]
	s_setprio 0
	s_setprio 1
	v_mfma_f32_16x16x32_bf16 v[118:121], v[164:167], v[180:183], v[118:121]
	v_mfma_f32_16x16x32_bf16 v[114:117], v[172:175], v[180:183], v[114:117]
	v_mfma_f32_16x16x32_bf16 v[102:105], v[164:167], v[188:191], v[102:105]
	v_mfma_f32_16x16x32_bf16 v[98:101], v[172:175], v[188:191], v[98:101]
	v_mfma_f32_16x16x32_bf16 v[86:89], v[164:167], v[196:199], v[86:89]
	v_mfma_f32_16x16x32_bf16 v[82:85], v[172:175], v[196:199], v[82:85]
	v_mfma_f32_16x16x32_bf16 v[70:73], v[164:167], v[204:207], v[70:73]
	v_mfma_f32_16x16x32_bf16 v[66:69], v[172:175], v[204:207], v[66:69]
	v_mfma_f32_16x16x32_bf16 v[118:121], v[168:171], v[184:187], v[118:121]
	v_mfma_f32_16x16x32_bf16 v[114:117], v[176:179], v[184:187], v[114:117]
	v_mfma_f32_16x16x32_bf16 v[102:105], v[168:171], v[192:195], v[102:105]
	v_mfma_f32_16x16x32_bf16 v[98:101], v[176:179], v[192:195], v[98:101]
	v_mfma_f32_16x16x32_bf16 v[86:89], v[168:171], v[200:203], v[86:89]
	v_mfma_f32_16x16x32_bf16 v[82:85], v[176:179], v[200:203], v[82:85]
	s_setprio 2
	s_barrier
	v_mfma_f32_16x16x32_bf16 v[70:73], v[168:171], v[208:211], v[70:73]
	v_mfma_f32_16x16x32_bf16 v[66:69], v[176:179], v[208:211], v[66:69]
	s_setprio 0
	s_add_u32 s22, s20, 0x80
	s_addc_u32 s23, s21, 0
	s_mov_b32 s71, m0
	s_mov_b32 m0, s44
	s_nop 0
	global_load_lds_dwordx4 v139, s[22:23]
	s_mov_b32 m0, s71
	s_add_u32 s20, s20, 0x80080
	s_mov_b32 s71, m0
	s_mov_b32 m0, s45
	s_nop 0
	global_load_lds_dwordx4 v141, s[22:23]
	s_mov_b32 m0, s71
	s_addc_u32 s21, s21, 0
	s_mov_b32 s22, m0
	s_mov_b32 m0, s46
	s_nop 0
	global_load_lds_dwordx4 v139, s[20:21]
	s_mov_b32 m0, s22
	s_nop 0
	s_mov_b32 s22, m0
	s_mov_b32 m0, s47
	s_nop 0
	global_load_lds_dwordx4 v141, s[20:21]
	s_mov_b32 m0, s22
	ds_read_b128 v[180:183], v145 offset:49152
	ds_read_b128 v[184:187], v145 offset:50176
	ds_read_b128 v[188:191], v145 offset:51200
	ds_read_b128 v[192:195], v145 offset:52224
	ds_read_b128 v[196:199], v145 offset:53248
	ds_read_b128 v[200:203], v145 offset:54272
	ds_read_b128 v[204:207], v145 offset:55296
	ds_read_b128 v[208:211], v145 offset:56320
	s_waitcnt vmcnt(4)
	s_waitcnt lgkmcnt(0)
	s_barrier
	s_setprio 1
	s_waitcnt lgkmcnt(7)
	v_mfma_f32_16x16x32_bf16 v[62:65], v[148:151], v[180:183], v[62:65]
	v_mfma_f32_16x16x32_bf16 v[58:61], v[156:159], v[180:183], v[58:61]
	s_waitcnt lgkmcnt(5)
	v_mfma_f32_16x16x32_bf16 v[46:49], v[148:151], v[188:191], v[46:49]
	v_mfma_f32_16x16x32_bf16 v[42:45], v[156:159], v[188:191], v[42:45]
	s_waitcnt lgkmcnt(3)
	v_mfma_f32_16x16x32_bf16 v[30:33], v[148:151], v[196:199], v[30:33]
	v_mfma_f32_16x16x32_bf16 v[26:29], v[156:159], v[196:199], v[26:29]
	s_waitcnt lgkmcnt(1)
	v_mfma_f32_16x16x32_bf16 v[14:17], v[148:151], v[204:207], v[14:17]
	v_mfma_f32_16x16x32_bf16 v[10:13], v[156:159], v[204:207], v[10:13]
	v_mfma_f32_16x16x32_bf16 v[62:65], v[152:155], v[184:187], v[62:65]
	v_mfma_f32_16x16x32_bf16 v[58:61], v[160:163], v[184:187], v[58:61]
	v_mfma_f32_16x16x32_bf16 v[46:49], v[152:155], v[192:195], v[46:49]
	v_mfma_f32_16x16x32_bf16 v[42:45], v[160:163], v[192:195], v[42:45]
	v_mfma_f32_16x16x32_bf16 v[30:33], v[152:155], v[200:203], v[30:33]
	v_mfma_f32_16x16x32_bf16 v[26:29], v[160:163], v[200:203], v[26:29]
	s_waitcnt lgkmcnt(0)
	v_mfma_f32_16x16x32_bf16 v[14:17], v[152:155], v[208:211], v[14:17]
	v_mfma_f32_16x16x32_bf16 v[10:13], v[160:163], v[208:211], v[10:13]
	s_setprio 0
	s_setprio 1
	v_mfma_f32_16x16x32_bf16 v[54:57], v[164:167], v[180:183], v[54:57]
	v_mfma_f32_16x16x32_bf16 v[50:53], v[172:175], v[180:183], v[50:53]
	v_mfma_f32_16x16x32_bf16 v[38:41], v[164:167], v[188:191], v[38:41]
	v_mfma_f32_16x16x32_bf16 v[34:37], v[172:175], v[188:191], v[34:37]
	v_mfma_f32_16x16x32_bf16 v[22:25], v[164:167], v[196:199], v[22:25]
	v_mfma_f32_16x16x32_bf16 v[18:21], v[172:175], v[196:199], v[18:21]
	v_mfma_f32_16x16x32_bf16 v[6:9], v[164:167], v[204:207], v[6:9]
	v_mfma_f32_16x16x32_bf16 v[2:5], v[172:175], v[204:207], v[2:5]
	v_mfma_f32_16x16x32_bf16 v[54:57], v[168:171], v[184:187], v[54:57]
	v_mfma_f32_16x16x32_bf16 v[50:53], v[176:179], v[184:187], v[50:53]
	v_mfma_f32_16x16x32_bf16 v[38:41], v[168:171], v[192:195], v[38:41]
	v_mfma_f32_16x16x32_bf16 v[34:37], v[176:179], v[192:195], v[34:37]
	v_mfma_f32_16x16x32_bf16 v[22:25], v[168:171], v[200:203], v[22:25]
	v_mfma_f32_16x16x32_bf16 v[18:21], v[176:179], v[200:203], v[18:21]
	s_setprio 2
	s_barrier
	v_mfma_f32_16x16x32_bf16 v[6:9], v[168:171], v[208:211], v[6:9]
	v_mfma_f32_16x16x32_bf16 v[2:5], v[176:179], v[208:211], v[2:5]
	s_setprio 0
	s_add_i32 s70, s70, 2
	s_add_u32 s64, s64, 0x100
	s_addc_u32 s65, s65, 0
	s_add_u32 s18, s18, 0x100
	s_addc_u32 s19, s19, 0
	s_add_u32 s66, s66, 0x100
	s_addc_u32 s67, s67, 0
	s_cmp_gt_u32 s70, 29
	s_cbranch_scc0 .LBB0_2594
	s_and_b64 vcc, exec, s[6:7]
	s_cbranch_vccz .LBB0_2597
	s_barrier

.LBB0_2792:
	s_cmpk_eq_i32 s69, 0x52
	s_cselect_b32 s31, s19, s66
	s_cselect_b32 s30, s64, s65
	s_cselect_b32 s35, s21, s68
	s_cselect_b32 s34, s63, s67
	s_add_u32 s70, s28, 0xffffc000
	s_addc_u32 s71, s29, -1
	s_mov_b32 s73, m0
	s_mov_b32 m0, s57
	s_nop 0
	global_load_lds_dwordx4 v1, s[70:71]
	s_mov_b32 m0, s73
	s_nop 0
	s_mov_b32 s73, m0
	s_mov_b32 m0, s59
	s_nop 0
	global_load_lds_dwordx4 v177, s[70:71]
	s_mov_b32 m0, s73
	s_mov_b32 s70, m0
	s_mov_b32 m0, s58
	s_nop 0
	global_load_lds_dwordx4 v1, s[28:29]
	s_mov_b32 m0, s70
	s_nop 0
	s_mov_b32 s70, m0
	s_mov_b32 m0, s60
	s_nop 0
	global_load_lds_dwordx4 v177, s[28:29]
	s_mov_b32 m0, s70
	ds_read_b128 v[130:133], v181
	ds_read_b128 v[134:137], v181 offset:1024
	ds_read_b128 v[138:141], v181 offset:2048
	ds_read_b128 v[142:145], v181 offset:3072
	ds_read_b128 v[150:153], v182
	ds_read_b128 v[154:157], v182 offset:1024
	ds_read_b128 v[158:161], v182 offset:2048
	ds_read_b128 v[162:165], v182 offset:3072
	ds_read_b128 v[166:169], v183
	ds_read_b128 v[170:173], v183 offset:1024
	ds_read_b128 v[186:189], v183 offset:2048
	ds_read_b128 v[190:193], v183 offset:3072
	ds_read_b128 v[194:197], v183 offset:4096
	ds_read_b128 v[198:201], v183 offset:5120
	ds_read_b128 v[202:205], v183 offset:6144
	ds_read_b128 v[206:209], v183 offset:7168
	s_waitcnt vmcnt(8)
	s_waitcnt lgkmcnt(0)
	s_barrier
	s_setprio 1
	s_waitcnt lgkmcnt(7)
	v_mfma_f32_16x16x32_bf16 v[126:129], v[130:133], v[166:169], v[126:129]
	v_mfma_f32_16x16x32_bf16 v[122:125], v[138:141], v[166:169], v[122:125]
	s_waitcnt lgkmcnt(5)
	v_mfma_f32_16x16x32_bf16 v[118:121], v[130:133], v[186:189], v[118:121]
	v_mfma_f32_16x16x32_bf16 v[110:113], v[138:141], v[186:189], v[110:113]
	s_waitcnt lgkmcnt(3)
	v_mfma_f32_16x16x32_bf16 v[94:97], v[130:133], v[194:197], v[94:97]
	v_mfma_f32_16x16x32_bf16 v[90:93], v[138:141], v[194:197], v[90:93]
	s_waitcnt lgkmcnt(1)
	v_mfma_f32_16x16x32_bf16 v[86:89], v[130:133], v[202:205], v[86:89]
	v_mfma_f32_16x16x32_bf16 v[78:81], v[138:141], v[202:205], v[78:81]
	v_mfma_f32_16x16x32_bf16 v[126:129], v[134:137], v[170:173], v[126:129]
	v_mfma_f32_16x16x32_bf16 v[122:125], v[142:145], v[170:173], v[122:125]
	v_mfma_f32_16x16x32_bf16 v[118:121], v[134:137], v[190:193], v[118:121]
	v_mfma_f32_16x16x32_bf16 v[110:113], v[142:145], v[190:193], v[110:113]
	v_mfma_f32_16x16x32_bf16 v[94:97], v[134:137], v[198:201], v[94:97]
	v_mfma_f32_16x16x32_bf16 v[90:93], v[142:145], v[198:201], v[90:93]
	s_waitcnt lgkmcnt(0)
	v_mfma_f32_16x16x32_bf16 v[86:89], v[134:137], v[206:209], v[86:89]
	v_mfma_f32_16x16x32_bf16 v[78:81], v[142:145], v[206:209], v[78:81]
	s_setprio 0
	s_setprio 1
	v_mfma_f32_16x16x32_bf16 v[114:117], v[150:153], v[166:169], v[114:117]
	v_mfma_f32_16x16x32_bf16 v[106:109], v[158:161], v[166:169], v[106:109]
	v_mfma_f32_16x16x32_bf16 v[102:105], v[150:153], v[186:189], v[102:105]
	v_mfma_f32_16x16x32_bf16 v[98:101], v[158:161], v[186:189], v[98:101]
	v_mfma_f32_16x16x32_bf16 v[82:85], v[150:153], v[194:197], v[82:85]
	v_mfma_f32_16x16x32_bf16 v[74:77], v[158:161], v[194:197], v[74:77]
	v_mfma_f32_16x16x32_bf16 v[70:73], v[150:153], v[202:205], v[70:73]
	v_mfma_f32_16x16x32_bf16 v[66:69], v[158:161], v[202:205], v[66:69]
	v_mfma_f32_16x16x32_bf16 v[114:117], v[154:157], v[170:173], v[114:117]
	v_mfma_f32_16x16x32_bf16 v[106:109], v[162:165], v[170:173], v[106:109]
	v_mfma_f32_16x16x32_bf16 v[102:105], v[154:157], v[190:193], v[102:105]
	v_mfma_f32_16x16x32_bf16 v[98:101], v[162:165], v[190:193], v[98:101]
	v_mfma_f32_16x16x32_bf16 v[82:85], v[154:157], v[198:201], v[82:85]
	v_mfma_f32_16x16x32_bf16 v[74:77], v[162:165], v[198:201], v[74:77]
	s_setprio 2
	s_barrier
	v_mfma_f32_16x16x32_bf16 v[70:73], v[154:157], v[206:209], v[70:73]
	v_mfma_f32_16x16x32_bf16 v[66:69], v[162:165], v[206:209], v[66:69]
	s_setprio 0
	s_mov_b32 s70, m0
	s_mov_b32 m0, s27
	s_nop 0
	global_load_lds_dwordx4 v176, s[30:31]
	s_mov_b32 m0, s70
	s_nop 0
	s_mov_b32 s70, m0
	s_mov_b32 m0, s45
	s_nop 0
	global_load_lds_dwordx4 v178, s[30:31]
	s_mov_b32 m0, s70
	s_add_u32 s70, s30, 0x4000
	s_addc_u32 s71, s31, 0
	s_mov_b32 s73, m0
	s_mov_b32 m0, s46
	s_nop 0
	global_load_lds_dwordx4 v176, s[70:71]
	s_mov_b32 m0, s73
	s_nop 0
	s_mov_b32 s73, m0
	s_mov_b32 m0, s47
	s_nop 0
	global_load_lds_dwordx4 v178, s[70:71]
	s_mov_b32 m0, s73
	ds_read_b128 v[166:169], v183 offset:16384
	ds_read_b128 v[170:173], v183 offset:17408
	ds_read_b128 v[186:189], v183 offset:18432
	ds_read_b128 v[190:193], v183 offset:19456
	ds_read_b128 v[194:197], v183 offset:20480
	ds_read_b128 v[198:201], v183 offset:21504
	ds_read_b128 v[202:205], v183 offset:22528
	ds_read_b128 v[206:209], v183 offset:23552
	s_waitcnt vmcnt(4)
	s_waitcnt lgkmcnt(0)
	s_barrier
	s_setprio 1
	s_waitcnt lgkmcnt(7)
	v_mfma_f32_16x16x32_bf16 v[62:65], v[130:133], v[166:169], v[62:65]
	v_mfma_f32_16x16x32_bf16 v[58:61], v[138:141], v[166:169], v[58:61]
	s_waitcnt lgkmcnt(5)
	v_mfma_f32_16x16x32_bf16 v[46:49], v[130:133], v[186:189], v[46:49]
	v_mfma_f32_16x16x32_bf16 v[42:45], v[138:141], v[186:189], v[42:45]
	s_waitcnt lgkmcnt(3)
	v_mfma_f32_16x16x32_bf16 v[30:33], v[130:133], v[194:197], v[30:33]
	v_mfma_f32_16x16x32_bf16 v[26:29], v[138:141], v[194:197], v[26:29]
	s_waitcnt lgkmcnt(1)
	v_mfma_f32_16x16x32_bf16 v[14:17], v[130:133], v[202:205], v[14:17]
	v_mfma_f32_16x16x32_bf16 v[10:13], v[138:141], v[202:205], v[10:13]
	v_mfma_f32_16x16x32_bf16 v[62:65], v[134:137], v[170:173], v[62:65]
	v_mfma_f32_16x16x32_bf16 v[58:61], v[142:145], v[170:173], v[58:61]
	v_mfma_f32_16x16x32_bf16 v[46:49], v[134:137], v[190:193], v[46:49]
	v_mfma_f32_16x16x32_bf16 v[42:45], v[142:145], v[190:193], v[42:45]
	v_mfma_f32_16x16x32_bf16 v[30:33], v[134:137], v[198:201], v[30:33]
	v_mfma_f32_16x16x32_bf16 v[26:29], v[142:145], v[198:201], v[26:29]
	s_waitcnt lgkmcnt(0)
	v_mfma_f32_16x16x32_bf16 v[14:17], v[134:137], v[206:209], v[14:17]
	v_mfma_f32_16x16x32_bf16 v[10:13], v[142:145], v[206:209], v[10:13]
	s_setprio 0
	s_setprio 1
	v_mfma_f32_16x16x32_bf16 v[54:57], v[150:153], v[166:169], v[54:57]
	v_mfma_f32_16x16x32_bf16 v[50:53], v[158:161], v[166:169], v[50:53]
	v_mfma_f32_16x16x32_bf16 v[38:41], v[150:153], v[186:189], v[38:41]
	v_mfma_f32_16x16x32_bf16 v[34:37], v[158:161], v[186:189], v[34:37]
	v_mfma_f32_16x16x32_bf16 v[22:25], v[150:153], v[194:197], v[22:25]
	v_mfma_f32_16x16x32_bf16 v[18:21], v[158:161], v[194:197], v[18:21]
	v_mfma_f32_16x16x32_bf16 v[6:9], v[150:153], v[202:205], v[6:9]
	v_mfma_f32_16x16x32_bf16 v[2:5], v[158:161], v[202:205], v[2:5]
	v_mfma_f32_16x16x32_bf16 v[54:57], v[154:157], v[170:173], v[54:57]
	v_mfma_f32_16x16x32_bf16 v[50:53], v[162:165], v[170:173], v[50:53]
	v_mfma_f32_16x16x32_bf16 v[38:41], v[154:157], v[190:193], v[38:41]
	v_mfma_f32_16x16x32_bf16 v[34:37], v[162:165], v[190:193], v[34:37]
	v_mfma_f32_16x16x32_bf16 v[22:25], v[154:157], v[198:201], v[22:25]
	v_mfma_f32_16x16x32_bf16 v[18:21], v[162:165], v[198:201], v[18:21]
	s_setprio 2
	s_barrier
	v_mfma_f32_16x16x32_bf16 v[6:9], v[154:157], v[206:209], v[6:9]
	v_mfma_f32_16x16x32_bf16 v[2:5], v[162:165], v[206:209], v[2:5]
	s_setprio 0
	s_mov_b32 s70, m0
	s_mov_b32 m0, s44
	s_nop 0
	global_load_lds_dwordx4 v1, s[34:35]
	s_mov_b32 m0, s70
	s_nop 0
	s_mov_b32 s70, m0
	s_mov_b32 m0, s48
	s_nop 0
	global_load_lds_dwordx4 v177, s[34:35]
	s_mov_b32 m0, s70
	s_add_u32 s34, s34, 0x4000
	s_addc_u32 s35, s35, 0
	s_mov_b32 s70, m0
	s_mov_b32 m0, s49
	s_nop 0
	global_load_lds_dwordx4 v1, s[34:35]
	s_mov_b32 m0, s70
	s_nop 0
	s_mov_b32 s70, m0
	s_mov_b32 m0, s50
	s_nop 0
	global_load_lds_dwordx4 v177, s[34:35]
	s_mov_b32 m0, s70
	ds_read_b128 v[130:133], v184
	ds_read_b128 v[134:137], v184 offset:1024
	ds_read_b128 v[138:141], v184 offset:2048
	ds_read_b128 v[142:145], v184 offset:3072
	ds_read_b128 v[150:153], v185
	ds_read_b128 v[154:157], v185 offset:1024
	ds_read_b128 v[158:161], v185 offset:2048
	ds_read_b128 v[162:165], v185 offset:3072
	ds_read_b128 v[166:169], v183 offset:32768
	ds_read_b128 v[170:173], v183 offset:33792
	ds_read_b128 v[186:189], v183 offset:34816
	ds_read_b128 v[190:193], v183 offset:35840
	ds_read_b128 v[194:197], v183 offset:36864
	ds_read_b128 v[198:201], v183 offset:37888
	ds_read_b128 v[202:205], v183 offset:38912
	ds_read_b128 v[206:209], v183 offset:39936
	s_waitcnt vmcnt(8)
	s_waitcnt lgkmcnt(0)
	s_barrier
	s_setprio 1
	s_waitcnt lgkmcnt(7)
	v_mfma_f32_16x16x32_bf16 v[126:129], v[130:133], v[166:169], v[126:129]
	v_mfma_f32_16x16x32_bf16 v[122:125], v[138:141], v[166:169], v[122:125]
	s_waitcnt lgkmcnt(5)
	v_mfma_f32_16x16x32_bf16 v[118:121], v[130:133], v[186:189], v[118:121]
	v_mfma_f32_16x16x32_bf16 v[110:113], v[138:141], v[186:189], v[110:113]
	s_waitcnt lgkmcnt(3)
	v_mfma_f32_16x16x32_bf16 v[94:97], v[130:133], v[194:197], v[94:97]
	v_mfma_f32_16x16x32_bf16 v[90:93], v[138:141], v[194:197], v[90:93]
	s_waitcnt lgkmcnt(1)
	v_mfma_f32_16x16x32_bf16 v[86:89], v[130:133], v[202:205], v[86:89]
	v_mfma_f32_16x16x32_bf16 v[78:81], v[138:141], v[202:205], v[78:81]
	v_mfma_f32_16x16x32_bf16 v[126:129], v[134:137], v[170:173], v[126:129]
	v_mfma_f32_16x16x32_bf16 v[122:125], v[142:145], v[170:173], v[122:125]
	v_mfma_f32_16x16x32_bf16 v[118:121], v[134:137], v[190:193], v[118:121]
	v_mfma_f32_16x16x32_bf16 v[110:113], v[142:145], v[190:193], v[110:113]
	v_mfma_f32_16x16x32_bf16 v[94:97], v[134:137], v[198:201], v[94:97]
	v_mfma_f32_16x16x32_bf16 v[90:93], v[142:145], v[198:201], v[90:93]
	s_waitcnt lgkmcnt(0)
	v_mfma_f32_16x16x32_bf16 v[86:89], v[134:137], v[206:209], v[86:89]
	v_mfma_f32_16x16x32_bf16 v[78:81], v[142:145], v[206:209], v[78:81]
	s_setprio 0
	s_setprio 1
	v_mfma_f32_16x16x32_bf16 v[114:117], v[150:153], v[166:169], v[114:117]
	v_mfma_f32_16x16x32_bf16 v[106:109], v[158:161], v[166:169], v[106:109]
	v_mfma_f32_16x16x32_bf16 v[102:105], v[150:153], v[186:189], v[102:105]
	v_mfma_f32_16x16x32_bf16 v[98:101], v[158:161], v[186:189], v[98:101]
	v_mfma_f32_16x16x32_bf16 v[82:85], v[150:153], v[194:197], v[82:85]
	v_mfma_f32_16x16x32_bf16 v[74:77], v[158:161], v[194:197], v[74:77]
	v_mfma_f32_16x16x32_bf16 v[70:73], v[150:153], v[202:205], v[70:73]
	v_mfma_f32_16x16x32_bf16 v[66:69], v[158:161], v[202:205], v[66:69]
	v_mfma_f32_16x16x32_bf16 v[114:117], v[154:157], v[170:173], v[114:117]
	v_mfma_f32_16x16x32_bf16 v[106:109], v[162:165], v[170:173], v[106:109]
	v_mfma_f32_16x16x32_bf16 v[102:105], v[154:157], v[190:193], v[102:105]
	v_mfma_f32_16x16x32_bf16 v[98:101], v[162:165], v[190:193], v[98:101]
	v_mfma_f32_16x16x32_bf16 v[82:85], v[154:157], v[198:201], v[82:85]
	v_mfma_f32_16x16x32_bf16 v[74:77], v[162:165], v[198:201], v[74:77]
	s_setprio 2
	s_barrier
	v_mfma_f32_16x16x32_bf16 v[70:73], v[154:157], v[206:209], v[70:73]
	v_mfma_f32_16x16x32_bf16 v[66:69], v[162:165], v[206:209], v[66:69]
	s_setprio 0
	s_add_u32 s34, s30, 0x40000
	s_addc_u32 s35, s31, 0
	s_mov_b32 s70, m0
	s_mov_b32 m0, s51
	s_nop 0
	global_load_lds_dwordx4 v176, s[34:35]
	s_mov_b32 m0, s70
	s_add_u32 s30, s30, 0x44000
	s_mov_b32 s70, m0
	s_mov_b32 m0, s52
	s_nop 0
	global_load_lds_dwordx4 v178, s[34:35]
	s_mov_b32 m0, s70
	s_addc_u32 s31, s31, 0
	s_mov_b32 s34, m0
	s_mov_b32 m0, s53
	s_nop 0
	global_load_lds_dwordx4 v176, s[30:31]
	s_mov_b32 m0, s34
	s_nop 0
	s_mov_b32 s34, m0
	s_mov_b32 m0, s54
	s_nop 0
	global_load_lds_dwordx4 v178, s[30:31]
	s_mov_b32 m0, s34
	ds_read_b128 v[166:169], v183 offset:49152
	ds_read_b128 v[170:173], v183 offset:50176
	ds_read_b128 v[186:189], v183 offset:51200
	ds_read_b128 v[190:193], v183 offset:52224
	ds_read_b128 v[194:197], v183 offset:53248
	ds_read_b128 v[198:201], v183 offset:54272
	ds_read_b128 v[202:205], v183 offset:55296
	ds_read_b128 v[206:209], v183 offset:56320
	s_waitcnt vmcnt(4)
	s_waitcnt lgkmcnt(0)
	s_barrier
	s_setprio 1
	s_waitcnt lgkmcnt(7)
	v_mfma_f32_16x16x32_bf16 v[62:65], v[130:133], v[166:169], v[62:65]
	v_mfma_f32_16x16x32_bf16 v[58:61], v[138:141], v[166:169], v[58:61]
	s_waitcnt lgkmcnt(5)
	v_mfma_f32_16x16x32_bf16 v[46:49], v[130:133], v[186:189], v[46:49]
	v_mfma_f32_16x16x32_bf16 v[42:45], v[138:141], v[186:189], v[42:45]
	s_waitcnt lgkmcnt(3)
	v_mfma_f32_16x16x32_bf16 v[30:33], v[130:133], v[194:197], v[30:33]
	v_mfma_f32_16x16x32_bf16 v[26:29], v[138:141], v[194:197], v[26:29]
	s_waitcnt lgkmcnt(1)
	v_mfma_f32_16x16x32_bf16 v[14:17], v[130:133], v[202:205], v[14:17]
	v_mfma_f32_16x16x32_bf16 v[10:13], v[138:141], v[202:205], v[10:13]
	v_mfma_f32_16x16x32_bf16 v[62:65], v[134:137], v[170:173], v[62:65]
	v_mfma_f32_16x16x32_bf16 v[58:61], v[142:145], v[170:173], v[58:61]
	v_mfma_f32_16x16x32_bf16 v[46:49], v[134:137], v[190:193], v[46:49]
	v_mfma_f32_16x16x32_bf16 v[42:45], v[142:145], v[190:193], v[42:45]
	v_mfma_f32_16x16x32_bf16 v[30:33], v[134:137], v[198:201], v[30:33]
	v_mfma_f32_16x16x32_bf16 v[26:29], v[142:145], v[198:201], v[26:29]
	s_waitcnt lgkmcnt(0)
	v_mfma_f32_16x16x32_bf16 v[14:17], v[134:137], v[206:209], v[14:17]
	v_mfma_f32_16x16x32_bf16 v[10:13], v[142:145], v[206:209], v[10:13]
	s_setprio 0
	s_setprio 1
	v_mfma_f32_16x16x32_bf16 v[54:57], v[150:153], v[166:169], v[54:57]
	v_mfma_f32_16x16x32_bf16 v[50:53], v[158:161], v[166:169], v[50:53]
	v_mfma_f32_16x16x32_bf16 v[38:41], v[150:153], v[186:189], v[38:41]
	v_mfma_f32_16x16x32_bf16 v[34:37], v[158:161], v[186:189], v[34:37]
	v_mfma_f32_16x16x32_bf16 v[22:25], v[150:153], v[194:197], v[22:25]
	v_mfma_f32_16x16x32_bf16 v[18:21], v[158:161], v[194:197], v[18:21]
	v_mfma_f32_16x16x32_bf16 v[6:9], v[150:153], v[202:205], v[6:9]
	v_mfma_f32_16x16x32_bf16 v[2:5], v[158:161], v[202:205], v[2:5]
	v_mfma_f32_16x16x32_bf16 v[54:57], v[154:157], v[170:173], v[54:57]
	v_mfma_f32_16x16x32_bf16 v[50:53], v[162:165], v[170:173], v[50:53]
	v_mfma_f32_16x16x32_bf16 v[38:41], v[154:157], v[190:193], v[38:41]
	v_mfma_f32_16x16x32_bf16 v[34:37], v[162:165], v[190:193], v[34:37]
	v_mfma_f32_16x16x32_bf16 v[22:25], v[154:157], v[198:201], v[22:25]
	v_mfma_f32_16x16x32_bf16 v[18:21], v[162:165], v[198:201], v[18:21]
	s_setprio 2
	s_barrier
	v_mfma_f32_16x16x32_bf16 v[6:9], v[154:157], v[206:209], v[6:9]
	v_mfma_f32_16x16x32_bf16 v[2:5], v[162:165], v[206:209], v[2:5]
	s_setprio 0
	s_add_i32 s69, s69, 2
	s_add_u32 s65, s65, 0x80000
	s_addc_u32 s66, s66, 0
	s_add_u32 s28, s28, 0x400000
	s_addc_u32 s29, s29, 0
	s_add_u32 s67, s67, 0x400000
	s_addc_u32 s68, s68, 0
	s_cmpk_gt_u32 s69, 0x53
	s_cbranch_scc0 .LBB0_2792
	s_and_b64 vcc, exec, s[8:9]
	s_cbranch_vccz .LBB0_2795
	s_barrier
